# snake MFMA order + drop redundant post-barrier lgkmcnt(0) in K-loops
# baseline (speedup 1.0000x reference)
.LBB0_142:
	ds_read_b128 v[168:171], v165
	ds_read_b128 v[172:175], v165 offset:1024
	ds_read_b128 v[176:179], v165 offset:2048
	ds_read_b128 v[180:183], v165 offset:3072
	ds_read_b128 v[184:187], v166
	ds_read_b128 v[188:191], v166 offset:1024
	ds_read_b128 v[192:195], v166 offset:2048
	ds_read_b128 v[196:199], v166 offset:3072
	s_add_i32 s54, s22, 2
	s_add_u32 s55, s20, 0x80
	s_addc_u32 s23, s21, 0
	s_cmp_eq_u32 s42, s22
	s_cselect_b32 s22, s4, s55
	s_cselect_b32 s23, s5, s23
	s_cselect_b32 s61, s19, s53
	s_cselect_b32 s60, s18, s52
	v_lshl_add_u64 v[234:235], s[20:21], 0, v[154:155]
	s_add_i32 m0, s31, 0xc000
	ds_read_b128 v[200:203], v167
	ds_read_b128 v[204:207], v167 offset:1024
	ds_read_b128 v[208:211], v167 offset:2048
	ds_read_b128 v[212:215], v167 offset:3072
	ds_read_b128 v[216:219], v167 offset:4096
	ds_read_b128 v[222:225], v167 offset:5120
	ds_read_b128 v[226:229], v167 offset:6144
	ds_read_b128 v[230:233], v167 offset:7168
	global_load_lds_dwordx4 v[234:235], off
	v_lshl_add_u64 v[234:235], s[20:21], 0, v[156:157]
	s_add_i32 m0, s31, 0xe000
	s_nop 0
	global_load_lds_dwordx4 v[234:235], off
	s_waitcnt vmcnt(8)
	s_waitcnt lgkmcnt(0)
	s_barrier
	s_setprio 1
	v_mfma_f32_16x16x32_bf16 v[120:123], v[168:171], v[200:203], v[120:123]
	v_mfma_f32_16x16x32_bf16 v[120:123], v[172:175], v[204:207], v[120:123]
	v_mfma_f32_16x16x32_bf16 v[116:119], v[180:183], v[204:207], v[116:119]
	v_mfma_f32_16x16x32_bf16 v[116:119], v[176:179], v[200:203], v[116:119]
	v_mfma_f32_16x16x32_bf16 v[124:127], v[184:187], v[200:203], v[124:127]
	v_mfma_f32_16x16x32_bf16 v[124:127], v[188:191], v[204:207], v[124:127]
	v_mfma_f32_16x16x32_bf16 v[112:115], v[196:199], v[204:207], v[112:115]
	v_mfma_f32_16x16x32_bf16 v[112:115], v[192:195], v[200:203], v[112:115]
	v_mfma_f32_16x16x32_bf16 v[96:99], v[192:195], v[208:211], v[96:99]
	v_mfma_f32_16x16x32_bf16 v[96:99], v[196:199], v[212:215], v[96:99]
	v_mfma_f32_16x16x32_bf16 v[104:107], v[188:191], v[212:215], v[104:107]
	v_mfma_f32_16x16x32_bf16 v[104:107], v[184:187], v[208:211], v[104:107]
	v_mfma_f32_16x16x32_bf16 v[100:103], v[176:179], v[208:211], v[100:103]
	v_mfma_f32_16x16x32_bf16 v[100:103], v[180:183], v[212:215], v[100:103]
	v_mfma_f32_16x16x32_bf16 v[108:111], v[172:175], v[212:215], v[108:111]
	v_mfma_f32_16x16x32_bf16 v[108:111], v[168:171], v[208:211], v[108:111]
	v_mfma_f32_16x16x32_bf16 v[92:95], v[168:171], v[216:219], v[92:95]
	v_mfma_f32_16x16x32_bf16 v[92:95], v[172:175], v[222:225], v[92:95]
	v_mfma_f32_16x16x32_bf16 v[84:87], v[180:183], v[222:225], v[84:87]
	v_mfma_f32_16x16x32_bf16 v[84:87], v[176:179], v[216:219], v[84:87]
	v_mfma_f32_16x16x32_bf16 v[88:91], v[184:187], v[216:219], v[88:91]
	v_mfma_f32_16x16x32_bf16 v[88:91], v[188:191], v[222:225], v[88:91]
	v_mfma_f32_16x16x32_bf16 v[80:83], v[196:199], v[222:225], v[80:83]
	v_mfma_f32_16x16x32_bf16 v[80:83], v[192:195], v[216:219], v[80:83]
	v_mfma_f32_16x16x32_bf16 v[64:67], v[192:195], v[226:229], v[64:67]
	v_mfma_f32_16x16x32_bf16 v[64:67], v[196:199], v[230:233], v[64:67]
	v_mfma_f32_16x16x32_bf16 v[72:75], v[188:191], v[230:233], v[72:75]
	v_mfma_f32_16x16x32_bf16 v[72:75], v[184:187], v[226:229], v[72:75]
	v_mfma_f32_16x16x32_bf16 v[68:71], v[176:179], v[226:229], v[68:71]
	v_mfma_f32_16x16x32_bf16 v[68:71], v[180:183], v[230:233], v[68:71]
	v_mfma_f32_16x16x32_bf16 v[76:79], v[172:175], v[230:233], v[76:79]
	v_mfma_f32_16x16x32_bf16 v[76:79], v[168:171], v[226:229], v[76:79]
	s_setprio 0
	s_barrier
	s_add_i32 s55, s46, s28
	v_lshl_add_u64 v[234:235], s[60:61], 0, v[132:133]
	s_mov_b32 m0, s55
	ds_read_b128 v[200:203], v167 offset:16384
	ds_read_b128 v[204:207], v167 offset:17408
	ds_read_b128 v[208:211], v167 offset:18432
	ds_read_b128 v[212:215], v167 offset:19456
	ds_read_b128 v[216:219], v167 offset:20480
	ds_read_b128 v[222:225], v167 offset:21504
	ds_read_b128 v[226:229], v167 offset:22528
	ds_read_b128 v[230:233], v167 offset:23552
	global_load_lds_dwordx4 v[234:235], off
	s_add_i32 m0, s55, 0x2000
	v_lshl_add_u64 v[236:237], s[60:61], 0, v[128:129]
	s_add_u32 s60, s60, s10
	s_addc_u32 s61, s61, s11
	s_add_i32 s55, s47, s28
	global_load_lds_dwordx4 v[236:237], off
	v_lshl_add_u64 v[238:239], s[60:61], 0, v[132:133]
	s_mov_b32 m0, s55
	v_lshl_add_u64 v[240:241], s[60:61], 0, v[128:129]
	global_load_lds_dwordx4 v[238:239], off
	s_add_i32 m0, s55, 0x2000
	v_lshl_add_u64 v[242:243], s[22:23], 0, v[134:135]
	global_load_lds_dwordx4 v[240:241], off
	s_mov_b32 m0, s31
	v_lshl_add_u64 v[244:245], s[22:23], 0, v[130:131]
	global_load_lds_dwordx4 v[242:243], off
	s_mov_b32 m0, s33
	s_nop 0
	global_load_lds_dwordx4 v[244:245], off
	s_waitcnt vmcnt(8)
	s_waitcnt lgkmcnt(0)
	s_barrier
	s_setprio 1
	v_mfma_f32_16x16x32_bf16 v[60:63], v[168:171], v[200:203], v[60:63]
	v_mfma_f32_16x16x32_bf16 v[60:63], v[172:175], v[204:207], v[60:63]
	v_mfma_f32_16x16x32_bf16 v[52:55], v[180:183], v[204:207], v[52:55]
	v_mfma_f32_16x16x32_bf16 v[52:55], v[176:179], v[200:203], v[52:55]
	v_mfma_f32_16x16x32_bf16 v[56:59], v[184:187], v[200:203], v[56:59]
	v_mfma_f32_16x16x32_bf16 v[56:59], v[188:191], v[204:207], v[56:59]
	v_mfma_f32_16x16x32_bf16 v[48:51], v[196:199], v[204:207], v[48:51]
	v_mfma_f32_16x16x32_bf16 v[48:51], v[192:195], v[200:203], v[48:51]
	v_mfma_f32_16x16x32_bf16 v[32:35], v[192:195], v[208:211], v[32:35]
	v_mfma_f32_16x16x32_bf16 v[32:35], v[196:199], v[212:215], v[32:35]
	v_mfma_f32_16x16x32_bf16 v[40:43], v[188:191], v[212:215], v[40:43]
	v_mfma_f32_16x16x32_bf16 v[40:43], v[184:187], v[208:211], v[40:43]
	v_mfma_f32_16x16x32_bf16 v[36:39], v[176:179], v[208:211], v[36:39]
	v_mfma_f32_16x16x32_bf16 v[36:39], v[180:183], v[212:215], v[36:39]
	v_mfma_f32_16x16x32_bf16 v[44:47], v[172:175], v[212:215], v[44:47]
	v_mfma_f32_16x16x32_bf16 v[44:47], v[168:171], v[208:211], v[44:47]
	v_mfma_f32_16x16x32_bf16 v[28:31], v[168:171], v[216:219], v[28:31]
	v_mfma_f32_16x16x32_bf16 v[28:31], v[172:175], v[222:225], v[28:31]
	v_mfma_f32_16x16x32_bf16 v[20:23], v[180:183], v[222:225], v[20:23]
	v_mfma_f32_16x16x32_bf16 v[20:23], v[176:179], v[216:219], v[20:23]
	v_mfma_f32_16x16x32_bf16 v[24:27], v[184:187], v[216:219], v[24:27]
	v_mfma_f32_16x16x32_bf16 v[24:27], v[188:191], v[222:225], v[24:27]
	v_mfma_f32_16x16x32_bf16 v[16:19], v[196:199], v[222:225], v[16:19]
	v_mfma_f32_16x16x32_bf16 v[16:19], v[192:195], v[216:219], v[16:19]
	v_mfma_f32_16x16x32_bf16 v[0:3], v[192:195], v[226:229], v[0:3]
	v_mfma_f32_16x16x32_bf16 v[0:3], v[196:199], v[230:233], v[0:3]
	v_mfma_f32_16x16x32_bf16 v[8:11], v[188:191], v[230:233], v[8:11]
	v_mfma_f32_16x16x32_bf16 v[8:11], v[184:187], v[226:229], v[8:11]
	v_mfma_f32_16x16x32_bf16 v[4:7], v[176:179], v[226:229], v[4:7]
	v_mfma_f32_16x16x32_bf16 v[4:7], v[180:183], v[230:233], v[4:7]
	v_mfma_f32_16x16x32_bf16 v[12:15], v[172:175], v[230:233], v[12:15]
	v_mfma_f32_16x16x32_bf16 v[12:15], v[168:171], v[226:229], v[12:15]
	s_setprio 0
	s_barrier
	s_add_i32 s55, 0, 0x18000
	s_add_i32 s60, 0, 0x1c000
	v_add_u32_e32 v180, s55, v164
	v_add_u32_e32 v196, s60, v164
	ds_read_b128 v[168:171], v180
	ds_read_b128 v[172:175], v180 offset:1024
	ds_read_b128 v[176:179], v180 offset:2048
	ds_read_b128 v[180:183], v180 offset:3072
	ds_read_b128 v[184:187], v196
	ds_read_b128 v[188:191], v196 offset:1024
	ds_read_b128 v[192:195], v196 offset:2048
	ds_read_b128 v[196:199], v196 offset:3072
	s_add_u32 s22, s22, s10
	s_addc_u32 s23, s23, s11
	s_mov_b32 m0, s34
	v_lshl_add_u64 v[246:247], s[22:23], 0, v[134:135]
	ds_read_b128 v[200:203], v167 offset:32768
	ds_read_b128 v[204:207], v167 offset:33792
	ds_read_b128 v[208:211], v167 offset:34816
	ds_read_b128 v[212:215], v167 offset:35840
	ds_read_b128 v[216:219], v167 offset:36864
	ds_read_b128 v[222:225], v167 offset:37888
	ds_read_b128 v[226:229], v167 offset:38912
	ds_read_b128 v[230:233], v167 offset:39936
	global_load_lds_dwordx4 v[246:247], off
	v_lshl_add_u64 v[246:247], s[22:23], 0, v[130:131]
	s_mov_b32 m0, s35
	s_nop 0
	global_load_lds_dwordx4 v[246:247], off
	s_waitcnt vmcnt(8)
	s_waitcnt lgkmcnt(0)
	s_barrier
	s_setprio 1
	v_mfma_f32_16x16x32_bf16 v[120:123], v[168:171], v[200:203], v[120:123]
	v_mfma_f32_16x16x32_bf16 v[120:123], v[172:175], v[204:207], v[120:123]
	v_mfma_f32_16x16x32_bf16 v[116:119], v[180:183], v[204:207], v[116:119]
	v_mfma_f32_16x16x32_bf16 v[116:119], v[176:179], v[200:203], v[116:119]
	v_mfma_f32_16x16x32_bf16 v[124:127], v[184:187], v[200:203], v[124:127]
	v_mfma_f32_16x16x32_bf16 v[124:127], v[188:191], v[204:207], v[124:127]
	v_mfma_f32_16x16x32_bf16 v[112:115], v[196:199], v[204:207], v[112:115]
	v_mfma_f32_16x16x32_bf16 v[112:115], v[192:195], v[200:203], v[112:115]
	v_mfma_f32_16x16x32_bf16 v[96:99], v[192:195], v[208:211], v[96:99]
	v_mfma_f32_16x16x32_bf16 v[96:99], v[196:199], v[212:215], v[96:99]
	v_mfma_f32_16x16x32_bf16 v[104:107], v[188:191], v[212:215], v[104:107]
	v_mfma_f32_16x16x32_bf16 v[104:107], v[184:187], v[208:211], v[104:107]
	v_mfma_f32_16x16x32_bf16 v[100:103], v[176:179], v[208:211], v[100:103]
	v_mfma_f32_16x16x32_bf16 v[100:103], v[180:183], v[212:215], v[100:103]
	v_mfma_f32_16x16x32_bf16 v[108:111], v[172:175], v[212:215], v[108:111]
	v_mfma_f32_16x16x32_bf16 v[108:111], v[168:171], v[208:211], v[108:111]
	v_mfma_f32_16x16x32_bf16 v[92:95], v[168:171], v[216:219], v[92:95]
	v_mfma_f32_16x16x32_bf16 v[92:95], v[172:175], v[222:225], v[92:95]
	v_mfma_f32_16x16x32_bf16 v[84:87], v[180:183], v[222:225], v[84:87]
	v_mfma_f32_16x16x32_bf16 v[84:87], v[176:179], v[216:219], v[84:87]
	v_mfma_f32_16x16x32_bf16 v[88:91], v[184:187], v[216:219], v[88:91]
	v_mfma_f32_16x16x32_bf16 v[88:91], v[188:191], v[222:225], v[88:91]
	v_mfma_f32_16x16x32_bf16 v[80:83], v[196:199], v[222:225], v[80:83]
	v_mfma_f32_16x16x32_bf16 v[80:83], v[192:195], v[216:219], v[80:83]
	v_mfma_f32_16x16x32_bf16 v[64:67], v[192:195], v[226:229], v[64:67]
	v_mfma_f32_16x16x32_bf16 v[64:67], v[196:199], v[230:233], v[64:67]
	v_mfma_f32_16x16x32_bf16 v[72:75], v[188:191], v[230:233], v[72:75]
	v_mfma_f32_16x16x32_bf16 v[72:75], v[184:187], v[226:229], v[72:75]
	v_mfma_f32_16x16x32_bf16 v[68:71], v[176:179], v[226:229], v[68:71]
	v_mfma_f32_16x16x32_bf16 v[68:71], v[180:183], v[230:233], v[68:71]
	v_mfma_f32_16x16x32_bf16 v[76:79], v[172:175], v[230:233], v[76:79]
	v_mfma_f32_16x16x32_bf16 v[76:79], v[168:171], v[226:229], v[76:79]
	s_setprio 0
	s_barrier
	s_add_i32 s22, s55, s28
	v_lshl_add_u64 v[234:235], v[234:235], 0, s[14:15]
	s_mov_b32 m0, s22
	ds_read_b128 v[200:203], v167 offset:49152
	ds_read_b128 v[204:207], v167 offset:50176
	ds_read_b128 v[208:211], v167 offset:51200
	ds_read_b128 v[212:215], v167 offset:52224
	ds_read_b128 v[216:219], v167 offset:53248
	ds_read_b128 v[222:225], v167 offset:54272
	ds_read_b128 v[226:229], v167 offset:55296
	ds_read_b128 v[230:233], v167 offset:56320
	global_load_lds_dwordx4 v[234:235], off
	v_lshl_add_u64 v[234:235], v[236:237], 0, s[14:15]
	s_add_i32 m0, s22, 0x2000
	s_add_i32 s22, s60, s28
	global_load_lds_dwordx4 v[234:235], off
	v_lshl_add_u64 v[234:235], v[238:239], 0, s[14:15]
	s_mov_b32 m0, s22
	s_nop 0
	global_load_lds_dwordx4 v[234:235], off
	v_lshl_add_u64 v[234:235], v[240:241], 0, s[14:15]
	s_add_i32 m0, s22, 0x2000
	s_nop 0
	global_load_lds_dwordx4 v[234:235], off
	v_lshl_add_u64 v[234:235], v[242:243], 0, s[14:15]
	s_mov_b32 m0, s39
	s_nop 0
	global_load_lds_dwordx4 v[234:235], off
	v_lshl_add_u64 v[234:235], v[244:245], 0, s[14:15]
	s_mov_b32 m0, s40
	s_nop 0
	global_load_lds_dwordx4 v[234:235], off
	s_waitcnt vmcnt(8)
	s_waitcnt lgkmcnt(0)
	s_barrier
	s_setprio 1
	v_mfma_f32_16x16x32_bf16 v[60:63], v[168:171], v[200:203], v[60:63]
	v_mfma_f32_16x16x32_bf16 v[60:63], v[172:175], v[204:207], v[60:63]
	v_mfma_f32_16x16x32_bf16 v[52:55], v[180:183], v[204:207], v[52:55]
	v_mfma_f32_16x16x32_bf16 v[52:55], v[176:179], v[200:203], v[52:55]
	v_mfma_f32_16x16x32_bf16 v[56:59], v[184:187], v[200:203], v[56:59]
	v_mfma_f32_16x16x32_bf16 v[56:59], v[188:191], v[204:207], v[56:59]
	v_mfma_f32_16x16x32_bf16 v[48:51], v[196:199], v[204:207], v[48:51]
	v_mfma_f32_16x16x32_bf16 v[48:51], v[192:195], v[200:203], v[48:51]
	v_mfma_f32_16x16x32_bf16 v[32:35], v[192:195], v[208:211], v[32:35]
	v_mfma_f32_16x16x32_bf16 v[32:35], v[196:199], v[212:215], v[32:35]
	v_mfma_f32_16x16x32_bf16 v[40:43], v[188:191], v[212:215], v[40:43]
	v_mfma_f32_16x16x32_bf16 v[40:43], v[184:187], v[208:211], v[40:43]
	v_mfma_f32_16x16x32_bf16 v[36:39], v[176:179], v[208:211], v[36:39]
	v_mfma_f32_16x16x32_bf16 v[36:39], v[180:183], v[212:215], v[36:39]
	v_mfma_f32_16x16x32_bf16 v[44:47], v[172:175], v[212:215], v[44:47]
	v_mfma_f32_16x16x32_bf16 v[44:47], v[168:171], v[208:211], v[44:47]
	v_mfma_f32_16x16x32_bf16 v[28:31], v[168:171], v[216:219], v[28:31]
	v_mfma_f32_16x16x32_bf16 v[28:31], v[172:175], v[222:225], v[28:31]
	v_mfma_f32_16x16x32_bf16 v[20:23], v[180:183], v[222:225], v[20:23]
	v_mfma_f32_16x16x32_bf16 v[20:23], v[176:179], v[216:219], v[20:23]
	v_mfma_f32_16x16x32_bf16 v[24:27], v[184:187], v[216:219], v[24:27]
	v_mfma_f32_16x16x32_bf16 v[24:27], v[188:191], v[222:225], v[24:27]
	v_mfma_f32_16x16x32_bf16 v[16:19], v[196:199], v[222:225], v[16:19]
	v_mfma_f32_16x16x32_bf16 v[16:19], v[192:195], v[216:219], v[16:19]
	v_mfma_f32_16x16x32_bf16 v[0:3], v[192:195], v[226:229], v[0:3]
	v_mfma_f32_16x16x32_bf16 v[0:3], v[196:199], v[230:233], v[0:3]
	v_mfma_f32_16x16x32_bf16 v[8:11], v[188:191], v[230:233], v[8:11]
	v_mfma_f32_16x16x32_bf16 v[8:11], v[184:187], v[226:229], v[8:11]
	v_mfma_f32_16x16x32_bf16 v[4:7], v[176:179], v[226:229], v[4:7]
	v_mfma_f32_16x16x32_bf16 v[4:7], v[180:183], v[230:233], v[4:7]
	v_mfma_f32_16x16x32_bf16 v[12:15], v[172:175], v[230:233], v[12:15]
	v_mfma_f32_16x16x32_bf16 v[12:15], v[168:171], v[226:229], v[12:15]
	s_setprio 0
	s_barrier
	s_add_u32 s20, s20, 0x100
	s_addc_u32 s21, s21, 0
	s_add_u32 s52, s52, 0x100
	s_addc_u32 s53, s53, 0
	s_cmp_ge_i32 s54, s41
	s_mov_b32 s22, s54
	s_cbranch_scc0 .LBB0_142

.LBB0_228:
	ds_read_b128 v[140:143], v219
	ds_read_b128 v[144:147], v219 offset:1024
	ds_read_b128 v[148:151], v219 offset:2048
	ds_read_b128 v[152:155], v219 offset:3072
	ds_read_b128 v[156:159], v221
	ds_read_b128 v[164:167], v221 offset:1024
	ds_read_b128 v[168:171], v221 offset:2048
	ds_read_b128 v[172:175], v221 offset:3072
	s_add_i32 s62, s26, 2
	s_add_u32 s27, s24, 0x4000
	s_addc_u32 s28, s25, 0
	s_cmp_eq_u32 s46, s26
	s_cselect_b32 s30, s0, s27
	s_cselect_b32 s31, s1, s28
	s_cselect_b32 s28, s22, s60
	s_cselect_b32 s29, s23, s61
	s_add_u32 s26, s30, 0x8000
	s_addc_u32 s27, s31, 0
	v_lshl_add_u64 v[160:161], s[24:25], 0, v[132:133]
	s_add_i32 m0, s38, 0xc000
	ds_read_b128 v[176:179], v222
	ds_read_b128 v[180:183], v222 offset:1024
	ds_read_b128 v[184:187], v222 offset:2048
	ds_read_b128 v[188:191], v222 offset:3072
	ds_read_b128 v[192:195], v222 offset:4096
	ds_read_b128 v[196:199], v222 offset:5120
	ds_read_b128 v[200:203], v222 offset:6144
	ds_read_b128 v[204:207], v222 offset:7168
	global_load_lds_dwordx4 v[160:161], off
	v_lshl_add_u64 v[160:161], s[24:25], 0, v[134:135]
	s_add_i32 m0, s38, 0xe000
	s_nop 0
	global_load_lds_dwordx4 v[160:161], off
	s_waitcnt vmcnt(8)
	s_waitcnt lgkmcnt(0)
	s_barrier
	s_setprio 1
	v_mfma_f32_16x16x32_bf16 v[124:127], v[140:143], v[176:179], v[124:127]
	v_mfma_f32_16x16x32_bf16 v[124:127], v[144:147], v[180:183], v[124:127]
	v_mfma_f32_16x16x32_bf16 v[120:123], v[152:155], v[180:183], v[120:123]
	v_mfma_f32_16x16x32_bf16 v[120:123], v[148:151], v[176:179], v[120:123]
	v_mfma_f32_16x16x32_bf16 v[108:111], v[156:159], v[176:179], v[108:111]
	v_mfma_f32_16x16x32_bf16 v[108:111], v[164:167], v[180:183], v[108:111]
	v_mfma_f32_16x16x32_bf16 v[100:103], v[172:175], v[180:183], v[100:103]
	v_mfma_f32_16x16x32_bf16 v[100:103], v[168:171], v[176:179], v[100:103]
	v_mfma_f32_16x16x32_bf16 v[84:87], v[168:171], v[184:187], v[84:87]
	v_mfma_f32_16x16x32_bf16 v[84:87], v[172:175], v[188:191], v[84:87]
	v_mfma_f32_16x16x32_bf16 v[92:95], v[164:167], v[188:191], v[92:95]
	v_mfma_f32_16x16x32_bf16 v[92:95], v[156:159], v[184:187], v[92:95]
	v_mfma_f32_16x16x32_bf16 v[112:115], v[148:151], v[184:187], v[112:115]
	v_mfma_f32_16x16x32_bf16 v[112:115], v[152:155], v[188:191], v[112:115]
	v_mfma_f32_16x16x32_bf16 v[116:119], v[144:147], v[188:191], v[116:119]
	v_mfma_f32_16x16x32_bf16 v[116:119], v[140:143], v[184:187], v[116:119]
	v_mfma_f32_16x16x32_bf16 v[104:107], v[140:143], v[192:195], v[104:107]
	v_mfma_f32_16x16x32_bf16 v[104:107], v[144:147], v[196:199], v[104:107]
	v_mfma_f32_16x16x32_bf16 v[96:99], v[152:155], v[196:199], v[96:99]
	v_mfma_f32_16x16x32_bf16 v[96:99], v[148:151], v[192:195], v[96:99]
	v_mfma_f32_16x16x32_bf16 v[76:79], v[156:159], v[192:195], v[76:79]
	v_mfma_f32_16x16x32_bf16 v[76:79], v[164:167], v[196:199], v[76:79]
	v_mfma_f32_16x16x32_bf16 v[72:75], v[172:175], v[196:199], v[72:75]
	v_mfma_f32_16x16x32_bf16 v[72:75], v[168:171], v[192:195], v[72:75]
	v_mfma_f32_16x16x32_bf16 v[64:67], v[168:171], v[200:203], v[64:67]
	v_mfma_f32_16x16x32_bf16 v[64:67], v[172:175], v[204:207], v[64:67]
	v_mfma_f32_16x16x32_bf16 v[68:71], v[164:167], v[204:207], v[68:71]
	v_mfma_f32_16x16x32_bf16 v[68:71], v[156:159], v[200:203], v[68:71]
	v_mfma_f32_16x16x32_bf16 v[80:83], v[148:151], v[200:203], v[80:83]
	v_mfma_f32_16x16x32_bf16 v[80:83], v[152:155], v[204:207], v[80:83]
	v_mfma_f32_16x16x32_bf16 v[88:91], v[144:147], v[204:207], v[88:91]
	v_mfma_f32_16x16x32_bf16 v[88:91], v[140:143], v[200:203], v[88:91]
	s_setprio 0
	s_barrier
	s_add_i32 s63, s50, s37
	v_lshl_add_u64 v[160:161], s[28:29], 0, v[128:129]
	s_mov_b32 m0, s63
	ds_read_b128 v[176:179], v222 offset:16384
	ds_read_b128 v[180:183], v222 offset:17408
	ds_read_b128 v[184:187], v222 offset:18432
	ds_read_b128 v[188:191], v222 offset:19456
	ds_read_b128 v[192:195], v222 offset:20480
	ds_read_b128 v[196:199], v222 offset:21504
	ds_read_b128 v[200:203], v222 offset:22528
	ds_read_b128 v[204:207], v222 offset:23552
	global_load_lds_dwordx4 v[160:161], off
	s_add_i32 m0, s63, 0x2000
	s_add_u32 s64, s28, 0x4000
	v_lshl_add_u64 v[160:161], s[28:29], 0, v[130:131]
	s_addc_u32 s65, s29, 0
	s_add_i32 s63, s51, s37
	global_load_lds_dwordx4 v[160:161], off
	v_lshl_add_u64 v[160:161], s[64:65], 0, v[128:129]
	s_mov_b32 m0, s63
	s_nop 0
	global_load_lds_dwordx4 v[160:161], off
	v_lshl_add_u64 v[160:161], s[64:65], 0, v[130:131]
	s_add_i32 m0, s63, 0x2000
	s_nop 0
	global_load_lds_dwordx4 v[160:161], off
	v_lshl_add_u64 v[160:161], s[30:31], 0, v[128:129]
	s_mov_b32 m0, s38
	s_nop 0
	global_load_lds_dwordx4 v[160:161], off
	v_lshl_add_u64 v[160:161], s[30:31], 0, v[130:131]
	s_mov_b32 m0, s39
	s_nop 0
	global_load_lds_dwordx4 v[160:161], off
	s_waitcnt vmcnt(8)
	s_waitcnt lgkmcnt(0)
	s_barrier
	s_setprio 1
	v_mfma_f32_16x16x32_bf16 v[60:63], v[140:143], v[176:179], v[60:63]
	v_mfma_f32_16x16x32_bf16 v[60:63], v[144:147], v[180:183], v[60:63]
	v_mfma_f32_16x16x32_bf16 v[56:59], v[152:155], v[180:183], v[56:59]
	v_mfma_f32_16x16x32_bf16 v[56:59], v[148:151], v[176:179], v[56:59]
	v_mfma_f32_16x16x32_bf16 v[44:47], v[156:159], v[176:179], v[44:47]
	v_mfma_f32_16x16x32_bf16 v[44:47], v[164:167], v[180:183], v[44:47]
	v_mfma_f32_16x16x32_bf16 v[36:39], v[172:175], v[180:183], v[36:39]
	v_mfma_f32_16x16x32_bf16 v[36:39], v[168:171], v[176:179], v[36:39]
	v_mfma_f32_16x16x32_bf16 v[20:23], v[168:171], v[184:187], v[20:23]
	v_mfma_f32_16x16x32_bf16 v[20:23], v[172:175], v[188:191], v[20:23]
	v_mfma_f32_16x16x32_bf16 v[28:31], v[164:167], v[188:191], v[28:31]
	v_mfma_f32_16x16x32_bf16 v[28:31], v[156:159], v[184:187], v[28:31]
	v_mfma_f32_16x16x32_bf16 v[48:51], v[148:151], v[184:187], v[48:51]
	v_mfma_f32_16x16x32_bf16 v[48:51], v[152:155], v[188:191], v[48:51]
	v_mfma_f32_16x16x32_bf16 v[52:55], v[144:147], v[188:191], v[52:55]
	v_mfma_f32_16x16x32_bf16 v[52:55], v[140:143], v[184:187], v[52:55]
	v_mfma_f32_16x16x32_bf16 v[40:43], v[140:143], v[192:195], v[40:43]
	v_mfma_f32_16x16x32_bf16 v[40:43], v[144:147], v[196:199], v[40:43]
	v_mfma_f32_16x16x32_bf16 v[32:35], v[152:155], v[196:199], v[32:35]
	v_mfma_f32_16x16x32_bf16 v[32:35], v[148:151], v[192:195], v[32:35]
	v_mfma_f32_16x16x32_bf16 v[12:15], v[156:159], v[192:195], v[12:15]
	v_mfma_f32_16x16x32_bf16 v[12:15], v[164:167], v[196:199], v[12:15]
	v_mfma_f32_16x16x32_bf16 v[8:11], v[172:175], v[196:199], v[8:11]
	v_mfma_f32_16x16x32_bf16 v[8:11], v[168:171], v[192:195], v[8:11]
	v_mfma_f32_16x16x32_bf16 v[0:3], v[168:171], v[200:203], v[0:3]
	v_mfma_f32_16x16x32_bf16 v[0:3], v[172:175], v[204:207], v[0:3]
	v_mfma_f32_16x16x32_bf16 v[4:7], v[164:167], v[204:207], v[4:7]
	v_mfma_f32_16x16x32_bf16 v[4:7], v[156:159], v[200:203], v[4:7]
	v_mfma_f32_16x16x32_bf16 v[16:19], v[148:151], v[200:203], v[16:19]
	v_mfma_f32_16x16x32_bf16 v[16:19], v[152:155], v[204:207], v[16:19]
	v_mfma_f32_16x16x32_bf16 v[24:27], v[144:147], v[204:207], v[24:27]
	v_mfma_f32_16x16x32_bf16 v[24:27], v[140:143], v[200:203], v[24:27]
	s_setprio 0
	s_barrier
	s_add_i32 s63, 0, 0x18000
	s_add_i32 s64, 0, 0x1c000
	v_add_u32_e32 v152, s63, v217
	v_add_u32_e32 v160, s64, v217
	ds_read_b128 v[140:143], v152
	ds_read_b128 v[144:147], v152 offset:1024
	ds_read_b128 v[148:151], v152 offset:2048
	ds_read_b128 v[152:155], v152 offset:3072
	ds_read_b128 v[156:159], v160
	ds_read_b128 v[164:167], v160 offset:1024
	ds_read_b128 v[168:171], v160 offset:2048
	ds_read_b128 v[172:175], v160 offset:3072
	s_add_u32 s30, s30, 0x4000
	s_addc_u32 s31, s31, 0
	s_mov_b32 m0, s40
	v_lshl_add_u64 v[160:161], s[30:31], 0, v[128:129]
	ds_read_b128 v[176:179], v222 offset:32768
	ds_read_b128 v[180:183], v222 offset:33792
	ds_read_b128 v[184:187], v222 offset:34816
	ds_read_b128 v[188:191], v222 offset:35840
	ds_read_b128 v[192:195], v222 offset:36864
	ds_read_b128 v[196:199], v222 offset:37888
	ds_read_b128 v[200:203], v222 offset:38912
	ds_read_b128 v[204:207], v222 offset:39936
	global_load_lds_dwordx4 v[160:161], off
	v_lshl_add_u64 v[160:161], s[30:31], 0, v[130:131]
	s_mov_b32 m0, s41
	s_nop 0
	global_load_lds_dwordx4 v[160:161], off
	s_waitcnt vmcnt(8)
	s_waitcnt lgkmcnt(0)
	s_barrier
	s_setprio 1
	v_mfma_f32_16x16x32_bf16 v[124:127], v[140:143], v[176:179], v[124:127]
	v_mfma_f32_16x16x32_bf16 v[124:127], v[144:147], v[180:183], v[124:127]
	v_mfma_f32_16x16x32_bf16 v[120:123], v[152:155], v[180:183], v[120:123]
	v_mfma_f32_16x16x32_bf16 v[120:123], v[148:151], v[176:179], v[120:123]
	v_mfma_f32_16x16x32_bf16 v[108:111], v[156:159], v[176:179], v[108:111]
	v_mfma_f32_16x16x32_bf16 v[108:111], v[164:167], v[180:183], v[108:111]
	v_mfma_f32_16x16x32_bf16 v[100:103], v[172:175], v[180:183], v[100:103]
	v_mfma_f32_16x16x32_bf16 v[100:103], v[168:171], v[176:179], v[100:103]
	v_mfma_f32_16x16x32_bf16 v[84:87], v[168:171], v[184:187], v[84:87]
	v_mfma_f32_16x16x32_bf16 v[84:87], v[172:175], v[188:191], v[84:87]
	v_mfma_f32_16x16x32_bf16 v[92:95], v[164:167], v[188:191], v[92:95]
	v_mfma_f32_16x16x32_bf16 v[92:95], v[156:159], v[184:187], v[92:95]
	v_mfma_f32_16x16x32_bf16 v[112:115], v[148:151], v[184:187], v[112:115]
	v_mfma_f32_16x16x32_bf16 v[112:115], v[152:155], v[188:191], v[112:115]
	v_mfma_f32_16x16x32_bf16 v[116:119], v[144:147], v[188:191], v[116:119]
	v_mfma_f32_16x16x32_bf16 v[116:119], v[140:143], v[184:187], v[116:119]
	v_mfma_f32_16x16x32_bf16 v[104:107], v[140:143], v[192:195], v[104:107]
	v_mfma_f32_16x16x32_bf16 v[104:107], v[144:147], v[196:199], v[104:107]
	v_mfma_f32_16x16x32_bf16 v[96:99], v[152:155], v[196:199], v[96:99]
	v_mfma_f32_16x16x32_bf16 v[96:99], v[148:151], v[192:195], v[96:99]
	v_mfma_f32_16x16x32_bf16 v[76:79], v[156:159], v[192:195], v[76:79]
	v_mfma_f32_16x16x32_bf16 v[76:79], v[164:167], v[196:199], v[76:79]
	v_mfma_f32_16x16x32_bf16 v[72:75], v[172:175], v[196:199], v[72:75]
	v_mfma_f32_16x16x32_bf16 v[72:75], v[168:171], v[192:195], v[72:75]
	v_mfma_f32_16x16x32_bf16 v[64:67], v[168:171], v[200:203], v[64:67]
	v_mfma_f32_16x16x32_bf16 v[64:67], v[172:175], v[204:207], v[64:67]
	v_mfma_f32_16x16x32_bf16 v[68:71], v[164:167], v[204:207], v[68:71]
	v_mfma_f32_16x16x32_bf16 v[68:71], v[156:159], v[200:203], v[68:71]
	v_mfma_f32_16x16x32_bf16 v[80:83], v[148:151], v[200:203], v[80:83]
	v_mfma_f32_16x16x32_bf16 v[80:83], v[152:155], v[204:207], v[80:83]
	v_mfma_f32_16x16x32_bf16 v[88:91], v[144:147], v[204:207], v[88:91]
	v_mfma_f32_16x16x32_bf16 v[88:91], v[140:143], v[200:203], v[88:91]
	s_setprio 0
	s_barrier
	s_add_u32 s30, s28, 0x8000
	s_addc_u32 s31, s29, 0
	s_add_i32 s63, s63, s37
	v_lshl_add_u64 v[160:161], s[30:31], 0, v[128:129]
	s_mov_b32 m0, s63
	ds_read_b128 v[176:179], v222 offset:49152
	ds_read_b128 v[180:183], v222 offset:50176
	ds_read_b128 v[184:187], v222 offset:51200
	ds_read_b128 v[188:191], v222 offset:52224
	ds_read_b128 v[192:195], v222 offset:53248
	ds_read_b128 v[196:199], v222 offset:54272
	ds_read_b128 v[200:203], v222 offset:55296
	ds_read_b128 v[204:207], v222 offset:56320
	global_load_lds_dwordx4 v[160:161], off
	s_add_i32 m0, s63, 0x2000
	s_add_u32 s28, s28, 0xc000
	v_lshl_add_u64 v[160:161], s[30:31], 0, v[130:131]
	s_addc_u32 s29, s29, 0
	s_add_i32 s30, s64, s37
	global_load_lds_dwordx4 v[160:161], off
	v_lshl_add_u64 v[160:161], s[28:29], 0, v[128:129]
	s_mov_b32 m0, s30
	s_nop 0
	global_load_lds_dwordx4 v[160:161], off
	v_lshl_add_u64 v[160:161], s[28:29], 0, v[130:131]
	s_add_i32 m0, s30, 0x2000
	s_nop 0
	global_load_lds_dwordx4 v[160:161], off
	v_lshl_add_u64 v[160:161], s[26:27], 0, v[128:129]
	s_mov_b32 m0, s44
	s_nop 0
	global_load_lds_dwordx4 v[160:161], off
	v_lshl_add_u64 v[160:161], s[26:27], 0, v[130:131]
	s_mov_b32 m0, s45
	s_nop 0
	global_load_lds_dwordx4 v[160:161], off
	s_waitcnt vmcnt(8)
	s_waitcnt lgkmcnt(0)
	s_barrier
	s_setprio 1
	v_mfma_f32_16x16x32_bf16 v[60:63], v[140:143], v[176:179], v[60:63]
	v_mfma_f32_16x16x32_bf16 v[60:63], v[144:147], v[180:183], v[60:63]
	v_mfma_f32_16x16x32_bf16 v[56:59], v[152:155], v[180:183], v[56:59]
	v_mfma_f32_16x16x32_bf16 v[56:59], v[148:151], v[176:179], v[56:59]
	v_mfma_f32_16x16x32_bf16 v[44:47], v[156:159], v[176:179], v[44:47]
	v_mfma_f32_16x16x32_bf16 v[44:47], v[164:167], v[180:183], v[44:47]
	v_mfma_f32_16x16x32_bf16 v[36:39], v[172:175], v[180:183], v[36:39]
	v_mfma_f32_16x16x32_bf16 v[36:39], v[168:171], v[176:179], v[36:39]
	v_mfma_f32_16x16x32_bf16 v[20:23], v[168:171], v[184:187], v[20:23]
	v_mfma_f32_16x16x32_bf16 v[20:23], v[172:175], v[188:191], v[20:23]
	v_mfma_f32_16x16x32_bf16 v[28:31], v[164:167], v[188:191], v[28:31]
	v_mfma_f32_16x16x32_bf16 v[28:31], v[156:159], v[184:187], v[28:31]
	v_mfma_f32_16x16x32_bf16 v[48:51], v[148:151], v[184:187], v[48:51]
	v_mfma_f32_16x16x32_bf16 v[48:51], v[152:155], v[188:191], v[48:51]
	v_mfma_f32_16x16x32_bf16 v[52:55], v[144:147], v[188:191], v[52:55]
	v_mfma_f32_16x16x32_bf16 v[52:55], v[140:143], v[184:187], v[52:55]
	v_mfma_f32_16x16x32_bf16 v[40:43], v[140:143], v[192:195], v[40:43]
	v_mfma_f32_16x16x32_bf16 v[40:43], v[144:147], v[196:199], v[40:43]
	v_mfma_f32_16x16x32_bf16 v[32:35], v[152:155], v[196:199], v[32:35]
	v_mfma_f32_16x16x32_bf16 v[32:35], v[148:151], v[192:195], v[32:35]
	v_mfma_f32_16x16x32_bf16 v[12:15], v[156:159], v[192:195], v[12:15]
	v_mfma_f32_16x16x32_bf16 v[12:15], v[164:167], v[196:199], v[12:15]
	v_mfma_f32_16x16x32_bf16 v[8:11], v[172:175], v[196:199], v[8:11]
	v_mfma_f32_16x16x32_bf16 v[8:11], v[168:171], v[192:195], v[8:11]
	v_mfma_f32_16x16x32_bf16 v[0:3], v[168:171], v[200:203], v[0:3]
	v_mfma_f32_16x16x32_bf16 v[0:3], v[172:175], v[204:207], v[0:3]
	v_mfma_f32_16x16x32_bf16 v[4:7], v[164:167], v[204:207], v[4:7]
	v_mfma_f32_16x16x32_bf16 v[4:7], v[156:159], v[200:203], v[4:7]
	v_mfma_f32_16x16x32_bf16 v[16:19], v[148:151], v[200:203], v[16:19]
	v_mfma_f32_16x16x32_bf16 v[16:19], v[152:155], v[204:207], v[16:19]
	v_mfma_f32_16x16x32_bf16 v[24:27], v[144:147], v[204:207], v[24:27]
	v_mfma_f32_16x16x32_bf16 v[24:27], v[140:143], v[200:203], v[24:27]
	s_setprio 0
	s_barrier
	s_add_u32 s24, s24, 0x10000
	s_addc_u32 s25, s25, 0
	s_add_u32 s60, s60, 0x10000
	s_addc_u32 s61, s61, 0
	s_cmp_ge_i32 s62, s43
	s_mov_b32 s26, s62
	s_cbranch_scc0 .LBB0_228
	v_pk_mul_f32 v[200:201], v[126:127], 0.5 op_sel_hi:[1,0]
	v_pk_mul_f32 v[202:203], v[124:125], 0.5 op_sel_hi:[1,0]
	v_pk_mul_f32 v[204:205], v[122:123], 0.5 op_sel_hi:[1,0]
	v_pk_mul_f32 v[206:207], v[120:121], 0.5 op_sel_hi:[1,0]
	v_pk_mul_f32 v[210:211], v[110:111], 0.5 op_sel_hi:[1,0]
	v_pk_mul_f32 v[208:209], v[108:109], 0.5 op_sel_hi:[1,0]
	v_pk_mul_f32 v[198:199], v[102:103], 0.5 op_sel_hi:[1,0]
	v_pk_mul_f32 v[196:197], v[100:101], 0.5 op_sel_hi:[1,0]
	v_pk_mul_f32 v[194:195], v[118:119], 0.5 op_sel_hi:[1,0]
	v_pk_mul_f32 v[192:193], v[116:117], 0.5 op_sel_hi:[1,0]
	v_pk_mul_f32 v[190:191], v[114:115], 0.5 op_sel_hi:[1,0]
	v_pk_mul_f32 v[188:189], v[112:113], 0.5 op_sel_hi:[1,0]
	v_pk_mul_f32 v[186:187], v[94:95], 0.5 op_sel_hi:[1,0]
	v_pk_mul_f32 v[184:185], v[92:93], 0.5 op_sel_hi:[1,0]
	v_pk_mul_f32 v[182:183], v[86:87], 0.5 op_sel_hi:[1,0]
	v_pk_mul_f32 v[180:181], v[84:85], 0.5 op_sel_hi:[1,0]
	v_pk_mul_f32 v[178:179], v[106:107], 0.5 op_sel_hi:[1,0]
	v_pk_mul_f32 v[176:177], v[104:105], 0.5 op_sel_hi:[1,0]
	v_pk_mul_f32 v[174:175], v[98:99], 0.5 op_sel_hi:[1,0]
	v_pk_mul_f32 v[172:173], v[96:97], 0.5 op_sel_hi:[1,0]
	v_pk_mul_f32 v[170:171], v[78:79], 0.5 op_sel_hi:[1,0]
	v_pk_mul_f32 v[168:169], v[76:77], 0.5 op_sel_hi:[1,0]
	v_pk_mul_f32 v[166:167], v[74:75], 0.5 op_sel_hi:[1,0]
	v_pk_mul_f32 v[164:165], v[72:73], 0.5 op_sel_hi:[1,0]
	v_pk_mul_f32 v[160:161], v[90:91], 0.5 op_sel_hi:[1,0]
	v_pk_mul_f32 v[158:159], v[88:89], 0.5 op_sel_hi:[1,0]
	v_pk_mul_f32 v[156:157], v[82:83], 0.5 op_sel_hi:[1,0]
	v_pk_mul_f32 v[154:155], v[80:81], 0.5 op_sel_hi:[1,0]
	v_pk_mul_f32 v[152:153], v[70:71], 0.5 op_sel_hi:[1,0]
	v_pk_mul_f32 v[150:151], v[68:69], 0.5 op_sel_hi:[1,0]
	v_pk_mul_f32 v[148:149], v[66:67], 0.5 op_sel_hi:[1,0]
	v_pk_mul_f32 v[146:147], v[64:65], 0.5 op_sel_hi:[1,0]
	v_pk_mul_f32 v[144:145], v[62:63], 0.5 op_sel_hi:[1,0]
	v_pk_mul_f32 v[142:143], v[60:61], 0.5 op_sel_hi:[1,0]
	v_pk_mul_f32 v[126:127], v[58:59], 0.5 op_sel_hi:[1,0]
	v_pk_mul_f32 v[124:125], v[56:57], 0.5 op_sel_hi:[1,0]
	v_pk_mul_f32 v[122:123], v[46:47], 0.5 op_sel_hi:[1,0]
	v_pk_mul_f32 v[120:121], v[44:45], 0.5 op_sel_hi:[1,0]
	v_pk_mul_f32 v[118:119], v[38:39], 0.5 op_sel_hi:[1,0]
	v_pk_mul_f32 v[116:117], v[36:37], 0.5 op_sel_hi:[1,0]
	v_pk_mul_f32 v[114:115], v[54:55], 0.5 op_sel_hi:[1,0]
	v_pk_mul_f32 v[112:113], v[52:53], 0.5 op_sel_hi:[1,0]
	v_pk_mul_f32 v[110:111], v[50:51], 0.5 op_sel_hi:[1,0]
	v_pk_mul_f32 v[108:109], v[48:49], 0.5 op_sel_hi:[1,0]
	v_pk_mul_f32 v[106:107], v[30:31], 0.5 op_sel_hi:[1,0]
	v_pk_mul_f32 v[104:105], v[28:29], 0.5 op_sel_hi:[1,0]
	v_pk_mul_f32 v[102:103], v[22:23], 0.5 op_sel_hi:[1,0]
	v_pk_mul_f32 v[100:101], v[20:21], 0.5 op_sel_hi:[1,0]
	v_pk_mul_f32 v[98:99], v[42:43], 0.5 op_sel_hi:[1,0]
	v_pk_mul_f32 v[96:97], v[40:41], 0.5 op_sel_hi:[1,0]
	v_pk_mul_f32 v[94:95], v[34:35], 0.5 op_sel_hi:[1,0]
	v_pk_mul_f32 v[92:93], v[32:33], 0.5 op_sel_hi:[1,0]
	v_pk_mul_f32 v[90:91], v[14:15], 0.5 op_sel_hi:[1,0]
	v_pk_mul_f32 v[88:89], v[12:13], 0.5 op_sel_hi:[1,0]
	v_pk_mul_f32 v[86:87], v[10:11], 0.5 op_sel_hi:[1,0]
	v_pk_mul_f32 v[84:85], v[8:9], 0.5 op_sel_hi:[1,0]
	v_pk_mul_f32 v[82:83], v[26:27], 0.5 op_sel_hi:[1,0]
	v_pk_mul_f32 v[80:81], v[24:25], 0.5 op_sel_hi:[1,0]
	v_pk_mul_f32 v[78:79], v[18:19], 0.5 op_sel_hi:[1,0]
	v_pk_mul_f32 v[76:77], v[16:17], 0.5 op_sel_hi:[1,0]
	v_pk_mul_f32 v[74:75], v[6:7], 0.5 op_sel_hi:[1,0]
	v_pk_mul_f32 v[72:73], v[4:5], 0.5 op_sel_hi:[1,0]
	v_pk_mul_f32 v[70:71], v[2:3], 0.5 op_sel_hi:[1,0]
	v_pk_mul_f32 v[68:69], v[0:1], 0.5 op_sel_hi:[1,0]

.LBB0_323:
	ds_read_b128 v[128:131], v222
	ds_read_b128 v[132:135], v222 offset:1024
	ds_read_b128 v[136:139], v222 offset:2048
	ds_read_b128 v[140:143], v222 offset:3072
	ds_read_b128 v[144:147], v223
	ds_read_b128 v[148:151], v223 offset:1024
	ds_read_b128 v[152:155], v223 offset:2048
	ds_read_b128 v[156:159], v223 offset:3072
	s_add_i32 s53, s50, 2
	s_add_u32 s54, s0, 0x80
	s_addc_u32 s51, s1, 0
	s_cmp_eq_u32 s78, s50
	s_cselect_b32 s50, s46, s54
	s_cselect_b32 s51, s47, s51
	s_cselect_b32 s55, s49, s52
	s_cselect_b32 s54, s48, s33
	v_lshl_add_u64 v[160:161], s[0:1], 0, v[176:177]
	s_add_i32 m0, s71, 0xc000
	ds_read_b128 v[184:187], v224
	ds_read_b128 v[188:191], v224 offset:1024
	ds_read_b128 v[192:195], v224 offset:2048
	ds_read_b128 v[196:199], v224 offset:3072
	ds_read_b128 v[200:203], v224 offset:4096
	ds_read_b128 v[204:207], v224 offset:5120
	ds_read_b128 v[208:211], v224 offset:6144
	ds_read_b128 v[212:215], v224 offset:7168
	global_load_lds_dwordx4 v[160:161], off
	v_lshl_add_u64 v[160:161], s[0:1], 0, v[178:179]
	s_add_i32 m0, s71, 0xe000
	s_nop 0
	global_load_lds_dwordx4 v[160:161], off
	s_waitcnt vmcnt(8)
	s_waitcnt lgkmcnt(0)
	s_barrier
	s_setprio 1
	v_mfma_f32_16x16x32_bf16 v[124:127], v[128:131], v[184:187], v[124:127]
	v_mfma_f32_16x16x32_bf16 v[124:127], v[132:135], v[188:191], v[124:127]
	v_mfma_f32_16x16x32_bf16 v[120:123], v[140:143], v[188:191], v[120:123]
	v_mfma_f32_16x16x32_bf16 v[120:123], v[136:139], v[184:187], v[120:123]
	v_mfma_f32_16x16x32_bf16 v[116:119], v[144:147], v[184:187], v[116:119]
	v_mfma_f32_16x16x32_bf16 v[116:119], v[148:151], v[188:191], v[116:119]
	v_mfma_f32_16x16x32_bf16 v[112:115], v[156:159], v[188:191], v[112:115]
	v_mfma_f32_16x16x32_bf16 v[112:115], v[152:155], v[184:187], v[112:115]
	v_mfma_f32_16x16x32_bf16 v[96:99], v[152:155], v[192:195], v[96:99]
	v_mfma_f32_16x16x32_bf16 v[96:99], v[156:159], v[196:199], v[96:99]
	v_mfma_f32_16x16x32_bf16 v[100:103], v[148:151], v[196:199], v[100:103]
	v_mfma_f32_16x16x32_bf16 v[100:103], v[144:147], v[192:195], v[100:103]
	v_mfma_f32_16x16x32_bf16 v[104:107], v[136:139], v[192:195], v[104:107]
	v_mfma_f32_16x16x32_bf16 v[104:107], v[140:143], v[196:199], v[104:107]
	v_mfma_f32_16x16x32_bf16 v[108:111], v[132:135], v[196:199], v[108:111]
	v_mfma_f32_16x16x32_bf16 v[108:111], v[128:131], v[192:195], v[108:111]
	v_mfma_f32_16x16x32_bf16 v[92:95], v[128:131], v[200:203], v[92:95]
	v_mfma_f32_16x16x32_bf16 v[92:95], v[132:135], v[204:207], v[92:95]
	v_mfma_f32_16x16x32_bf16 v[88:91], v[140:143], v[204:207], v[88:91]
	v_mfma_f32_16x16x32_bf16 v[88:91], v[136:139], v[200:203], v[88:91]
	v_mfma_f32_16x16x32_bf16 v[84:87], v[144:147], v[200:203], v[84:87]
	v_mfma_f32_16x16x32_bf16 v[84:87], v[148:151], v[204:207], v[84:87]
	v_mfma_f32_16x16x32_bf16 v[80:83], v[156:159], v[204:207], v[80:83]
	v_mfma_f32_16x16x32_bf16 v[80:83], v[152:155], v[200:203], v[80:83]
	v_mfma_f32_16x16x32_bf16 v[64:67], v[152:155], v[208:211], v[64:67]
	v_mfma_f32_16x16x32_bf16 v[64:67], v[156:159], v[212:215], v[64:67]
	v_mfma_f32_16x16x32_bf16 v[68:71], v[148:151], v[212:215], v[68:71]
	v_mfma_f32_16x16x32_bf16 v[68:71], v[144:147], v[208:211], v[68:71]
	v_mfma_f32_16x16x32_bf16 v[72:75], v[136:139], v[208:211], v[72:75]
	v_mfma_f32_16x16x32_bf16 v[72:75], v[140:143], v[212:215], v[72:75]
	v_mfma_f32_16x16x32_bf16 v[76:79], v[132:135], v[212:215], v[76:79]
	v_mfma_f32_16x16x32_bf16 v[76:79], v[128:131], v[208:211], v[76:79]
	s_setprio 0
	s_barrier
	s_add_i32 s60, s82, s70
	v_lshl_add_u64 v[160:161], s[54:55], 0, v[166:167]
	s_mov_b32 m0, s60
	ds_read_b128 v[184:187], v224 offset:16384
	ds_read_b128 v[188:191], v224 offset:17408
	ds_read_b128 v[192:195], v224 offset:18432
	ds_read_b128 v[196:199], v224 offset:19456
	ds_read_b128 v[200:203], v224 offset:20480
	ds_read_b128 v[204:207], v224 offset:21504
	ds_read_b128 v[208:211], v224 offset:22528
	ds_read_b128 v[212:215], v224 offset:23552
	global_load_lds_dwordx4 v[160:161], off
	s_add_i32 m0, s60, 0x2000
	v_lshl_add_u64 v[216:217], s[54:55], 0, v[170:171]
	s_add_u32 s54, s54, s10
	s_addc_u32 s55, s55, s11
	s_add_i32 s60, s83, s70
	global_load_lds_dwordx4 v[216:217], off
	v_lshl_add_u64 v[218:219], s[54:55], 0, v[166:167]
	s_mov_b32 m0, s60
	v_lshl_add_u64 v[230:231], s[54:55], 0, v[170:171]
	global_load_lds_dwordx4 v[218:219], off
	s_add_i32 m0, s60, 0x2000
	v_lshl_add_u64 v[232:233], s[50:51], 0, v[164:165]
	global_load_lds_dwordx4 v[230:231], off
	s_mov_b32 m0, s71
	v_lshl_add_u64 v[234:235], s[50:51], 0, v[168:169]
	global_load_lds_dwordx4 v[232:233], off
	s_mov_b32 m0, s72
	s_nop 0
	global_load_lds_dwordx4 v[234:235], off
	s_waitcnt vmcnt(8)
	s_waitcnt lgkmcnt(0)
	s_barrier
	s_setprio 1
	v_mfma_f32_16x16x32_bf16 v[60:63], v[128:131], v[184:187], v[60:63]
	v_mfma_f32_16x16x32_bf16 v[60:63], v[132:135], v[188:191], v[60:63]
	v_mfma_f32_16x16x32_bf16 v[56:59], v[140:143], v[188:191], v[56:59]
	v_mfma_f32_16x16x32_bf16 v[56:59], v[136:139], v[184:187], v[56:59]
	v_mfma_f32_16x16x32_bf16 v[52:55], v[144:147], v[184:187], v[52:55]
	v_mfma_f32_16x16x32_bf16 v[52:55], v[148:151], v[188:191], v[52:55]
	v_mfma_f32_16x16x32_bf16 v[48:51], v[156:159], v[188:191], v[48:51]
	v_mfma_f32_16x16x32_bf16 v[48:51], v[152:155], v[184:187], v[48:51]
	v_mfma_f32_16x16x32_bf16 v[32:35], v[152:155], v[192:195], v[32:35]
	v_mfma_f32_16x16x32_bf16 v[32:35], v[156:159], v[196:199], v[32:35]
	v_mfma_f32_16x16x32_bf16 v[36:39], v[148:151], v[196:199], v[36:39]
	v_mfma_f32_16x16x32_bf16 v[36:39], v[144:147], v[192:195], v[36:39]
	v_mfma_f32_16x16x32_bf16 v[40:43], v[136:139], v[192:195], v[40:43]
	v_mfma_f32_16x16x32_bf16 v[40:43], v[140:143], v[196:199], v[40:43]
	v_mfma_f32_16x16x32_bf16 v[44:47], v[132:135], v[196:199], v[44:47]
	v_mfma_f32_16x16x32_bf16 v[44:47], v[128:131], v[192:195], v[44:47]
	v_mfma_f32_16x16x32_bf16 v[28:31], v[128:131], v[200:203], v[28:31]
	v_mfma_f32_16x16x32_bf16 v[28:31], v[132:135], v[204:207], v[28:31]
	v_mfma_f32_16x16x32_bf16 v[24:27], v[140:143], v[204:207], v[24:27]
	v_mfma_f32_16x16x32_bf16 v[24:27], v[136:139], v[200:203], v[24:27]
	v_mfma_f32_16x16x32_bf16 v[20:23], v[144:147], v[200:203], v[20:23]
	v_mfma_f32_16x16x32_bf16 v[20:23], v[148:151], v[204:207], v[20:23]
	v_mfma_f32_16x16x32_bf16 v[16:19], v[156:159], v[204:207], v[16:19]
	v_mfma_f32_16x16x32_bf16 v[16:19], v[152:155], v[200:203], v[16:19]
	v_mfma_f32_16x16x32_bf16 v[0:3], v[152:155], v[208:211], v[0:3]
	v_mfma_f32_16x16x32_bf16 v[0:3], v[156:159], v[212:215], v[0:3]
	v_mfma_f32_16x16x32_bf16 v[4:7], v[148:151], v[212:215], v[4:7]
	v_mfma_f32_16x16x32_bf16 v[4:7], v[144:147], v[208:211], v[4:7]
	v_mfma_f32_16x16x32_bf16 v[8:11], v[136:139], v[208:211], v[8:11]
	v_mfma_f32_16x16x32_bf16 v[8:11], v[140:143], v[212:215], v[8:11]
	v_mfma_f32_16x16x32_bf16 v[12:15], v[132:135], v[212:215], v[12:15]
	v_mfma_f32_16x16x32_bf16 v[12:15], v[128:131], v[208:211], v[12:15]
	s_setprio 0
	s_barrier
	s_add_i32 s54, 0, 0x18000
	s_add_i32 s55, 0, 0x1c000
	v_add_u32_e32 v140, s54, v221
	v_add_u32_e32 v156, s55, v221
	ds_read_b128 v[128:131], v140
	ds_read_b128 v[132:135], v140 offset:1024
	ds_read_b128 v[136:139], v140 offset:2048
	ds_read_b128 v[140:143], v140 offset:3072
	ds_read_b128 v[144:147], v156
	ds_read_b128 v[148:151], v156 offset:1024
	ds_read_b128 v[152:155], v156 offset:2048
	ds_read_b128 v[156:159], v156 offset:3072
	s_add_u32 s50, s50, s10
	s_addc_u32 s51, s51, s11
	s_mov_b32 m0, s73
	v_lshl_add_u64 v[236:237], s[50:51], 0, v[164:165]
	ds_read_b128 v[184:187], v224 offset:32768
	ds_read_b128 v[188:191], v224 offset:33792
	ds_read_b128 v[192:195], v224 offset:34816
	ds_read_b128 v[196:199], v224 offset:35840
	ds_read_b128 v[200:203], v224 offset:36864
	ds_read_b128 v[204:207], v224 offset:37888
	ds_read_b128 v[208:211], v224 offset:38912
	ds_read_b128 v[212:215], v224 offset:39936
	global_load_lds_dwordx4 v[236:237], off
	v_lshl_add_u64 v[236:237], s[50:51], 0, v[168:169]
	s_mov_b32 m0, s74
	s_nop 0
	global_load_lds_dwordx4 v[236:237], off
	s_waitcnt vmcnt(8)
	s_waitcnt lgkmcnt(0)
	s_barrier
	s_setprio 1
	v_mfma_f32_16x16x32_bf16 v[124:127], v[128:131], v[184:187], v[124:127]
	v_mfma_f32_16x16x32_bf16 v[124:127], v[132:135], v[188:191], v[124:127]
	v_mfma_f32_16x16x32_bf16 v[120:123], v[140:143], v[188:191], v[120:123]
	v_mfma_f32_16x16x32_bf16 v[120:123], v[136:139], v[184:187], v[120:123]
	v_mfma_f32_16x16x32_bf16 v[116:119], v[144:147], v[184:187], v[116:119]
	v_mfma_f32_16x16x32_bf16 v[116:119], v[148:151], v[188:191], v[116:119]
	v_mfma_f32_16x16x32_bf16 v[112:115], v[156:159], v[188:191], v[112:115]
	v_mfma_f32_16x16x32_bf16 v[112:115], v[152:155], v[184:187], v[112:115]
	v_mfma_f32_16x16x32_bf16 v[96:99], v[152:155], v[192:195], v[96:99]
	v_mfma_f32_16x16x32_bf16 v[96:99], v[156:159], v[196:199], v[96:99]
	v_mfma_f32_16x16x32_bf16 v[100:103], v[148:151], v[196:199], v[100:103]
	v_mfma_f32_16x16x32_bf16 v[100:103], v[144:147], v[192:195], v[100:103]
	v_mfma_f32_16x16x32_bf16 v[104:107], v[136:139], v[192:195], v[104:107]
	v_mfma_f32_16x16x32_bf16 v[104:107], v[140:143], v[196:199], v[104:107]
	v_mfma_f32_16x16x32_bf16 v[108:111], v[132:135], v[196:199], v[108:111]
	v_mfma_f32_16x16x32_bf16 v[108:111], v[128:131], v[192:195], v[108:111]
	v_mfma_f32_16x16x32_bf16 v[92:95], v[128:131], v[200:203], v[92:95]
	v_mfma_f32_16x16x32_bf16 v[92:95], v[132:135], v[204:207], v[92:95]
	v_mfma_f32_16x16x32_bf16 v[88:91], v[140:143], v[204:207], v[88:91]
	v_mfma_f32_16x16x32_bf16 v[88:91], v[136:139], v[200:203], v[88:91]
	v_mfma_f32_16x16x32_bf16 v[84:87], v[144:147], v[200:203], v[84:87]
	v_mfma_f32_16x16x32_bf16 v[84:87], v[148:151], v[204:207], v[84:87]
	v_mfma_f32_16x16x32_bf16 v[80:83], v[156:159], v[204:207], v[80:83]
	v_mfma_f32_16x16x32_bf16 v[80:83], v[152:155], v[200:203], v[80:83]
	v_mfma_f32_16x16x32_bf16 v[64:67], v[152:155], v[208:211], v[64:67]
	v_mfma_f32_16x16x32_bf16 v[64:67], v[156:159], v[212:215], v[64:67]
	v_mfma_f32_16x16x32_bf16 v[68:71], v[148:151], v[212:215], v[68:71]
	v_mfma_f32_16x16x32_bf16 v[68:71], v[144:147], v[208:211], v[68:71]
	v_mfma_f32_16x16x32_bf16 v[72:75], v[136:139], v[208:211], v[72:75]
	v_mfma_f32_16x16x32_bf16 v[72:75], v[140:143], v[212:215], v[72:75]
	v_mfma_f32_16x16x32_bf16 v[76:79], v[132:135], v[212:215], v[76:79]
	v_mfma_f32_16x16x32_bf16 v[76:79], v[128:131], v[208:211], v[76:79]
	s_setprio 0
	s_barrier
	s_add_i32 s50, s54, s70
	v_lshl_add_u64 v[160:161], v[160:161], 0, s[36:37]
	s_mov_b32 m0, s50
	ds_read_b128 v[184:187], v224 offset:49152
	ds_read_b128 v[188:191], v224 offset:50176
	ds_read_b128 v[192:195], v224 offset:51200
	ds_read_b128 v[196:199], v224 offset:52224
	ds_read_b128 v[200:203], v224 offset:53248
	ds_read_b128 v[204:207], v224 offset:54272
	ds_read_b128 v[208:211], v224 offset:55296
	ds_read_b128 v[212:215], v224 offset:56320
	global_load_lds_dwordx4 v[160:161], off
	v_lshl_add_u64 v[160:161], v[216:217], 0, s[36:37]
	s_add_i32 m0, s50, 0x2000
	s_add_i32 s50, s55, s70
	global_load_lds_dwordx4 v[160:161], off
	v_lshl_add_u64 v[160:161], v[218:219], 0, s[36:37]
	s_mov_b32 m0, s50
	s_nop 0
	global_load_lds_dwordx4 v[160:161], off
	v_lshl_add_u64 v[160:161], v[230:231], 0, s[36:37]
	s_add_i32 m0, s50, 0x2000
	s_nop 0
	global_load_lds_dwordx4 v[160:161], off
	v_lshl_add_u64 v[160:161], v[232:233], 0, s[36:37]
	s_mov_b32 m0, s76
	s_nop 0
	global_load_lds_dwordx4 v[160:161], off
	v_lshl_add_u64 v[160:161], v[234:235], 0, s[36:37]
	s_mov_b32 m0, s77
	s_nop 0
	global_load_lds_dwordx4 v[160:161], off
	s_waitcnt vmcnt(8)
	s_waitcnt lgkmcnt(0)
	s_barrier
	s_setprio 1
	v_mfma_f32_16x16x32_bf16 v[60:63], v[128:131], v[184:187], v[60:63]
	v_mfma_f32_16x16x32_bf16 v[60:63], v[132:135], v[188:191], v[60:63]
	v_mfma_f32_16x16x32_bf16 v[56:59], v[140:143], v[188:191], v[56:59]
	v_mfma_f32_16x16x32_bf16 v[56:59], v[136:139], v[184:187], v[56:59]
	v_mfma_f32_16x16x32_bf16 v[52:55], v[144:147], v[184:187], v[52:55]
	v_mfma_f32_16x16x32_bf16 v[52:55], v[148:151], v[188:191], v[52:55]
	v_mfma_f32_16x16x32_bf16 v[48:51], v[156:159], v[188:191], v[48:51]
	v_mfma_f32_16x16x32_bf16 v[48:51], v[152:155], v[184:187], v[48:51]
	v_mfma_f32_16x16x32_bf16 v[32:35], v[152:155], v[192:195], v[32:35]
	v_mfma_f32_16x16x32_bf16 v[32:35], v[156:159], v[196:199], v[32:35]
	v_mfma_f32_16x16x32_bf16 v[36:39], v[148:151], v[196:199], v[36:39]
	v_mfma_f32_16x16x32_bf16 v[36:39], v[144:147], v[192:195], v[36:39]
	v_mfma_f32_16x16x32_bf16 v[40:43], v[136:139], v[192:195], v[40:43]
	v_mfma_f32_16x16x32_bf16 v[40:43], v[140:143], v[196:199], v[40:43]
	v_mfma_f32_16x16x32_bf16 v[44:47], v[132:135], v[196:199], v[44:47]
	v_mfma_f32_16x16x32_bf16 v[44:47], v[128:131], v[192:195], v[44:47]
	v_mfma_f32_16x16x32_bf16 v[28:31], v[128:131], v[200:203], v[28:31]
	v_mfma_f32_16x16x32_bf16 v[28:31], v[132:135], v[204:207], v[28:31]
	v_mfma_f32_16x16x32_bf16 v[24:27], v[140:143], v[204:207], v[24:27]
	v_mfma_f32_16x16x32_bf16 v[24:27], v[136:139], v[200:203], v[24:27]
	v_mfma_f32_16x16x32_bf16 v[20:23], v[144:147], v[200:203], v[20:23]
	v_mfma_f32_16x16x32_bf16 v[20:23], v[148:151], v[204:207], v[20:23]
	v_mfma_f32_16x16x32_bf16 v[16:19], v[156:159], v[204:207], v[16:19]
	v_mfma_f32_16x16x32_bf16 v[16:19], v[152:155], v[200:203], v[16:19]
	v_mfma_f32_16x16x32_bf16 v[0:3], v[152:155], v[208:211], v[0:3]
	v_mfma_f32_16x16x32_bf16 v[0:3], v[156:159], v[212:215], v[0:3]
	v_mfma_f32_16x16x32_bf16 v[4:7], v[148:151], v[212:215], v[4:7]
	v_mfma_f32_16x16x32_bf16 v[4:7], v[144:147], v[208:211], v[4:7]
	v_mfma_f32_16x16x32_bf16 v[8:11], v[136:139], v[208:211], v[8:11]
	v_mfma_f32_16x16x32_bf16 v[8:11], v[140:143], v[212:215], v[8:11]
	v_mfma_f32_16x16x32_bf16 v[12:15], v[132:135], v[212:215], v[12:15]
	v_mfma_f32_16x16x32_bf16 v[12:15], v[128:131], v[208:211], v[12:15]
	s_setprio 0
	s_barrier
	s_add_u32 s0, s0, 0x100
	s_addc_u32 s1, s1, 0
	s_add_u32 s33, s33, 0x100
	s_addc_u32 s52, s52, 0
	s_cmp_ge_i32 s53, s75
	s_mov_b32 s50, s53
	s_cbranch_scc0 .LBB0_323

.LBB0_592:
	ds_read_b128 v[144:147], v157
	ds_read_b128 v[148:151], v157 offset:1024
	ds_read_b128 v[164:167], v157 offset:2048
	ds_read_b128 v[168:171], v157 offset:3072
	ds_read_b128 v[172:175], v158
	ds_read_b128 v[176:179], v158 offset:1024
	ds_read_b128 v[180:183], v158 offset:2048
	ds_read_b128 v[184:187], v158 offset:3072
	s_add_i32 s64, s34, 2
	s_add_u32 s65, s30, 0x80
	s_addc_u32 s35, s31, 0
	s_cmp_eq_u32 s49, s34
	s_cselect_b32 s34, s2, s65
	s_cselect_b32 s35, s3, s35
	s_cselect_b32 s67, s29, s63
	s_cselect_b32 s66, s28, s62
	v_lshl_add_u64 v[152:153], s[30:31], 0, v[136:137]
	s_add_i32 m0, s41, 0xc000
	ds_read_b128 v[188:191], v159
	ds_read_b128 v[192:195], v159 offset:1024
	ds_read_b128 v[196:199], v159 offset:2048
	ds_read_b128 v[200:203], v159 offset:3072
	ds_read_b128 v[204:207], v159 offset:4096
	ds_read_b128 v[208:211], v159 offset:5120
	ds_read_b128 v[212:215], v159 offset:6144
	ds_read_b128 v[216:219], v159 offset:7168
	global_load_lds_dwordx4 v[152:153], off
	v_lshl_add_u64 v[152:153], s[30:31], 0, v[138:139]
	s_add_i32 m0, s41, 0xe000
	s_nop 0
	global_load_lds_dwordx4 v[152:153], off
	s_waitcnt vmcnt(8)
	s_waitcnt lgkmcnt(0)
	s_barrier
	s_setprio 1
	v_mfma_f32_16x16x32_bf16 v[120:123], v[144:147], v[188:191], v[120:123]
	v_mfma_f32_16x16x32_bf16 v[120:123], v[148:151], v[192:195], v[120:123]
	v_mfma_f32_16x16x32_bf16 v[124:127], v[168:171], v[192:195], v[124:127]
	v_mfma_f32_16x16x32_bf16 v[124:127], v[164:167], v[188:191], v[124:127]
	v_mfma_f32_16x16x32_bf16 v[116:119], v[172:175], v[188:191], v[116:119]
	v_mfma_f32_16x16x32_bf16 v[116:119], v[176:179], v[192:195], v[116:119]
	v_mfma_f32_16x16x32_bf16 v[112:115], v[184:187], v[192:195], v[112:115]
	v_mfma_f32_16x16x32_bf16 v[112:115], v[180:183], v[188:191], v[112:115]
	v_mfma_f32_16x16x32_bf16 v[96:99], v[180:183], v[196:199], v[96:99]
	v_mfma_f32_16x16x32_bf16 v[96:99], v[184:187], v[200:203], v[96:99]
	v_mfma_f32_16x16x32_bf16 v[100:103], v[176:179], v[200:203], v[100:103]
	v_mfma_f32_16x16x32_bf16 v[100:103], v[172:175], v[196:199], v[100:103]
	v_mfma_f32_16x16x32_bf16 v[104:107], v[164:167], v[196:199], v[104:107]
	v_mfma_f32_16x16x32_bf16 v[104:107], v[168:171], v[200:203], v[104:107]
	v_mfma_f32_16x16x32_bf16 v[108:111], v[148:151], v[200:203], v[108:111]
	v_mfma_f32_16x16x32_bf16 v[108:111], v[144:147], v[196:199], v[108:111]
	v_mfma_f32_16x16x32_bf16 v[92:95], v[144:147], v[204:207], v[92:95]
	v_mfma_f32_16x16x32_bf16 v[92:95], v[148:151], v[208:211], v[92:95]
	v_mfma_f32_16x16x32_bf16 v[88:91], v[168:171], v[208:211], v[88:91]
	v_mfma_f32_16x16x32_bf16 v[88:91], v[164:167], v[204:207], v[88:91]
	v_mfma_f32_16x16x32_bf16 v[84:87], v[172:175], v[204:207], v[84:87]
	v_mfma_f32_16x16x32_bf16 v[84:87], v[176:179], v[208:211], v[84:87]
	v_mfma_f32_16x16x32_bf16 v[80:83], v[184:187], v[208:211], v[80:83]
	v_mfma_f32_16x16x32_bf16 v[80:83], v[180:183], v[204:207], v[80:83]
	v_mfma_f32_16x16x32_bf16 v[64:67], v[180:183], v[212:215], v[64:67]
	v_mfma_f32_16x16x32_bf16 v[64:67], v[184:187], v[216:219], v[64:67]
	v_mfma_f32_16x16x32_bf16 v[68:71], v[176:179], v[216:219], v[68:71]
	v_mfma_f32_16x16x32_bf16 v[68:71], v[172:175], v[212:215], v[68:71]
	v_mfma_f32_16x16x32_bf16 v[72:75], v[164:167], v[212:215], v[72:75]
	v_mfma_f32_16x16x32_bf16 v[72:75], v[168:171], v[216:219], v[72:75]
	v_mfma_f32_16x16x32_bf16 v[76:79], v[148:151], v[216:219], v[76:79]
	v_mfma_f32_16x16x32_bf16 v[76:79], v[144:147], v[212:215], v[76:79]
	s_setprio 0
	s_barrier
	s_add_i32 s65, s52, s40
	v_lshl_add_u64 v[152:153], s[66:67], 0, v[130:131]
	s_mov_b32 m0, s65
	ds_read_b128 v[188:191], v159 offset:16384
	ds_read_b128 v[192:195], v159 offset:17408
	ds_read_b128 v[196:199], v159 offset:18432
	ds_read_b128 v[200:203], v159 offset:19456
	ds_read_b128 v[204:207], v159 offset:20480
	ds_read_b128 v[208:211], v159 offset:21504
	ds_read_b128 v[212:215], v159 offset:22528
	ds_read_b128 v[216:219], v159 offset:23552
	global_load_lds_dwordx4 v[152:153], off
	s_add_i32 m0, s65, 0x2000
	v_lshl_add_u64 v[160:161], s[66:67], 0, v[134:135]
	s_add_u32 s66, s66, s8
	s_addc_u32 s67, s67, s9
	s_add_i32 s65, s53, s40
	global_load_lds_dwordx4 v[160:161], off
	v_lshl_add_u64 v[222:223], s[66:67], 0, v[130:131]
	s_mov_b32 m0, s65
	v_lshl_add_u64 v[224:225], s[66:67], 0, v[134:135]
	global_load_lds_dwordx4 v[222:223], off
	s_add_i32 m0, s65, 0x2000
	v_lshl_add_u64 v[226:227], s[34:35], 0, v[128:129]
	global_load_lds_dwordx4 v[224:225], off
	s_mov_b32 m0, s41
	v_lshl_add_u64 v[228:229], s[34:35], 0, v[132:133]
	global_load_lds_dwordx4 v[226:227], off
	s_mov_b32 m0, s42
	s_nop 0
	global_load_lds_dwordx4 v[228:229], off
	s_waitcnt vmcnt(8)
	s_waitcnt lgkmcnt(0)
	s_barrier
	s_setprio 1
	v_mfma_f32_16x16x32_bf16 v[60:63], v[144:147], v[188:191], v[60:63]
	v_mfma_f32_16x16x32_bf16 v[60:63], v[148:151], v[192:195], v[60:63]
	v_mfma_f32_16x16x32_bf16 v[56:59], v[168:171], v[192:195], v[56:59]
	v_mfma_f32_16x16x32_bf16 v[56:59], v[164:167], v[188:191], v[56:59]
	v_mfma_f32_16x16x32_bf16 v[52:55], v[172:175], v[188:191], v[52:55]
	v_mfma_f32_16x16x32_bf16 v[52:55], v[176:179], v[192:195], v[52:55]
	v_mfma_f32_16x16x32_bf16 v[48:51], v[184:187], v[192:195], v[48:51]
	v_mfma_f32_16x16x32_bf16 v[48:51], v[180:183], v[188:191], v[48:51]
	v_mfma_f32_16x16x32_bf16 v[32:35], v[180:183], v[196:199], v[32:35]
	v_mfma_f32_16x16x32_bf16 v[32:35], v[184:187], v[200:203], v[32:35]
	v_mfma_f32_16x16x32_bf16 v[36:39], v[176:179], v[200:203], v[36:39]
	v_mfma_f32_16x16x32_bf16 v[36:39], v[172:175], v[196:199], v[36:39]
	v_mfma_f32_16x16x32_bf16 v[40:43], v[164:167], v[196:199], v[40:43]
	v_mfma_f32_16x16x32_bf16 v[40:43], v[168:171], v[200:203], v[40:43]
	v_mfma_f32_16x16x32_bf16 v[44:47], v[148:151], v[200:203], v[44:47]
	v_mfma_f32_16x16x32_bf16 v[44:47], v[144:147], v[196:199], v[44:47]
	v_mfma_f32_16x16x32_bf16 v[28:31], v[144:147], v[204:207], v[28:31]
	v_mfma_f32_16x16x32_bf16 v[28:31], v[148:151], v[208:211], v[28:31]
	v_mfma_f32_16x16x32_bf16 v[24:27], v[168:171], v[208:211], v[24:27]
	v_mfma_f32_16x16x32_bf16 v[24:27], v[164:167], v[204:207], v[24:27]
	v_mfma_f32_16x16x32_bf16 v[20:23], v[172:175], v[204:207], v[20:23]
	v_mfma_f32_16x16x32_bf16 v[20:23], v[176:179], v[208:211], v[20:23]
	v_mfma_f32_16x16x32_bf16 v[16:19], v[184:187], v[208:211], v[16:19]
	v_mfma_f32_16x16x32_bf16 v[16:19], v[180:183], v[204:207], v[16:19]
	v_mfma_f32_16x16x32_bf16 v[0:3], v[180:183], v[212:215], v[0:3]
	v_mfma_f32_16x16x32_bf16 v[0:3], v[184:187], v[216:219], v[0:3]
	v_mfma_f32_16x16x32_bf16 v[4:7], v[176:179], v[216:219], v[4:7]
	v_mfma_f32_16x16x32_bf16 v[4:7], v[172:175], v[212:215], v[4:7]
	v_mfma_f32_16x16x32_bf16 v[8:11], v[164:167], v[212:215], v[8:11]
	v_mfma_f32_16x16x32_bf16 v[8:11], v[168:171], v[216:219], v[8:11]
	v_mfma_f32_16x16x32_bf16 v[12:15], v[148:151], v[216:219], v[12:15]
	v_mfma_f32_16x16x32_bf16 v[12:15], v[144:147], v[212:215], v[12:15]
	s_setprio 0
	s_barrier
	s_add_i32 s65, 0, 0x18000
	s_add_i32 s66, 0, 0x1c000
	v_add_u32_e32 v168, s65, v155
	v_add_u32_e32 v184, s66, v155
	ds_read_b128 v[144:147], v168
	ds_read_b128 v[148:151], v168 offset:1024
	ds_read_b128 v[164:167], v168 offset:2048
	ds_read_b128 v[168:171], v168 offset:3072
	ds_read_b128 v[172:175], v184
	ds_read_b128 v[176:179], v184 offset:1024
	ds_read_b128 v[180:183], v184 offset:2048
	ds_read_b128 v[184:187], v184 offset:3072
	s_add_u32 s34, s34, s8
	s_addc_u32 s35, s35, s9
	s_mov_b32 m0, s43
	v_lshl_add_u64 v[230:231], s[34:35], 0, v[128:129]
	ds_read_b128 v[188:191], v159 offset:32768
	ds_read_b128 v[192:195], v159 offset:33792
	ds_read_b128 v[196:199], v159 offset:34816
	ds_read_b128 v[200:203], v159 offset:35840
	ds_read_b128 v[204:207], v159 offset:36864
	ds_read_b128 v[208:211], v159 offset:37888
	ds_read_b128 v[212:215], v159 offset:38912
	ds_read_b128 v[216:219], v159 offset:39936
	global_load_lds_dwordx4 v[230:231], off
	v_lshl_add_u64 v[230:231], s[34:35], 0, v[132:133]
	s_mov_b32 m0, s44
	s_nop 0
	global_load_lds_dwordx4 v[230:231], off
	s_waitcnt vmcnt(8)
	s_waitcnt lgkmcnt(0)
	s_barrier
	s_setprio 1
	v_mfma_f32_16x16x32_bf16 v[120:123], v[144:147], v[188:191], v[120:123]
	v_mfma_f32_16x16x32_bf16 v[120:123], v[148:151], v[192:195], v[120:123]
	v_mfma_f32_16x16x32_bf16 v[124:127], v[168:171], v[192:195], v[124:127]
	v_mfma_f32_16x16x32_bf16 v[124:127], v[164:167], v[188:191], v[124:127]
	v_mfma_f32_16x16x32_bf16 v[116:119], v[172:175], v[188:191], v[116:119]
	v_mfma_f32_16x16x32_bf16 v[116:119], v[176:179], v[192:195], v[116:119]
	v_mfma_f32_16x16x32_bf16 v[112:115], v[184:187], v[192:195], v[112:115]
	v_mfma_f32_16x16x32_bf16 v[112:115], v[180:183], v[188:191], v[112:115]
	v_mfma_f32_16x16x32_bf16 v[96:99], v[180:183], v[196:199], v[96:99]
	v_mfma_f32_16x16x32_bf16 v[96:99], v[184:187], v[200:203], v[96:99]
	v_mfma_f32_16x16x32_bf16 v[100:103], v[176:179], v[200:203], v[100:103]
	v_mfma_f32_16x16x32_bf16 v[100:103], v[172:175], v[196:199], v[100:103]
	v_mfma_f32_16x16x32_bf16 v[104:107], v[164:167], v[196:199], v[104:107]
	v_mfma_f32_16x16x32_bf16 v[104:107], v[168:171], v[200:203], v[104:107]
	v_mfma_f32_16x16x32_bf16 v[108:111], v[148:151], v[200:203], v[108:111]
	v_mfma_f32_16x16x32_bf16 v[108:111], v[144:147], v[196:199], v[108:111]
	v_mfma_f32_16x16x32_bf16 v[92:95], v[144:147], v[204:207], v[92:95]
	v_mfma_f32_16x16x32_bf16 v[92:95], v[148:151], v[208:211], v[92:95]
	v_mfma_f32_16x16x32_bf16 v[88:91], v[168:171], v[208:211], v[88:91]
	v_mfma_f32_16x16x32_bf16 v[88:91], v[164:167], v[204:207], v[88:91]
	v_mfma_f32_16x16x32_bf16 v[84:87], v[172:175], v[204:207], v[84:87]
	v_mfma_f32_16x16x32_bf16 v[84:87], v[176:179], v[208:211], v[84:87]
	v_mfma_f32_16x16x32_bf16 v[80:83], v[184:187], v[208:211], v[80:83]
	v_mfma_f32_16x16x32_bf16 v[80:83], v[180:183], v[204:207], v[80:83]
	v_mfma_f32_16x16x32_bf16 v[64:67], v[180:183], v[212:215], v[64:67]
	v_mfma_f32_16x16x32_bf16 v[64:67], v[184:187], v[216:219], v[64:67]
	v_mfma_f32_16x16x32_bf16 v[68:71], v[176:179], v[216:219], v[68:71]
	v_mfma_f32_16x16x32_bf16 v[68:71], v[172:175], v[212:215], v[68:71]
	v_mfma_f32_16x16x32_bf16 v[72:75], v[164:167], v[212:215], v[72:75]
	v_mfma_f32_16x16x32_bf16 v[72:75], v[168:171], v[216:219], v[72:75]
	v_mfma_f32_16x16x32_bf16 v[76:79], v[148:151], v[216:219], v[76:79]
	v_mfma_f32_16x16x32_bf16 v[76:79], v[144:147], v[212:215], v[76:79]
	s_setprio 0
	s_barrier
	s_add_i32 s34, s65, s40
	v_lshl_add_u64 v[152:153], v[152:153], 0, s[14:15]
	s_mov_b32 m0, s34
	ds_read_b128 v[188:191], v159 offset:49152
	ds_read_b128 v[192:195], v159 offset:50176
	ds_read_b128 v[196:199], v159 offset:51200
	ds_read_b128 v[200:203], v159 offset:52224
	ds_read_b128 v[204:207], v159 offset:53248
	ds_read_b128 v[208:211], v159 offset:54272
	ds_read_b128 v[212:215], v159 offset:55296
	ds_read_b128 v[216:219], v159 offset:56320
	global_load_lds_dwordx4 v[152:153], off
	v_lshl_add_u64 v[152:153], v[160:161], 0, s[14:15]
	s_add_i32 m0, s34, 0x2000
	s_add_i32 s34, s66, s40
	global_load_lds_dwordx4 v[152:153], off
	v_lshl_add_u64 v[152:153], v[222:223], 0, s[14:15]
	s_mov_b32 m0, s34
	s_nop 0
	global_load_lds_dwordx4 v[152:153], off
	v_lshl_add_u64 v[152:153], v[224:225], 0, s[14:15]
	s_add_i32 m0, s34, 0x2000
	s_nop 0
	global_load_lds_dwordx4 v[152:153], off
	v_lshl_add_u64 v[152:153], v[226:227], 0, s[14:15]
	s_mov_b32 m0, s46
	s_nop 0
	global_load_lds_dwordx4 v[152:153], off
	v_lshl_add_u64 v[152:153], v[228:229], 0, s[14:15]
	s_mov_b32 m0, s47
	s_nop 0
	global_load_lds_dwordx4 v[152:153], off
	s_waitcnt vmcnt(8)
	s_waitcnt lgkmcnt(0)
	s_barrier
	s_setprio 1
	v_mfma_f32_16x16x32_bf16 v[60:63], v[144:147], v[188:191], v[60:63]
	v_mfma_f32_16x16x32_bf16 v[60:63], v[148:151], v[192:195], v[60:63]
	v_mfma_f32_16x16x32_bf16 v[56:59], v[168:171], v[192:195], v[56:59]
	v_mfma_f32_16x16x32_bf16 v[56:59], v[164:167], v[188:191], v[56:59]
	v_mfma_f32_16x16x32_bf16 v[52:55], v[172:175], v[188:191], v[52:55]
	v_mfma_f32_16x16x32_bf16 v[52:55], v[176:179], v[192:195], v[52:55]
	v_mfma_f32_16x16x32_bf16 v[48:51], v[184:187], v[192:195], v[48:51]
	v_mfma_f32_16x16x32_bf16 v[48:51], v[180:183], v[188:191], v[48:51]
	v_mfma_f32_16x16x32_bf16 v[32:35], v[180:183], v[196:199], v[32:35]
	v_mfma_f32_16x16x32_bf16 v[32:35], v[184:187], v[200:203], v[32:35]
	v_mfma_f32_16x16x32_bf16 v[36:39], v[176:179], v[200:203], v[36:39]
	v_mfma_f32_16x16x32_bf16 v[36:39], v[172:175], v[196:199], v[36:39]
	v_mfma_f32_16x16x32_bf16 v[40:43], v[164:167], v[196:199], v[40:43]
	v_mfma_f32_16x16x32_bf16 v[40:43], v[168:171], v[200:203], v[40:43]
	v_mfma_f32_16x16x32_bf16 v[44:47], v[148:151], v[200:203], v[44:47]
	v_mfma_f32_16x16x32_bf16 v[44:47], v[144:147], v[196:199], v[44:47]
	v_mfma_f32_16x16x32_bf16 v[28:31], v[144:147], v[204:207], v[28:31]
	v_mfma_f32_16x16x32_bf16 v[28:31], v[148:151], v[208:211], v[28:31]
	v_mfma_f32_16x16x32_bf16 v[24:27], v[168:171], v[208:211], v[24:27]
	v_mfma_f32_16x16x32_bf16 v[24:27], v[164:167], v[204:207], v[24:27]
	v_mfma_f32_16x16x32_bf16 v[20:23], v[172:175], v[204:207], v[20:23]
	v_mfma_f32_16x16x32_bf16 v[20:23], v[176:179], v[208:211], v[20:23]
	v_mfma_f32_16x16x32_bf16 v[16:19], v[184:187], v[208:211], v[16:19]
	v_mfma_f32_16x16x32_bf16 v[16:19], v[180:183], v[204:207], v[16:19]
	v_mfma_f32_16x16x32_bf16 v[0:3], v[180:183], v[212:215], v[0:3]
	v_mfma_f32_16x16x32_bf16 v[0:3], v[184:187], v[216:219], v[0:3]
	v_mfma_f32_16x16x32_bf16 v[4:7], v[176:179], v[216:219], v[4:7]
	v_mfma_f32_16x16x32_bf16 v[4:7], v[172:175], v[212:215], v[4:7]
	v_mfma_f32_16x16x32_bf16 v[8:11], v[164:167], v[212:215], v[8:11]
	v_mfma_f32_16x16x32_bf16 v[8:11], v[168:171], v[216:219], v[8:11]
	v_mfma_f32_16x16x32_bf16 v[12:15], v[148:151], v[216:219], v[12:15]
	v_mfma_f32_16x16x32_bf16 v[12:15], v[144:147], v[212:215], v[12:15]
	s_setprio 0
	s_barrier
	s_add_u32 s30, s30, 0x100
	s_addc_u32 s31, s31, 0
	s_add_u32 s62, s62, 0x100
	s_addc_u32 s63, s63, 0
	s_cmp_ge_i32 s64, s48
	s_mov_b32 s34, s64
	s_cbranch_scc0 .LBB0_592

.LBB0_763:
	ds_read_b128 v[128:131], v181
	ds_read_b128 v[132:135], v181 offset:1024
	ds_read_b128 v[136:139], v181 offset:2048
	ds_read_b128 v[140:143], v181 offset:3072
	ds_read_b128 v[144:147], v182
	ds_read_b128 v[148:151], v182 offset:1024
	ds_read_b128 v[168:171], v182 offset:2048
	ds_read_b128 v[172:175], v182 offset:3072
	s_add_i32 s54, s26, 2
	s_add_u32 s55, s24, 0x80
	s_addc_u32 s27, s25, 0
	s_cmp_eq_u32 s43, s26
	s_cselect_b32 s26, s2, s55
	s_cselect_b32 s27, s3, s27
	s_cselect_b32 s61, s23, s53
	s_cselect_b32 s60, s22, s52
	v_lshl_add_u64 v[176:177], s[24:25], 0, v[160:161]
	s_add_i32 m0, s35, 0xc000
	ds_read_b128 v[184:187], v183
	ds_read_b128 v[188:191], v183 offset:1024
	ds_read_b128 v[192:195], v183 offset:2048
	ds_read_b128 v[196:199], v183 offset:3072
	ds_read_b128 v[200:203], v183 offset:4096
	ds_read_b128 v[204:207], v183 offset:5120
	ds_read_b128 v[208:211], v183 offset:6144
	ds_read_b128 v[212:215], v183 offset:7168
	global_load_lds_dwordx4 v[176:177], off
	v_lshl_add_u64 v[176:177], s[24:25], 0, v[162:163]
	s_add_i32 m0, s35, 0xe000
	s_nop 0
	global_load_lds_dwordx4 v[176:177], off
	s_waitcnt vmcnt(8)
	s_waitcnt lgkmcnt(0)
	s_barrier
	s_setprio 1
	v_mfma_f32_16x16x32_bf16 v[120:123], v[128:131], v[184:187], v[120:123]
	v_mfma_f32_16x16x32_bf16 v[120:123], v[132:135], v[188:191], v[120:123]
	v_mfma_f32_16x16x32_bf16 v[124:127], v[140:143], v[188:191], v[124:127]
	v_mfma_f32_16x16x32_bf16 v[124:127], v[136:139], v[184:187], v[124:127]
	v_mfma_f32_16x16x32_bf16 v[116:119], v[144:147], v[184:187], v[116:119]
	v_mfma_f32_16x16x32_bf16 v[116:119], v[148:151], v[188:191], v[116:119]
	v_mfma_f32_16x16x32_bf16 v[112:115], v[172:175], v[188:191], v[112:115]
	v_mfma_f32_16x16x32_bf16 v[112:115], v[168:171], v[184:187], v[112:115]
	v_mfma_f32_16x16x32_bf16 v[96:99], v[168:171], v[192:195], v[96:99]
	v_mfma_f32_16x16x32_bf16 v[96:99], v[172:175], v[196:199], v[96:99]
	v_mfma_f32_16x16x32_bf16 v[100:103], v[148:151], v[196:199], v[100:103]
	v_mfma_f32_16x16x32_bf16 v[100:103], v[144:147], v[192:195], v[100:103]
	v_mfma_f32_16x16x32_bf16 v[104:107], v[136:139], v[192:195], v[104:107]
	v_mfma_f32_16x16x32_bf16 v[104:107], v[140:143], v[196:199], v[104:107]
	v_mfma_f32_16x16x32_bf16 v[108:111], v[132:135], v[196:199], v[108:111]
	v_mfma_f32_16x16x32_bf16 v[108:111], v[128:131], v[192:195], v[108:111]
	v_mfma_f32_16x16x32_bf16 v[92:95], v[128:131], v[200:203], v[92:95]
	v_mfma_f32_16x16x32_bf16 v[92:95], v[132:135], v[204:207], v[92:95]
	v_mfma_f32_16x16x32_bf16 v[88:91], v[140:143], v[204:207], v[88:91]
	v_mfma_f32_16x16x32_bf16 v[88:91], v[136:139], v[200:203], v[88:91]
	v_mfma_f32_16x16x32_bf16 v[84:87], v[144:147], v[200:203], v[84:87]
	v_mfma_f32_16x16x32_bf16 v[84:87], v[148:151], v[204:207], v[84:87]
	v_mfma_f32_16x16x32_bf16 v[80:83], v[172:175], v[204:207], v[80:83]
	v_mfma_f32_16x16x32_bf16 v[80:83], v[168:171], v[200:203], v[80:83]
	v_mfma_f32_16x16x32_bf16 v[64:67], v[168:171], v[208:211], v[64:67]
	v_mfma_f32_16x16x32_bf16 v[64:67], v[172:175], v[212:215], v[64:67]
	v_mfma_f32_16x16x32_bf16 v[68:71], v[148:151], v[212:215], v[68:71]
	v_mfma_f32_16x16x32_bf16 v[68:71], v[144:147], v[208:211], v[68:71]
	v_mfma_f32_16x16x32_bf16 v[72:75], v[136:139], v[208:211], v[72:75]
	v_mfma_f32_16x16x32_bf16 v[72:75], v[140:143], v[212:215], v[72:75]
	v_mfma_f32_16x16x32_bf16 v[76:79], v[132:135], v[212:215], v[76:79]
	v_mfma_f32_16x16x32_bf16 v[76:79], v[128:131], v[208:211], v[76:79]
	s_setprio 0
	s_barrier
	s_add_i32 s55, s46, s34
	v_lshl_add_u64 v[176:177], s[60:61], 0, v[154:155]
	s_mov_b32 m0, s55
	ds_read_b128 v[184:187], v183 offset:16384
	ds_read_b128 v[188:191], v183 offset:17408
	ds_read_b128 v[192:195], v183 offset:18432
	ds_read_b128 v[196:199], v183 offset:19456
	ds_read_b128 v[200:203], v183 offset:20480
	ds_read_b128 v[204:207], v183 offset:21504
	ds_read_b128 v[208:211], v183 offset:22528
	ds_read_b128 v[212:215], v183 offset:23552
	global_load_lds_dwordx4 v[176:177], off
	s_add_i32 m0, s55, 0x2000
	v_lshl_add_u64 v[216:217], s[60:61], 0, v[158:159]
	s_add_u32 s60, s60, s8
	s_addc_u32 s61, s61, s9
	s_add_i32 s55, s47, s34
	global_load_lds_dwordx4 v[216:217], off
	v_lshl_add_u64 v[218:219], s[60:61], 0, v[154:155]
	s_mov_b32 m0, s55
	v_lshl_add_u64 v[222:223], s[60:61], 0, v[158:159]
	global_load_lds_dwordx4 v[218:219], off
	s_add_i32 m0, s55, 0x2000
	v_lshl_add_u64 v[224:225], s[26:27], 0, v[152:153]
	global_load_lds_dwordx4 v[222:223], off
	s_mov_b32 m0, s35
	v_lshl_add_u64 v[226:227], s[26:27], 0, v[156:157]
	global_load_lds_dwordx4 v[224:225], off
	s_mov_b32 m0, s36
	s_nop 0
	global_load_lds_dwordx4 v[226:227], off
	s_waitcnt vmcnt(8)
	s_waitcnt lgkmcnt(0)
	s_barrier
	s_setprio 1
	v_mfma_f32_16x16x32_bf16 v[60:63], v[128:131], v[184:187], v[60:63]
	v_mfma_f32_16x16x32_bf16 v[60:63], v[132:135], v[188:191], v[60:63]
	v_mfma_f32_16x16x32_bf16 v[56:59], v[140:143], v[188:191], v[56:59]
	v_mfma_f32_16x16x32_bf16 v[56:59], v[136:139], v[184:187], v[56:59]
	v_mfma_f32_16x16x32_bf16 v[52:55], v[144:147], v[184:187], v[52:55]
	v_mfma_f32_16x16x32_bf16 v[52:55], v[148:151], v[188:191], v[52:55]
	v_mfma_f32_16x16x32_bf16 v[48:51], v[172:175], v[188:191], v[48:51]
	v_mfma_f32_16x16x32_bf16 v[48:51], v[168:171], v[184:187], v[48:51]
	v_mfma_f32_16x16x32_bf16 v[32:35], v[168:171], v[192:195], v[32:35]
	v_mfma_f32_16x16x32_bf16 v[32:35], v[172:175], v[196:199], v[32:35]
	v_mfma_f32_16x16x32_bf16 v[36:39], v[148:151], v[196:199], v[36:39]
	v_mfma_f32_16x16x32_bf16 v[36:39], v[144:147], v[192:195], v[36:39]
	v_mfma_f32_16x16x32_bf16 v[40:43], v[136:139], v[192:195], v[40:43]
	v_mfma_f32_16x16x32_bf16 v[40:43], v[140:143], v[196:199], v[40:43]
	v_mfma_f32_16x16x32_bf16 v[44:47], v[132:135], v[196:199], v[44:47]
	v_mfma_f32_16x16x32_bf16 v[44:47], v[128:131], v[192:195], v[44:47]
	v_mfma_f32_16x16x32_bf16 v[28:31], v[128:131], v[200:203], v[28:31]
	v_mfma_f32_16x16x32_bf16 v[28:31], v[132:135], v[204:207], v[28:31]
	v_mfma_f32_16x16x32_bf16 v[24:27], v[140:143], v[204:207], v[24:27]
	v_mfma_f32_16x16x32_bf16 v[24:27], v[136:139], v[200:203], v[24:27]
	v_mfma_f32_16x16x32_bf16 v[20:23], v[144:147], v[200:203], v[20:23]
	v_mfma_f32_16x16x32_bf16 v[20:23], v[148:151], v[204:207], v[20:23]
	v_mfma_f32_16x16x32_bf16 v[16:19], v[172:175], v[204:207], v[16:19]
	v_mfma_f32_16x16x32_bf16 v[16:19], v[168:171], v[200:203], v[16:19]
	v_mfma_f32_16x16x32_bf16 v[0:3], v[168:171], v[208:211], v[0:3]
	v_mfma_f32_16x16x32_bf16 v[0:3], v[172:175], v[212:215], v[0:3]
	v_mfma_f32_16x16x32_bf16 v[4:7], v[148:151], v[212:215], v[4:7]
	v_mfma_f32_16x16x32_bf16 v[4:7], v[144:147], v[208:211], v[4:7]
	v_mfma_f32_16x16x32_bf16 v[8:11], v[136:139], v[208:211], v[8:11]
	v_mfma_f32_16x16x32_bf16 v[8:11], v[140:143], v[212:215], v[8:11]
	v_mfma_f32_16x16x32_bf16 v[12:15], v[132:135], v[212:215], v[12:15]
	v_mfma_f32_16x16x32_bf16 v[12:15], v[128:131], v[208:211], v[12:15]
	s_setprio 0
	s_barrier
	s_add_i32 s55, 0, 0x18000
	s_add_i32 s60, 0, 0x1c000
	v_add_u32_e32 v140, s55, v179
	v_add_u32_e32 v172, s60, v179
	ds_read_b128 v[128:131], v140
	ds_read_b128 v[132:135], v140 offset:1024
	ds_read_b128 v[136:139], v140 offset:2048
	ds_read_b128 v[140:143], v140 offset:3072
	ds_read_b128 v[144:147], v172
	ds_read_b128 v[148:151], v172 offset:1024
	ds_read_b128 v[168:171], v172 offset:2048
	ds_read_b128 v[172:175], v172 offset:3072
	s_add_u32 s26, s26, s8
	s_addc_u32 s27, s27, s9
	s_mov_b32 m0, s37
	v_lshl_add_u64 v[228:229], s[26:27], 0, v[152:153]
	ds_read_b128 v[184:187], v183 offset:32768
	ds_read_b128 v[188:191], v183 offset:33792
	ds_read_b128 v[192:195], v183 offset:34816
	ds_read_b128 v[196:199], v183 offset:35840
	ds_read_b128 v[200:203], v183 offset:36864
	ds_read_b128 v[204:207], v183 offset:37888
	ds_read_b128 v[208:211], v183 offset:38912
	ds_read_b128 v[212:215], v183 offset:39936
	global_load_lds_dwordx4 v[228:229], off
	v_lshl_add_u64 v[228:229], s[26:27], 0, v[156:157]
	s_mov_b32 m0, s38
	s_nop 0
	global_load_lds_dwordx4 v[228:229], off
	s_waitcnt vmcnt(8)
	s_waitcnt lgkmcnt(0)
	s_barrier
	s_setprio 1
	v_mfma_f32_16x16x32_bf16 v[120:123], v[128:131], v[184:187], v[120:123]
	v_mfma_f32_16x16x32_bf16 v[120:123], v[132:135], v[188:191], v[120:123]
	v_mfma_f32_16x16x32_bf16 v[124:127], v[140:143], v[188:191], v[124:127]
	v_mfma_f32_16x16x32_bf16 v[124:127], v[136:139], v[184:187], v[124:127]
	v_mfma_f32_16x16x32_bf16 v[116:119], v[144:147], v[184:187], v[116:119]
	v_mfma_f32_16x16x32_bf16 v[116:119], v[148:151], v[188:191], v[116:119]
	v_mfma_f32_16x16x32_bf16 v[112:115], v[172:175], v[188:191], v[112:115]
	v_mfma_f32_16x16x32_bf16 v[112:115], v[168:171], v[184:187], v[112:115]
	v_mfma_f32_16x16x32_bf16 v[96:99], v[168:171], v[192:195], v[96:99]
	v_mfma_f32_16x16x32_bf16 v[96:99], v[172:175], v[196:199], v[96:99]
	v_mfma_f32_16x16x32_bf16 v[100:103], v[148:151], v[196:199], v[100:103]
	v_mfma_f32_16x16x32_bf16 v[100:103], v[144:147], v[192:195], v[100:103]
	v_mfma_f32_16x16x32_bf16 v[104:107], v[136:139], v[192:195], v[104:107]
	v_mfma_f32_16x16x32_bf16 v[104:107], v[140:143], v[196:199], v[104:107]
	v_mfma_f32_16x16x32_bf16 v[108:111], v[132:135], v[196:199], v[108:111]
	v_mfma_f32_16x16x32_bf16 v[108:111], v[128:131], v[192:195], v[108:111]
	v_mfma_f32_16x16x32_bf16 v[92:95], v[128:131], v[200:203], v[92:95]
	v_mfma_f32_16x16x32_bf16 v[92:95], v[132:135], v[204:207], v[92:95]
	v_mfma_f32_16x16x32_bf16 v[88:91], v[140:143], v[204:207], v[88:91]
	v_mfma_f32_16x16x32_bf16 v[88:91], v[136:139], v[200:203], v[88:91]
	v_mfma_f32_16x16x32_bf16 v[84:87], v[144:147], v[200:203], v[84:87]
	v_mfma_f32_16x16x32_bf16 v[84:87], v[148:151], v[204:207], v[84:87]
	v_mfma_f32_16x16x32_bf16 v[80:83], v[172:175], v[204:207], v[80:83]
	v_mfma_f32_16x16x32_bf16 v[80:83], v[168:171], v[200:203], v[80:83]
	v_mfma_f32_16x16x32_bf16 v[64:67], v[168:171], v[208:211], v[64:67]
	v_mfma_f32_16x16x32_bf16 v[64:67], v[172:175], v[212:215], v[64:67]
	v_mfma_f32_16x16x32_bf16 v[68:71], v[148:151], v[212:215], v[68:71]
	v_mfma_f32_16x16x32_bf16 v[68:71], v[144:147], v[208:211], v[68:71]
	v_mfma_f32_16x16x32_bf16 v[72:75], v[136:139], v[208:211], v[72:75]
	v_mfma_f32_16x16x32_bf16 v[72:75], v[140:143], v[212:215], v[72:75]
	v_mfma_f32_16x16x32_bf16 v[76:79], v[132:135], v[212:215], v[76:79]
	v_mfma_f32_16x16x32_bf16 v[76:79], v[128:131], v[208:211], v[76:79]
	s_setprio 0
	s_barrier
	s_add_i32 s26, s55, s34
	v_lshl_add_u64 v[176:177], v[176:177], 0, s[16:17]
	s_mov_b32 m0, s26
	ds_read_b128 v[184:187], v183 offset:49152
	ds_read_b128 v[188:191], v183 offset:50176
	ds_read_b128 v[192:195], v183 offset:51200
	ds_read_b128 v[196:199], v183 offset:52224
	ds_read_b128 v[200:203], v183 offset:53248
	ds_read_b128 v[204:207], v183 offset:54272
	ds_read_b128 v[208:211], v183 offset:55296
	ds_read_b128 v[212:215], v183 offset:56320
	global_load_lds_dwordx4 v[176:177], off
	v_lshl_add_u64 v[176:177], v[216:217], 0, s[16:17]
	s_add_i32 m0, s26, 0x2000
	s_add_i32 s26, s60, s34
	global_load_lds_dwordx4 v[176:177], off
	v_lshl_add_u64 v[176:177], v[218:219], 0, s[16:17]
	s_mov_b32 m0, s26
	s_nop 0
	global_load_lds_dwordx4 v[176:177], off
	v_lshl_add_u64 v[176:177], v[222:223], 0, s[16:17]
	s_add_i32 m0, s26, 0x2000
	s_nop 0
	global_load_lds_dwordx4 v[176:177], off
	v_lshl_add_u64 v[176:177], v[224:225], 0, s[16:17]
	s_mov_b32 m0, s40
	s_nop 0
	global_load_lds_dwordx4 v[176:177], off
	v_lshl_add_u64 v[176:177], v[226:227], 0, s[16:17]
	s_mov_b32 m0, s41
	s_nop 0
	global_load_lds_dwordx4 v[176:177], off
	s_waitcnt vmcnt(8)
	s_waitcnt lgkmcnt(0)
	s_barrier
	s_setprio 1
	v_mfma_f32_16x16x32_bf16 v[60:63], v[128:131], v[184:187], v[60:63]
	v_mfma_f32_16x16x32_bf16 v[60:63], v[132:135], v[188:191], v[60:63]
	v_mfma_f32_16x16x32_bf16 v[56:59], v[140:143], v[188:191], v[56:59]
	v_mfma_f32_16x16x32_bf16 v[56:59], v[136:139], v[184:187], v[56:59]
	v_mfma_f32_16x16x32_bf16 v[52:55], v[144:147], v[184:187], v[52:55]
	v_mfma_f32_16x16x32_bf16 v[52:55], v[148:151], v[188:191], v[52:55]
	v_mfma_f32_16x16x32_bf16 v[48:51], v[172:175], v[188:191], v[48:51]
	v_mfma_f32_16x16x32_bf16 v[48:51], v[168:171], v[184:187], v[48:51]
	v_mfma_f32_16x16x32_bf16 v[32:35], v[168:171], v[192:195], v[32:35]
	v_mfma_f32_16x16x32_bf16 v[32:35], v[172:175], v[196:199], v[32:35]
	v_mfma_f32_16x16x32_bf16 v[36:39], v[148:151], v[196:199], v[36:39]
	v_mfma_f32_16x16x32_bf16 v[36:39], v[144:147], v[192:195], v[36:39]
	v_mfma_f32_16x16x32_bf16 v[40:43], v[136:139], v[192:195], v[40:43]
	v_mfma_f32_16x16x32_bf16 v[40:43], v[140:143], v[196:199], v[40:43]
	v_mfma_f32_16x16x32_bf16 v[44:47], v[132:135], v[196:199], v[44:47]
	v_mfma_f32_16x16x32_bf16 v[44:47], v[128:131], v[192:195], v[44:47]
	v_mfma_f32_16x16x32_bf16 v[28:31], v[128:131], v[200:203], v[28:31]
	v_mfma_f32_16x16x32_bf16 v[28:31], v[132:135], v[204:207], v[28:31]
	v_mfma_f32_16x16x32_bf16 v[24:27], v[140:143], v[204:207], v[24:27]
	v_mfma_f32_16x16x32_bf16 v[24:27], v[136:139], v[200:203], v[24:27]
	v_mfma_f32_16x16x32_bf16 v[20:23], v[144:147], v[200:203], v[20:23]
	v_mfma_f32_16x16x32_bf16 v[20:23], v[148:151], v[204:207], v[20:23]
	v_mfma_f32_16x16x32_bf16 v[16:19], v[172:175], v[204:207], v[16:19]
	v_mfma_f32_16x16x32_bf16 v[16:19], v[168:171], v[200:203], v[16:19]
	v_mfma_f32_16x16x32_bf16 v[0:3], v[168:171], v[208:211], v[0:3]
	v_mfma_f32_16x16x32_bf16 v[0:3], v[172:175], v[212:215], v[0:3]
	v_mfma_f32_16x16x32_bf16 v[4:7], v[148:151], v[212:215], v[4:7]
	v_mfma_f32_16x16x32_bf16 v[4:7], v[144:147], v[208:211], v[4:7]
	v_mfma_f32_16x16x32_bf16 v[8:11], v[136:139], v[208:211], v[8:11]
	v_mfma_f32_16x16x32_bf16 v[8:11], v[140:143], v[212:215], v[8:11]
	v_mfma_f32_16x16x32_bf16 v[12:15], v[132:135], v[212:215], v[12:15]
	v_mfma_f32_16x16x32_bf16 v[12:15], v[128:131], v[208:211], v[12:15]
	s_setprio 0
	s_barrier
	s_add_u32 s24, s24, 0x100
	s_addc_u32 s25, s25, 0
	s_add_u32 s52, s52, 0x100
	s_addc_u32 s53, s53, 0
	s_cmp_ge_i32 s54, s42
	s_mov_b32 s26, s54
	s_cbranch_scc0 .LBB0_763

.LBB0_849:
	ds_read_b128 v[112:115], v209
	ds_read_b128 v[116:119], v209 offset:1024
	ds_read_b128 v[120:123], v209 offset:2048
	ds_read_b128 v[128:131], v209 offset:3072
	ds_read_b128 v[144:147], v210
	ds_read_b128 v[148:151], v210 offset:1024
	ds_read_b128 v[152:155], v210 offset:2048
	ds_read_b128 v[156:159], v210 offset:3072
	s_add_i32 s62, s30, 2
	s_add_u32 s63, s28, 0x80
	s_addc_u32 s31, s29, 0
	s_cmp_eq_u32 s46, s30
	s_cselect_b32 s30, s4, s63
	s_cselect_b32 s31, s5, s31
	s_cselect_b32 s65, s27, s61
	s_cselect_b32 s64, s26, s60
	v_lshl_add_u64 v[204:205], s[28:29], 0, v[180:181]
	s_add_i32 m0, s38, 0xc000
	ds_read_b128 v[160:163], v211
	ds_read_b128 v[164:167], v211 offset:1024
	ds_read_b128 v[168:171], v211 offset:2048
	ds_read_b128 v[172:175], v211 offset:3072
	ds_read_b128 v[188:191], v211 offset:4096
	ds_read_b128 v[192:195], v211 offset:5120
	ds_read_b128 v[196:199], v211 offset:6144
	ds_read_b128 v[200:203], v211 offset:7168
	global_load_lds_dwordx4 v[204:205], off
	v_lshl_add_u64 v[204:205], s[28:29], 0, v[182:183]
	s_add_i32 m0, s38, 0xe000
	s_nop 0
	global_load_lds_dwordx4 v[204:205], off
	s_waitcnt vmcnt(8)
	s_waitcnt lgkmcnt(0)
	s_barrier
	s_setprio 1
	v_mfma_f32_16x16x32_bf16 v[136:139], v[112:115], v[160:163], v[136:139]
	v_mfma_f32_16x16x32_bf16 v[136:139], v[116:119], v[164:167], v[136:139]
	v_mfma_f32_16x16x32_bf16 v[140:143], v[128:131], v[164:167], v[140:143]
	v_mfma_f32_16x16x32_bf16 v[140:143], v[120:123], v[160:163], v[140:143]
	v_mfma_f32_16x16x32_bf16 v[132:135], v[144:147], v[160:163], v[132:135]
	v_mfma_f32_16x16x32_bf16 v[132:135], v[148:151], v[164:167], v[132:135]
	v_mfma_f32_16x16x32_bf16 v[124:127], v[156:159], v[164:167], v[124:127]
	v_mfma_f32_16x16x32_bf16 v[124:127], v[152:155], v[160:163], v[124:127]
	v_mfma_f32_16x16x32_bf16 v[96:99], v[152:155], v[168:171], v[96:99]
	v_mfma_f32_16x16x32_bf16 v[96:99], v[156:159], v[172:175], v[96:99]
	v_mfma_f32_16x16x32_bf16 v[100:103], v[148:151], v[172:175], v[100:103]
	v_mfma_f32_16x16x32_bf16 v[100:103], v[144:147], v[168:171], v[100:103]
	v_mfma_f32_16x16x32_bf16 v[104:107], v[120:123], v[168:171], v[104:107]
	v_mfma_f32_16x16x32_bf16 v[104:107], v[128:131], v[172:175], v[104:107]
	v_mfma_f32_16x16x32_bf16 v[108:111], v[116:119], v[172:175], v[108:111]
	v_mfma_f32_16x16x32_bf16 v[108:111], v[112:115], v[168:171], v[108:111]
	v_mfma_f32_16x16x32_bf16 v[92:95], v[112:115], v[188:191], v[92:95]
	v_mfma_f32_16x16x32_bf16 v[92:95], v[116:119], v[192:195], v[92:95]
	v_mfma_f32_16x16x32_bf16 v[88:91], v[128:131], v[192:195], v[88:91]
	v_mfma_f32_16x16x32_bf16 v[88:91], v[120:123], v[188:191], v[88:91]
	v_mfma_f32_16x16x32_bf16 v[84:87], v[144:147], v[188:191], v[84:87]
	v_mfma_f32_16x16x32_bf16 v[84:87], v[148:151], v[192:195], v[84:87]
	v_mfma_f32_16x16x32_bf16 v[80:83], v[156:159], v[192:195], v[80:83]
	v_mfma_f32_16x16x32_bf16 v[80:83], v[152:155], v[188:191], v[80:83]
	v_mfma_f32_16x16x32_bf16 v[64:67], v[152:155], v[196:199], v[64:67]
	v_mfma_f32_16x16x32_bf16 v[64:67], v[156:159], v[200:203], v[64:67]
	v_mfma_f32_16x16x32_bf16 v[68:71], v[148:151], v[200:203], v[68:71]
	v_mfma_f32_16x16x32_bf16 v[68:71], v[144:147], v[196:199], v[68:71]
	v_mfma_f32_16x16x32_bf16 v[72:75], v[120:123], v[196:199], v[72:75]
	v_mfma_f32_16x16x32_bf16 v[72:75], v[128:131], v[200:203], v[72:75]
	v_mfma_f32_16x16x32_bf16 v[76:79], v[116:119], v[200:203], v[76:79]
	v_mfma_f32_16x16x32_bf16 v[76:79], v[112:115], v[196:199], v[76:79]
	s_setprio 0
	s_barrier
	s_add_i32 s63, s50, s37
	v_lshl_add_u64 v[204:205], s[64:65], 0, v[176:177]
	s_mov_b32 m0, s63
	ds_read_b128 v[160:163], v211 offset:16384
	ds_read_b128 v[164:167], v211 offset:17408
	ds_read_b128 v[168:171], v211 offset:18432
	ds_read_b128 v[172:175], v211 offset:19456
	ds_read_b128 v[188:191], v211 offset:20480
	ds_read_b128 v[192:195], v211 offset:21504
	ds_read_b128 v[196:199], v211 offset:22528
	ds_read_b128 v[200:203], v211 offset:23552
	global_load_lds_dwordx4 v[204:205], off
	s_add_i32 m0, s63, 0x2000
	v_lshl_add_u64 v[214:215], s[64:65], 0, v[178:179]
	s_add_u32 s64, s64, s10
	s_addc_u32 s65, s65, s11
	s_add_i32 s63, s51, s37
	global_load_lds_dwordx4 v[214:215], off
	v_lshl_add_u64 v[216:217], s[64:65], 0, v[176:177]
	s_mov_b32 m0, s63
	v_lshl_add_u64 v[218:219], s[64:65], 0, v[178:179]
	global_load_lds_dwordx4 v[216:217], off
	s_add_i32 m0, s63, 0x2000
	v_lshl_add_u64 v[222:223], s[30:31], 0, v[176:177]
	global_load_lds_dwordx4 v[218:219], off
	s_mov_b32 m0, s38
	v_lshl_add_u64 v[224:225], s[30:31], 0, v[178:179]
	global_load_lds_dwordx4 v[222:223], off
	s_mov_b32 m0, s39
	s_nop 0
	global_load_lds_dwordx4 v[224:225], off
	s_waitcnt vmcnt(8)
	s_waitcnt lgkmcnt(0)
	s_barrier
	s_setprio 1
	v_mfma_f32_16x16x32_bf16 v[60:63], v[112:115], v[160:163], v[60:63]
	v_mfma_f32_16x16x32_bf16 v[60:63], v[116:119], v[164:167], v[60:63]
	v_mfma_f32_16x16x32_bf16 v[56:59], v[128:131], v[164:167], v[56:59]
	v_mfma_f32_16x16x32_bf16 v[56:59], v[120:123], v[160:163], v[56:59]
	v_mfma_f32_16x16x32_bf16 v[52:55], v[144:147], v[160:163], v[52:55]
	v_mfma_f32_16x16x32_bf16 v[52:55], v[148:151], v[164:167], v[52:55]
	v_mfma_f32_16x16x32_bf16 v[48:51], v[156:159], v[164:167], v[48:51]
	v_mfma_f32_16x16x32_bf16 v[48:51], v[152:155], v[160:163], v[48:51]
	v_mfma_f32_16x16x32_bf16 v[32:35], v[152:155], v[168:171], v[32:35]
	v_mfma_f32_16x16x32_bf16 v[32:35], v[156:159], v[172:175], v[32:35]
	v_mfma_f32_16x16x32_bf16 v[36:39], v[148:151], v[172:175], v[36:39]
	v_mfma_f32_16x16x32_bf16 v[36:39], v[144:147], v[168:171], v[36:39]
	v_mfma_f32_16x16x32_bf16 v[40:43], v[120:123], v[168:171], v[40:43]
	v_mfma_f32_16x16x32_bf16 v[40:43], v[128:131], v[172:175], v[40:43]
	v_mfma_f32_16x16x32_bf16 v[44:47], v[116:119], v[172:175], v[44:47]
	v_mfma_f32_16x16x32_bf16 v[44:47], v[112:115], v[168:171], v[44:47]
	v_mfma_f32_16x16x32_bf16 v[28:31], v[112:115], v[188:191], v[28:31]
	v_mfma_f32_16x16x32_bf16 v[28:31], v[116:119], v[192:195], v[28:31]
	v_mfma_f32_16x16x32_bf16 v[24:27], v[128:131], v[192:195], v[24:27]
	v_mfma_f32_16x16x32_bf16 v[24:27], v[120:123], v[188:191], v[24:27]
	v_mfma_f32_16x16x32_bf16 v[20:23], v[144:147], v[188:191], v[20:23]
	v_mfma_f32_16x16x32_bf16 v[20:23], v[148:151], v[192:195], v[20:23]
	v_mfma_f32_16x16x32_bf16 v[16:19], v[156:159], v[192:195], v[16:19]
	v_mfma_f32_16x16x32_bf16 v[16:19], v[152:155], v[188:191], v[16:19]
	v_mfma_f32_16x16x32_bf16 v[0:3], v[152:155], v[196:199], v[0:3]
	v_mfma_f32_16x16x32_bf16 v[0:3], v[156:159], v[200:203], v[0:3]
	v_mfma_f32_16x16x32_bf16 v[4:7], v[148:151], v[200:203], v[4:7]
	v_mfma_f32_16x16x32_bf16 v[4:7], v[144:147], v[196:199], v[4:7]
	v_mfma_f32_16x16x32_bf16 v[8:11], v[120:123], v[196:199], v[8:11]
	v_mfma_f32_16x16x32_bf16 v[8:11], v[128:131], v[200:203], v[8:11]
	v_mfma_f32_16x16x32_bf16 v[12:15], v[116:119], v[200:203], v[12:15]
	v_mfma_f32_16x16x32_bf16 v[12:15], v[112:115], v[196:199], v[12:15]
	s_setprio 0
	s_barrier
	s_add_i32 s63, 0, 0x18000
	s_add_i32 s64, 0, 0x1c000
	v_add_u32_e32 v128, s63, v207
	v_add_u32_e32 v156, s64, v207
	ds_read_b128 v[112:115], v128
	ds_read_b128 v[116:119], v128 offset:1024
	ds_read_b128 v[120:123], v128 offset:2048
	ds_read_b128 v[128:131], v128 offset:3072
	ds_read_b128 v[144:147], v156
	ds_read_b128 v[148:151], v156 offset:1024
	ds_read_b128 v[152:155], v156 offset:2048
	ds_read_b128 v[156:159], v156 offset:3072
	s_add_u32 s30, s30, s10
	s_addc_u32 s31, s31, s11
	s_mov_b32 m0, s40
	v_lshl_add_u64 v[226:227], s[30:31], 0, v[176:177]
	ds_read_b128 v[160:163], v211 offset:32768
	ds_read_b128 v[164:167], v211 offset:33792
	ds_read_b128 v[168:171], v211 offset:34816
	ds_read_b128 v[172:175], v211 offset:35840
	ds_read_b128 v[188:191], v211 offset:36864
	ds_read_b128 v[192:195], v211 offset:37888
	ds_read_b128 v[196:199], v211 offset:38912
	ds_read_b128 v[200:203], v211 offset:39936
	global_load_lds_dwordx4 v[226:227], off
	v_lshl_add_u64 v[226:227], s[30:31], 0, v[178:179]
	s_mov_b32 m0, s41
	s_nop 0
	global_load_lds_dwordx4 v[226:227], off
	s_waitcnt vmcnt(8)
	s_waitcnt lgkmcnt(0)
	s_barrier
	s_setprio 1
	v_mfma_f32_16x16x32_bf16 v[136:139], v[112:115], v[160:163], v[136:139]
	v_mfma_f32_16x16x32_bf16 v[136:139], v[116:119], v[164:167], v[136:139]
	v_mfma_f32_16x16x32_bf16 v[140:143], v[128:131], v[164:167], v[140:143]
	v_mfma_f32_16x16x32_bf16 v[140:143], v[120:123], v[160:163], v[140:143]
	v_mfma_f32_16x16x32_bf16 v[132:135], v[144:147], v[160:163], v[132:135]
	v_mfma_f32_16x16x32_bf16 v[132:135], v[148:151], v[164:167], v[132:135]
	v_mfma_f32_16x16x32_bf16 v[124:127], v[156:159], v[164:167], v[124:127]
	v_mfma_f32_16x16x32_bf16 v[124:127], v[152:155], v[160:163], v[124:127]
	v_mfma_f32_16x16x32_bf16 v[96:99], v[152:155], v[168:171], v[96:99]
	v_mfma_f32_16x16x32_bf16 v[96:99], v[156:159], v[172:175], v[96:99]
	v_mfma_f32_16x16x32_bf16 v[100:103], v[148:151], v[172:175], v[100:103]
	v_mfma_f32_16x16x32_bf16 v[100:103], v[144:147], v[168:171], v[100:103]
	v_mfma_f32_16x16x32_bf16 v[104:107], v[120:123], v[168:171], v[104:107]
	v_mfma_f32_16x16x32_bf16 v[104:107], v[128:131], v[172:175], v[104:107]
	v_mfma_f32_16x16x32_bf16 v[108:111], v[116:119], v[172:175], v[108:111]
	v_mfma_f32_16x16x32_bf16 v[108:111], v[112:115], v[168:171], v[108:111]
	v_mfma_f32_16x16x32_bf16 v[92:95], v[112:115], v[188:191], v[92:95]
	v_mfma_f32_16x16x32_bf16 v[92:95], v[116:119], v[192:195], v[92:95]
	v_mfma_f32_16x16x32_bf16 v[88:91], v[128:131], v[192:195], v[88:91]
	v_mfma_f32_16x16x32_bf16 v[88:91], v[120:123], v[188:191], v[88:91]
	v_mfma_f32_16x16x32_bf16 v[84:87], v[144:147], v[188:191], v[84:87]
	v_mfma_f32_16x16x32_bf16 v[84:87], v[148:151], v[192:195], v[84:87]
	v_mfma_f32_16x16x32_bf16 v[80:83], v[156:159], v[192:195], v[80:83]
	v_mfma_f32_16x16x32_bf16 v[80:83], v[152:155], v[188:191], v[80:83]
	v_mfma_f32_16x16x32_bf16 v[64:67], v[152:155], v[196:199], v[64:67]
	v_mfma_f32_16x16x32_bf16 v[64:67], v[156:159], v[200:203], v[64:67]
	v_mfma_f32_16x16x32_bf16 v[68:71], v[148:151], v[200:203], v[68:71]
	v_mfma_f32_16x16x32_bf16 v[68:71], v[144:147], v[196:199], v[68:71]
	v_mfma_f32_16x16x32_bf16 v[72:75], v[120:123], v[196:199], v[72:75]
	v_mfma_f32_16x16x32_bf16 v[72:75], v[128:131], v[200:203], v[72:75]
	v_mfma_f32_16x16x32_bf16 v[76:79], v[116:119], v[200:203], v[76:79]
	v_mfma_f32_16x16x32_bf16 v[76:79], v[112:115], v[196:199], v[76:79]
	s_setprio 0
	s_barrier
	s_add_i32 s30, s63, s37
	v_lshl_add_u64 v[204:205], v[204:205], 0, s[18:19]
	s_mov_b32 m0, s30
	ds_read_b128 v[160:163], v211 offset:49152
	ds_read_b128 v[164:167], v211 offset:50176
	ds_read_b128 v[168:171], v211 offset:51200
	ds_read_b128 v[172:175], v211 offset:52224
	ds_read_b128 v[188:191], v211 offset:53248
	ds_read_b128 v[192:195], v211 offset:54272
	ds_read_b128 v[196:199], v211 offset:55296
	ds_read_b128 v[200:203], v211 offset:56320
	global_load_lds_dwordx4 v[204:205], off
	v_lshl_add_u64 v[204:205], v[214:215], 0, s[18:19]
	s_add_i32 m0, s30, 0x2000
	s_add_i32 s30, s64, s37
	global_load_lds_dwordx4 v[204:205], off
	v_lshl_add_u64 v[204:205], v[216:217], 0, s[18:19]
	s_mov_b32 m0, s30
	s_nop 0
	global_load_lds_dwordx4 v[204:205], off
	v_lshl_add_u64 v[204:205], v[218:219], 0, s[18:19]
	s_add_i32 m0, s30, 0x2000
	s_nop 0
	global_load_lds_dwordx4 v[204:205], off
	v_lshl_add_u64 v[204:205], v[222:223], 0, s[18:19]
	s_mov_b32 m0, s43
	s_nop 0
	global_load_lds_dwordx4 v[204:205], off
	v_lshl_add_u64 v[204:205], v[224:225], 0, s[18:19]
	s_mov_b32 m0, s44
	s_nop 0
	global_load_lds_dwordx4 v[204:205], off
	s_waitcnt vmcnt(8)
	s_waitcnt lgkmcnt(0)
	s_barrier
	s_setprio 1
	v_mfma_f32_16x16x32_bf16 v[60:63], v[112:115], v[160:163], v[60:63]
	v_mfma_f32_16x16x32_bf16 v[60:63], v[116:119], v[164:167], v[60:63]
	v_mfma_f32_16x16x32_bf16 v[56:59], v[128:131], v[164:167], v[56:59]
	v_mfma_f32_16x16x32_bf16 v[56:59], v[120:123], v[160:163], v[56:59]
	v_mfma_f32_16x16x32_bf16 v[52:55], v[144:147], v[160:163], v[52:55]
	v_mfma_f32_16x16x32_bf16 v[52:55], v[148:151], v[164:167], v[52:55]
	v_mfma_f32_16x16x32_bf16 v[48:51], v[156:159], v[164:167], v[48:51]
	v_mfma_f32_16x16x32_bf16 v[48:51], v[152:155], v[160:163], v[48:51]
	v_mfma_f32_16x16x32_bf16 v[32:35], v[152:155], v[168:171], v[32:35]
	v_mfma_f32_16x16x32_bf16 v[32:35], v[156:159], v[172:175], v[32:35]
	v_mfma_f32_16x16x32_bf16 v[36:39], v[148:151], v[172:175], v[36:39]
	v_mfma_f32_16x16x32_bf16 v[36:39], v[144:147], v[168:171], v[36:39]
	v_mfma_f32_16x16x32_bf16 v[40:43], v[120:123], v[168:171], v[40:43]
	v_mfma_f32_16x16x32_bf16 v[40:43], v[128:131], v[172:175], v[40:43]
	v_mfma_f32_16x16x32_bf16 v[44:47], v[116:119], v[172:175], v[44:47]
	v_mfma_f32_16x16x32_bf16 v[44:47], v[112:115], v[168:171], v[44:47]
	v_mfma_f32_16x16x32_bf16 v[28:31], v[112:115], v[188:191], v[28:31]
	v_mfma_f32_16x16x32_bf16 v[28:31], v[116:119], v[192:195], v[28:31]
	v_mfma_f32_16x16x32_bf16 v[24:27], v[128:131], v[192:195], v[24:27]
	v_mfma_f32_16x16x32_bf16 v[24:27], v[120:123], v[188:191], v[24:27]
	v_mfma_f32_16x16x32_bf16 v[20:23], v[144:147], v[188:191], v[20:23]
	v_mfma_f32_16x16x32_bf16 v[20:23], v[148:151], v[192:195], v[20:23]
	v_mfma_f32_16x16x32_bf16 v[16:19], v[156:159], v[192:195], v[16:19]
	v_mfma_f32_16x16x32_bf16 v[16:19], v[152:155], v[188:191], v[16:19]
	v_mfma_f32_16x16x32_bf16 v[0:3], v[152:155], v[196:199], v[0:3]
	v_mfma_f32_16x16x32_bf16 v[0:3], v[156:159], v[200:203], v[0:3]
	v_mfma_f32_16x16x32_bf16 v[4:7], v[148:151], v[200:203], v[4:7]
	v_mfma_f32_16x16x32_bf16 v[4:7], v[144:147], v[196:199], v[4:7]
	v_mfma_f32_16x16x32_bf16 v[8:11], v[120:123], v[196:199], v[8:11]
	v_mfma_f32_16x16x32_bf16 v[8:11], v[128:131], v[200:203], v[8:11]
	v_mfma_f32_16x16x32_bf16 v[12:15], v[116:119], v[200:203], v[12:15]
	v_mfma_f32_16x16x32_bf16 v[12:15], v[112:115], v[196:199], v[12:15]
	s_setprio 0
	s_barrier
	s_add_u32 s28, s28, 0x100
	s_addc_u32 s29, s29, 0
	s_add_u32 s60, s60, 0x100
	s_addc_u32 s61, s61, 0
	s_cmp_ge_i32 s62, s45
	s_mov_b32 s30, s62
	s_cbranch_scc0 .LBB0_849

.LBB0_949:
	ds_read_b128 v[164:167], v157
	ds_read_b128 v[168:171], v157 offset:1024
	ds_read_b128 v[172:175], v157 offset:2048
	ds_read_b128 v[176:179], v157 offset:3072
	ds_read_b128 v[180:183], v162
	ds_read_b128 v[184:187], v162 offset:1024
	ds_read_b128 v[188:191], v162 offset:2048
	ds_read_b128 v[192:195], v162 offset:3072
	s_add_i32 s68, s34, 2
	s_add_u32 s69, s30, 0x80
	s_addc_u32 s35, s31, 0
	s_cmp_eq_u32 s49, s34
	s_cselect_b32 s34, s2, s69
	s_cselect_b32 s35, s3, s35
	s_cselect_b32 s71, s29, s67
	s_cselect_b32 s70, s28, s66
	v_lshl_add_u64 v[230:231], s[30:31], 0, v[136:137]
	s_add_i32 m0, s41, 0xc000
	ds_read_b128 v[196:199], v163
	ds_read_b128 v[200:203], v163 offset:1024
	ds_read_b128 v[204:207], v163 offset:2048
	ds_read_b128 v[208:211], v163 offset:3072
	ds_read_b128 v[212:215], v163 offset:4096
	ds_read_b128 v[216:219], v163 offset:5120
	ds_read_b128 v[222:225], v163 offset:6144
	ds_read_b128 v[226:229], v163 offset:7168
	global_load_lds_dwordx4 v[230:231], off
	v_lshl_add_u64 v[230:231], s[30:31], 0, v[138:139]
	s_add_i32 m0, s41, 0xe000
	s_nop 0
	global_load_lds_dwordx4 v[230:231], off
	s_waitcnt vmcnt(8)
	s_waitcnt lgkmcnt(0)
	s_barrier
	s_setprio 1
	v_mfma_f32_16x16x32_bf16 v[120:123], v[164:167], v[196:199], v[120:123]
	v_mfma_f32_16x16x32_bf16 v[120:123], v[168:171], v[200:203], v[120:123]
	v_mfma_f32_16x16x32_bf16 v[124:127], v[176:179], v[200:203], v[124:127]
	v_mfma_f32_16x16x32_bf16 v[124:127], v[172:175], v[196:199], v[124:127]
	v_mfma_f32_16x16x32_bf16 v[116:119], v[180:183], v[196:199], v[116:119]
	v_mfma_f32_16x16x32_bf16 v[116:119], v[184:187], v[200:203], v[116:119]
	v_mfma_f32_16x16x32_bf16 v[112:115], v[192:195], v[200:203], v[112:115]
	v_mfma_f32_16x16x32_bf16 v[112:115], v[188:191], v[196:199], v[112:115]
	v_mfma_f32_16x16x32_bf16 v[96:99], v[188:191], v[204:207], v[96:99]
	v_mfma_f32_16x16x32_bf16 v[96:99], v[192:195], v[208:211], v[96:99]
	v_mfma_f32_16x16x32_bf16 v[100:103], v[184:187], v[208:211], v[100:103]
	v_mfma_f32_16x16x32_bf16 v[100:103], v[180:183], v[204:207], v[100:103]
	v_mfma_f32_16x16x32_bf16 v[104:107], v[172:175], v[204:207], v[104:107]
	v_mfma_f32_16x16x32_bf16 v[104:107], v[176:179], v[208:211], v[104:107]
	v_mfma_f32_16x16x32_bf16 v[108:111], v[168:171], v[208:211], v[108:111]
	v_mfma_f32_16x16x32_bf16 v[108:111], v[164:167], v[204:207], v[108:111]
	v_mfma_f32_16x16x32_bf16 v[92:95], v[164:167], v[212:215], v[92:95]
	v_mfma_f32_16x16x32_bf16 v[92:95], v[168:171], v[216:219], v[92:95]
	v_mfma_f32_16x16x32_bf16 v[88:91], v[176:179], v[216:219], v[88:91]
	v_mfma_f32_16x16x32_bf16 v[88:91], v[172:175], v[212:215], v[88:91]
	v_mfma_f32_16x16x32_bf16 v[84:87], v[180:183], v[212:215], v[84:87]
	v_mfma_f32_16x16x32_bf16 v[84:87], v[184:187], v[216:219], v[84:87]
	v_mfma_f32_16x16x32_bf16 v[80:83], v[192:195], v[216:219], v[80:83]
	v_mfma_f32_16x16x32_bf16 v[80:83], v[188:191], v[212:215], v[80:83]
	v_mfma_f32_16x16x32_bf16 v[64:67], v[188:191], v[222:225], v[64:67]
	v_mfma_f32_16x16x32_bf16 v[64:67], v[192:195], v[226:229], v[64:67]
	v_mfma_f32_16x16x32_bf16 v[68:71], v[184:187], v[226:229], v[68:71]
	v_mfma_f32_16x16x32_bf16 v[68:71], v[180:183], v[222:225], v[68:71]
	v_mfma_f32_16x16x32_bf16 v[72:75], v[172:175], v[222:225], v[72:75]
	v_mfma_f32_16x16x32_bf16 v[72:75], v[176:179], v[226:229], v[72:75]
	v_mfma_f32_16x16x32_bf16 v[76:79], v[168:171], v[226:229], v[76:79]
	v_mfma_f32_16x16x32_bf16 v[76:79], v[164:167], v[222:225], v[76:79]
	s_setprio 0
	s_barrier
	s_add_i32 s69, s52, s40
	v_lshl_add_u64 v[230:231], s[70:71], 0, v[130:131]
	s_mov_b32 m0, s69
	ds_read_b128 v[196:199], v163 offset:16384
	ds_read_b128 v[200:203], v163 offset:17408
	ds_read_b128 v[204:207], v163 offset:18432
	ds_read_b128 v[208:211], v163 offset:19456
	ds_read_b128 v[212:215], v163 offset:20480
	ds_read_b128 v[216:219], v163 offset:21504
	ds_read_b128 v[222:225], v163 offset:22528
	ds_read_b128 v[226:229], v163 offset:23552
	global_load_lds_dwordx4 v[230:231], off
	s_add_i32 m0, s69, 0x2000
	v_lshl_add_u64 v[232:233], s[70:71], 0, v[134:135]
	s_add_u32 s70, s70, s6
	s_addc_u32 s71, s71, s7
	s_add_i32 s69, s53, s40
	global_load_lds_dwordx4 v[232:233], off
	v_lshl_add_u64 v[234:235], s[70:71], 0, v[130:131]
	s_mov_b32 m0, s69
	v_lshl_add_u64 v[236:237], s[70:71], 0, v[134:135]
	global_load_lds_dwordx4 v[234:235], off
	s_add_i32 m0, s69, 0x2000
	v_lshl_add_u64 v[238:239], s[34:35], 0, v[128:129]
	global_load_lds_dwordx4 v[236:237], off
	s_mov_b32 m0, s41
	v_lshl_add_u64 v[240:241], s[34:35], 0, v[132:133]
	global_load_lds_dwordx4 v[238:239], off
	s_mov_b32 m0, s42
	s_nop 0
	global_load_lds_dwordx4 v[240:241], off
	s_waitcnt vmcnt(8)
	s_waitcnt lgkmcnt(0)
	s_barrier
	s_setprio 1
	v_mfma_f32_16x16x32_bf16 v[60:63], v[164:167], v[196:199], v[60:63]
	v_mfma_f32_16x16x32_bf16 v[60:63], v[168:171], v[200:203], v[60:63]
	v_mfma_f32_16x16x32_bf16 v[56:59], v[176:179], v[200:203], v[56:59]
	v_mfma_f32_16x16x32_bf16 v[56:59], v[172:175], v[196:199], v[56:59]
	v_mfma_f32_16x16x32_bf16 v[52:55], v[180:183], v[196:199], v[52:55]
	v_mfma_f32_16x16x32_bf16 v[52:55], v[184:187], v[200:203], v[52:55]
	v_mfma_f32_16x16x32_bf16 v[48:51], v[192:195], v[200:203], v[48:51]
	v_mfma_f32_16x16x32_bf16 v[48:51], v[188:191], v[196:199], v[48:51]
	v_mfma_f32_16x16x32_bf16 v[32:35], v[188:191], v[204:207], v[32:35]
	v_mfma_f32_16x16x32_bf16 v[32:35], v[192:195], v[208:211], v[32:35]
	v_mfma_f32_16x16x32_bf16 v[36:39], v[184:187], v[208:211], v[36:39]
	v_mfma_f32_16x16x32_bf16 v[36:39], v[180:183], v[204:207], v[36:39]
	v_mfma_f32_16x16x32_bf16 v[40:43], v[172:175], v[204:207], v[40:43]
	v_mfma_f32_16x16x32_bf16 v[40:43], v[176:179], v[208:211], v[40:43]
	v_mfma_f32_16x16x32_bf16 v[44:47], v[168:171], v[208:211], v[44:47]
	v_mfma_f32_16x16x32_bf16 v[44:47], v[164:167], v[204:207], v[44:47]
	v_mfma_f32_16x16x32_bf16 v[28:31], v[164:167], v[212:215], v[28:31]
	v_mfma_f32_16x16x32_bf16 v[28:31], v[168:171], v[216:219], v[28:31]
	v_mfma_f32_16x16x32_bf16 v[24:27], v[176:179], v[216:219], v[24:27]
	v_mfma_f32_16x16x32_bf16 v[24:27], v[172:175], v[212:215], v[24:27]
	v_mfma_f32_16x16x32_bf16 v[20:23], v[180:183], v[212:215], v[20:23]
	v_mfma_f32_16x16x32_bf16 v[20:23], v[184:187], v[216:219], v[20:23]
	v_mfma_f32_16x16x32_bf16 v[16:19], v[192:195], v[216:219], v[16:19]
	v_mfma_f32_16x16x32_bf16 v[16:19], v[188:191], v[212:215], v[16:19]
	v_mfma_f32_16x16x32_bf16 v[0:3], v[188:191], v[222:225], v[0:3]
	v_mfma_f32_16x16x32_bf16 v[0:3], v[192:195], v[226:229], v[0:3]
	v_mfma_f32_16x16x32_bf16 v[4:7], v[184:187], v[226:229], v[4:7]
	v_mfma_f32_16x16x32_bf16 v[4:7], v[180:183], v[222:225], v[4:7]
	v_mfma_f32_16x16x32_bf16 v[8:11], v[172:175], v[222:225], v[8:11]
	v_mfma_f32_16x16x32_bf16 v[8:11], v[176:179], v[226:229], v[8:11]
	v_mfma_f32_16x16x32_bf16 v[12:15], v[168:171], v[226:229], v[12:15]
	v_mfma_f32_16x16x32_bf16 v[12:15], v[164:167], v[222:225], v[12:15]
	s_setprio 0
	s_barrier
	s_add_i32 s69, 0, 0x18000
	s_add_i32 s70, 0, 0x1c000
	v_add_u32_e32 v176, s69, v154
	v_add_u32_e32 v192, s70, v154
	ds_read_b128 v[164:167], v176
	ds_read_b128 v[168:171], v176 offset:1024
	ds_read_b128 v[172:175], v176 offset:2048
	ds_read_b128 v[176:179], v176 offset:3072
	ds_read_b128 v[180:183], v192
	ds_read_b128 v[184:187], v192 offset:1024
	ds_read_b128 v[188:191], v192 offset:2048
	ds_read_b128 v[192:195], v192 offset:3072
	s_add_u32 s34, s34, s6
	s_addc_u32 s35, s35, s7
	s_mov_b32 m0, s43
	v_lshl_add_u64 v[242:243], s[34:35], 0, v[128:129]
	ds_read_b128 v[196:199], v163 offset:32768
	ds_read_b128 v[200:203], v163 offset:33792
	ds_read_b128 v[204:207], v163 offset:34816
	ds_read_b128 v[208:211], v163 offset:35840
	ds_read_b128 v[212:215], v163 offset:36864
	ds_read_b128 v[216:219], v163 offset:37888
	ds_read_b128 v[222:225], v163 offset:38912
	ds_read_b128 v[226:229], v163 offset:39936
	global_load_lds_dwordx4 v[242:243], off
	v_lshl_add_u64 v[242:243], s[34:35], 0, v[132:133]
	s_mov_b32 m0, s44
	s_nop 0
	global_load_lds_dwordx4 v[242:243], off
	s_waitcnt vmcnt(8)
	s_waitcnt lgkmcnt(0)
	s_barrier
	s_setprio 1
	v_mfma_f32_16x16x32_bf16 v[120:123], v[164:167], v[196:199], v[120:123]
	v_mfma_f32_16x16x32_bf16 v[120:123], v[168:171], v[200:203], v[120:123]
	v_mfma_f32_16x16x32_bf16 v[124:127], v[176:179], v[200:203], v[124:127]
	v_mfma_f32_16x16x32_bf16 v[124:127], v[172:175], v[196:199], v[124:127]
	v_mfma_f32_16x16x32_bf16 v[116:119], v[180:183], v[196:199], v[116:119]
	v_mfma_f32_16x16x32_bf16 v[116:119], v[184:187], v[200:203], v[116:119]
	v_mfma_f32_16x16x32_bf16 v[112:115], v[192:195], v[200:203], v[112:115]
	v_mfma_f32_16x16x32_bf16 v[112:115], v[188:191], v[196:199], v[112:115]
	v_mfma_f32_16x16x32_bf16 v[96:99], v[188:191], v[204:207], v[96:99]
	v_mfma_f32_16x16x32_bf16 v[96:99], v[192:195], v[208:211], v[96:99]
	v_mfma_f32_16x16x32_bf16 v[100:103], v[184:187], v[208:211], v[100:103]
	v_mfma_f32_16x16x32_bf16 v[100:103], v[180:183], v[204:207], v[100:103]
	v_mfma_f32_16x16x32_bf16 v[104:107], v[172:175], v[204:207], v[104:107]
	v_mfma_f32_16x16x32_bf16 v[104:107], v[176:179], v[208:211], v[104:107]
	v_mfma_f32_16x16x32_bf16 v[108:111], v[168:171], v[208:211], v[108:111]
	v_mfma_f32_16x16x32_bf16 v[108:111], v[164:167], v[204:207], v[108:111]
	v_mfma_f32_16x16x32_bf16 v[92:95], v[164:167], v[212:215], v[92:95]
	v_mfma_f32_16x16x32_bf16 v[92:95], v[168:171], v[216:219], v[92:95]
	v_mfma_f32_16x16x32_bf16 v[88:91], v[176:179], v[216:219], v[88:91]
	v_mfma_f32_16x16x32_bf16 v[88:91], v[172:175], v[212:215], v[88:91]
	v_mfma_f32_16x16x32_bf16 v[84:87], v[180:183], v[212:215], v[84:87]
	v_mfma_f32_16x16x32_bf16 v[84:87], v[184:187], v[216:219], v[84:87]
	v_mfma_f32_16x16x32_bf16 v[80:83], v[192:195], v[216:219], v[80:83]
	v_mfma_f32_16x16x32_bf16 v[80:83], v[188:191], v[212:215], v[80:83]
	v_mfma_f32_16x16x32_bf16 v[64:67], v[188:191], v[222:225], v[64:67]
	v_mfma_f32_16x16x32_bf16 v[64:67], v[192:195], v[226:229], v[64:67]
	v_mfma_f32_16x16x32_bf16 v[68:71], v[184:187], v[226:229], v[68:71]
	v_mfma_f32_16x16x32_bf16 v[68:71], v[180:183], v[222:225], v[68:71]
	v_mfma_f32_16x16x32_bf16 v[72:75], v[172:175], v[222:225], v[72:75]
	v_mfma_f32_16x16x32_bf16 v[72:75], v[176:179], v[226:229], v[72:75]
	v_mfma_f32_16x16x32_bf16 v[76:79], v[168:171], v[226:229], v[76:79]
	v_mfma_f32_16x16x32_bf16 v[76:79], v[164:167], v[222:225], v[76:79]
	s_setprio 0
	s_barrier
	s_add_i32 s34, s69, s40
	v_lshl_add_u64 v[230:231], v[230:231], 0, s[12:13]
	s_mov_b32 m0, s34
	ds_read_b128 v[196:199], v163 offset:49152
	ds_read_b128 v[200:203], v163 offset:50176
	ds_read_b128 v[204:207], v163 offset:51200
	ds_read_b128 v[208:211], v163 offset:52224
	ds_read_b128 v[212:215], v163 offset:53248
	ds_read_b128 v[216:219], v163 offset:54272
	ds_read_b128 v[222:225], v163 offset:55296
	ds_read_b128 v[226:229], v163 offset:56320
	global_load_lds_dwordx4 v[230:231], off
	v_lshl_add_u64 v[230:231], v[232:233], 0, s[12:13]
	s_add_i32 m0, s34, 0x2000
	s_add_i32 s34, s70, s40
	global_load_lds_dwordx4 v[230:231], off
	v_lshl_add_u64 v[230:231], v[234:235], 0, s[12:13]
	s_mov_b32 m0, s34
	s_nop 0
	global_load_lds_dwordx4 v[230:231], off
	v_lshl_add_u64 v[230:231], v[236:237], 0, s[12:13]
	s_add_i32 m0, s34, 0x2000
	s_nop 0
	global_load_lds_dwordx4 v[230:231], off
	v_lshl_add_u64 v[230:231], v[238:239], 0, s[12:13]
	s_mov_b32 m0, s46
	s_nop 0
	global_load_lds_dwordx4 v[230:231], off
	v_lshl_add_u64 v[230:231], v[240:241], 0, s[12:13]
	s_mov_b32 m0, s47
	s_nop 0
	global_load_lds_dwordx4 v[230:231], off
	s_waitcnt vmcnt(8)
	s_waitcnt lgkmcnt(0)
	s_barrier
	s_setprio 1
	v_mfma_f32_16x16x32_bf16 v[60:63], v[164:167], v[196:199], v[60:63]
	v_mfma_f32_16x16x32_bf16 v[60:63], v[168:171], v[200:203], v[60:63]
	v_mfma_f32_16x16x32_bf16 v[56:59], v[176:179], v[200:203], v[56:59]
	v_mfma_f32_16x16x32_bf16 v[56:59], v[172:175], v[196:199], v[56:59]
	v_mfma_f32_16x16x32_bf16 v[52:55], v[180:183], v[196:199], v[52:55]
	v_mfma_f32_16x16x32_bf16 v[52:55], v[184:187], v[200:203], v[52:55]
	v_mfma_f32_16x16x32_bf16 v[48:51], v[192:195], v[200:203], v[48:51]
	v_mfma_f32_16x16x32_bf16 v[48:51], v[188:191], v[196:199], v[48:51]
	v_mfma_f32_16x16x32_bf16 v[32:35], v[188:191], v[204:207], v[32:35]
	v_mfma_f32_16x16x32_bf16 v[32:35], v[192:195], v[208:211], v[32:35]
	v_mfma_f32_16x16x32_bf16 v[36:39], v[184:187], v[208:211], v[36:39]
	v_mfma_f32_16x16x32_bf16 v[36:39], v[180:183], v[204:207], v[36:39]
	v_mfma_f32_16x16x32_bf16 v[40:43], v[172:175], v[204:207], v[40:43]
	v_mfma_f32_16x16x32_bf16 v[40:43], v[176:179], v[208:211], v[40:43]
	v_mfma_f32_16x16x32_bf16 v[44:47], v[168:171], v[208:211], v[44:47]
	v_mfma_f32_16x16x32_bf16 v[44:47], v[164:167], v[204:207], v[44:47]
	v_mfma_f32_16x16x32_bf16 v[28:31], v[164:167], v[212:215], v[28:31]
	v_mfma_f32_16x16x32_bf16 v[28:31], v[168:171], v[216:219], v[28:31]
	v_mfma_f32_16x16x32_bf16 v[24:27], v[176:179], v[216:219], v[24:27]
	v_mfma_f32_16x16x32_bf16 v[24:27], v[172:175], v[212:215], v[24:27]
	v_mfma_f32_16x16x32_bf16 v[20:23], v[180:183], v[212:215], v[20:23]
	v_mfma_f32_16x16x32_bf16 v[20:23], v[184:187], v[216:219], v[20:23]
	v_mfma_f32_16x16x32_bf16 v[16:19], v[192:195], v[216:219], v[16:19]
	v_mfma_f32_16x16x32_bf16 v[16:19], v[188:191], v[212:215], v[16:19]
	v_mfma_f32_16x16x32_bf16 v[0:3], v[188:191], v[222:225], v[0:3]
	v_mfma_f32_16x16x32_bf16 v[0:3], v[192:195], v[226:229], v[0:3]
	v_mfma_f32_16x16x32_bf16 v[4:7], v[184:187], v[226:229], v[4:7]
	v_mfma_f32_16x16x32_bf16 v[4:7], v[180:183], v[222:225], v[4:7]
	v_mfma_f32_16x16x32_bf16 v[8:11], v[172:175], v[222:225], v[8:11]
	v_mfma_f32_16x16x32_bf16 v[8:11], v[176:179], v[226:229], v[8:11]
	v_mfma_f32_16x16x32_bf16 v[12:15], v[168:171], v[226:229], v[12:15]
	v_mfma_f32_16x16x32_bf16 v[12:15], v[164:167], v[222:225], v[12:15]
	s_setprio 0
	s_barrier
	s_add_u32 s30, s30, 0x100
	s_addc_u32 s31, s31, 0
	s_add_u32 s66, s66, 0x100
	s_addc_u32 s67, s67, 0
	s_cmp_ge_i32 s68, s48
	s_mov_b32 s34, s68
	s_cbranch_scc0 .LBB0_949

.LBB0_970:
	ds_read_b128 v[170:173], v139
	ds_read_b128 v[174:177], v139 offset:1024
	ds_read_b128 v[178:181], v139 offset:2048
	ds_read_b128 v[182:185], v139 offset:3072
	ds_read_b128 v[186:189], v165
	ds_read_b128 v[190:193], v165 offset:1024
	ds_read_b128 v[194:197], v165 offset:2048
	ds_read_b128 v[198:201], v165 offset:3072
	s_add_i32 s8, s4, 2
	s_add_u32 s9, s2, 0x80
	s_addc_u32 s5, s3, 0
	s_cmp_eq_u32 s52, s4
	s_cselect_b32 s4, s30, s9
	s_cselect_b32 s5, s31, s5
	s_cselect_b32 s11, s35, s7
	s_cselect_b32 s10, s34, s6
	v_lshl_add_u64 v[218:219], s[2:3], 0, v[156:157]
	s_add_i32 m0, s42, 0xc000
	ds_read_b128 v[202:205], v166
	ds_read_b128 v[206:209], v166 offset:1024
	ds_read_b128 v[210:213], v166 offset:2048
	ds_read_b128 v[214:217], v166 offset:3072
	ds_read_b128 v[222:225], v166 offset:4096
	ds_read_b128 v[226:229], v166 offset:5120
	ds_read_b128 v[230:233], v166 offset:6144
	ds_read_b128 v[234:237], v166 offset:7168
	global_load_lds_dwordx4 v[218:219], off
	v_lshl_add_u64 v[218:219], s[2:3], 0, v[158:159]
	s_add_i32 m0, s42, 0xe000
	s_nop 0
	global_load_lds_dwordx4 v[218:219], off
	s_waitcnt vmcnt(8)
	s_waitcnt lgkmcnt(0)
	s_barrier
	s_setprio 1
	v_mfma_f32_16x16x32_bf16 v[124:127], v[170:173], v[202:205], v[124:127]
	v_mfma_f32_16x16x32_bf16 v[124:127], v[174:177], v[206:209], v[124:127]
	v_mfma_f32_16x16x32_bf16 v[120:123], v[182:185], v[206:209], v[120:123]
	v_mfma_f32_16x16x32_bf16 v[120:123], v[178:181], v[202:205], v[120:123]
	v_mfma_f32_16x16x32_bf16 v[116:119], v[186:189], v[202:205], v[116:119]
	v_mfma_f32_16x16x32_bf16 v[116:119], v[190:193], v[206:209], v[116:119]
	v_mfma_f32_16x16x32_bf16 v[112:115], v[198:201], v[206:209], v[112:115]
	v_mfma_f32_16x16x32_bf16 v[112:115], v[194:197], v[202:205], v[112:115]
	v_mfma_f32_16x16x32_bf16 v[96:99], v[194:197], v[210:213], v[96:99]
	v_mfma_f32_16x16x32_bf16 v[96:99], v[198:201], v[214:217], v[96:99]
	v_mfma_f32_16x16x32_bf16 v[100:103], v[190:193], v[214:217], v[100:103]
	v_mfma_f32_16x16x32_bf16 v[100:103], v[186:189], v[210:213], v[100:103]
	v_mfma_f32_16x16x32_bf16 v[104:107], v[178:181], v[210:213], v[104:107]
	v_mfma_f32_16x16x32_bf16 v[104:107], v[182:185], v[214:217], v[104:107]
	v_mfma_f32_16x16x32_bf16 v[108:111], v[174:177], v[214:217], v[108:111]
	v_mfma_f32_16x16x32_bf16 v[108:111], v[170:173], v[210:213], v[108:111]
	v_mfma_f32_16x16x32_bf16 v[92:95], v[170:173], v[222:225], v[92:95]
	v_mfma_f32_16x16x32_bf16 v[92:95], v[174:177], v[226:229], v[92:95]
	v_mfma_f32_16x16x32_bf16 v[88:91], v[182:185], v[226:229], v[88:91]
	v_mfma_f32_16x16x32_bf16 v[88:91], v[178:181], v[222:225], v[88:91]
	v_mfma_f32_16x16x32_bf16 v[84:87], v[186:189], v[222:225], v[84:87]
	v_mfma_f32_16x16x32_bf16 v[84:87], v[190:193], v[226:229], v[84:87]
	v_mfma_f32_16x16x32_bf16 v[80:83], v[198:201], v[226:229], v[80:83]
	v_mfma_f32_16x16x32_bf16 v[80:83], v[194:197], v[222:225], v[80:83]
	v_mfma_f32_16x16x32_bf16 v[64:67], v[194:197], v[230:233], v[64:67]
	v_mfma_f32_16x16x32_bf16 v[64:67], v[198:201], v[234:237], v[64:67]
	v_mfma_f32_16x16x32_bf16 v[68:71], v[190:193], v[234:237], v[68:71]
	v_mfma_f32_16x16x32_bf16 v[68:71], v[186:189], v[230:233], v[68:71]
	v_mfma_f32_16x16x32_bf16 v[72:75], v[178:181], v[230:233], v[72:75]
	v_mfma_f32_16x16x32_bf16 v[72:75], v[182:185], v[234:237], v[72:75]
	v_mfma_f32_16x16x32_bf16 v[76:79], v[174:177], v[234:237], v[76:79]
	v_mfma_f32_16x16x32_bf16 v[76:79], v[170:173], v[230:233], v[76:79]
	s_setprio 0
	s_barrier
	s_add_i32 s9, s60, s39
	v_lshl_add_u64 v[218:219], s[10:11], 0, v[132:133]
	s_mov_b32 m0, s9
	ds_read_b128 v[202:205], v166 offset:16384
	ds_read_b128 v[206:209], v166 offset:17408
	ds_read_b128 v[210:213], v166 offset:18432
	ds_read_b128 v[214:217], v166 offset:19456
	ds_read_b128 v[222:225], v166 offset:20480
	ds_read_b128 v[226:229], v166 offset:21504
	ds_read_b128 v[230:233], v166 offset:22528
	ds_read_b128 v[234:237], v166 offset:23552
	global_load_lds_dwordx4 v[218:219], off
	s_add_i32 m0, s9, 0x2000
	v_lshl_add_u64 v[238:239], s[10:11], 0, v[128:129]
	s_add_u32 s10, s10, s18
	s_addc_u32 s11, s11, s19
	s_add_i32 s9, s61, s39
	global_load_lds_dwordx4 v[238:239], off
	v_lshl_add_u64 v[240:241], s[10:11], 0, v[132:133]
	s_mov_b32 m0, s9
	v_lshl_add_u64 v[242:243], s[10:11], 0, v[128:129]
	global_load_lds_dwordx4 v[240:241], off
	s_add_i32 m0, s9, 0x2000
	v_lshl_add_u64 v[244:245], s[4:5], 0, v[134:135]
	global_load_lds_dwordx4 v[242:243], off
	s_mov_b32 m0, s42
	v_lshl_add_u64 v[246:247], s[4:5], 0, v[130:131]
	global_load_lds_dwordx4 v[244:245], off
	s_mov_b32 m0, s43
	s_nop 0
	global_load_lds_dwordx4 v[246:247], off
	s_waitcnt vmcnt(8)
	s_waitcnt lgkmcnt(0)
	s_barrier
	s_setprio 1
	v_mfma_f32_16x16x32_bf16 v[60:63], v[170:173], v[202:205], v[60:63]
	v_mfma_f32_16x16x32_bf16 v[60:63], v[174:177], v[206:209], v[60:63]
	v_mfma_f32_16x16x32_bf16 v[56:59], v[182:185], v[206:209], v[56:59]
	v_mfma_f32_16x16x32_bf16 v[56:59], v[178:181], v[202:205], v[56:59]
	v_mfma_f32_16x16x32_bf16 v[52:55], v[186:189], v[202:205], v[52:55]
	v_mfma_f32_16x16x32_bf16 v[52:55], v[190:193], v[206:209], v[52:55]
	v_mfma_f32_16x16x32_bf16 v[48:51], v[198:201], v[206:209], v[48:51]
	v_mfma_f32_16x16x32_bf16 v[48:51], v[194:197], v[202:205], v[48:51]
	v_mfma_f32_16x16x32_bf16 v[32:35], v[194:197], v[210:213], v[32:35]
	v_mfma_f32_16x16x32_bf16 v[32:35], v[198:201], v[214:217], v[32:35]
	v_mfma_f32_16x16x32_bf16 v[36:39], v[190:193], v[214:217], v[36:39]
	v_mfma_f32_16x16x32_bf16 v[36:39], v[186:189], v[210:213], v[36:39]
	v_mfma_f32_16x16x32_bf16 v[40:43], v[178:181], v[210:213], v[40:43]
	v_mfma_f32_16x16x32_bf16 v[40:43], v[182:185], v[214:217], v[40:43]
	v_mfma_f32_16x16x32_bf16 v[44:47], v[174:177], v[214:217], v[44:47]
	v_mfma_f32_16x16x32_bf16 v[44:47], v[170:173], v[210:213], v[44:47]
	v_mfma_f32_16x16x32_bf16 v[28:31], v[170:173], v[222:225], v[28:31]
	v_mfma_f32_16x16x32_bf16 v[28:31], v[174:177], v[226:229], v[28:31]
	v_mfma_f32_16x16x32_bf16 v[24:27], v[182:185], v[226:229], v[24:27]
	v_mfma_f32_16x16x32_bf16 v[24:27], v[178:181], v[222:225], v[24:27]
	v_mfma_f32_16x16x32_bf16 v[20:23], v[186:189], v[222:225], v[20:23]
	v_mfma_f32_16x16x32_bf16 v[20:23], v[190:193], v[226:229], v[20:23]
	v_mfma_f32_16x16x32_bf16 v[16:19], v[198:201], v[226:229], v[16:19]
	v_mfma_f32_16x16x32_bf16 v[16:19], v[194:197], v[222:225], v[16:19]
	v_mfma_f32_16x16x32_bf16 v[0:3], v[194:197], v[230:233], v[0:3]
	v_mfma_f32_16x16x32_bf16 v[0:3], v[198:201], v[234:237], v[0:3]
	v_mfma_f32_16x16x32_bf16 v[4:7], v[190:193], v[234:237], v[4:7]
	v_mfma_f32_16x16x32_bf16 v[4:7], v[186:189], v[230:233], v[4:7]
	v_mfma_f32_16x16x32_bf16 v[8:11], v[178:181], v[230:233], v[8:11]
	v_mfma_f32_16x16x32_bf16 v[8:11], v[182:185], v[234:237], v[8:11]
	v_mfma_f32_16x16x32_bf16 v[12:15], v[174:177], v[234:237], v[12:15]
	v_mfma_f32_16x16x32_bf16 v[12:15], v[170:173], v[230:233], v[12:15]
	s_setprio 0
	s_barrier
	s_add_i32 s9, 0, 0x18000
	v_add_u32_e32 v169, s9, v164
	s_add_i32 s10, 0, 0x1c000
	ds_read_b128 v[170:173], v169
	ds_read_b128 v[174:177], v169 offset:1024
	ds_read_b128 v[178:181], v169 offset:2048
	ds_read_b128 v[182:185], v169 offset:3072
	v_add_u32_e32 v169, s10, v164
	ds_read_b128 v[186:189], v169
	ds_read_b128 v[190:193], v169 offset:1024
	ds_read_b128 v[194:197], v169 offset:2048
	ds_read_b128 v[198:201], v169 offset:3072
	s_add_u32 s4, s4, s18
	s_addc_u32 s5, s5, s19
	s_mov_b32 m0, s44
	v_lshl_add_u64 v[248:249], s[4:5], 0, v[134:135]
	ds_read_b128 v[202:205], v166 offset:32768
	ds_read_b128 v[206:209], v166 offset:33792
	ds_read_b128 v[210:213], v166 offset:34816
	ds_read_b128 v[214:217], v166 offset:35840
	ds_read_b128 v[222:225], v166 offset:36864
	ds_read_b128 v[226:229], v166 offset:37888
	ds_read_b128 v[230:233], v166 offset:38912
	ds_read_b128 v[234:237], v166 offset:39936
	global_load_lds_dwordx4 v[248:249], off
	v_lshl_add_u64 v[248:249], s[4:5], 0, v[130:131]
	s_mov_b32 m0, s45
	s_nop 0
	global_load_lds_dwordx4 v[248:249], off
	s_waitcnt vmcnt(8)
	s_waitcnt lgkmcnt(0)
	s_barrier
	s_setprio 1
	v_mfma_f32_16x16x32_bf16 v[124:127], v[170:173], v[202:205], v[124:127]
	v_mfma_f32_16x16x32_bf16 v[124:127], v[174:177], v[206:209], v[124:127]
	v_mfma_f32_16x16x32_bf16 v[120:123], v[182:185], v[206:209], v[120:123]
	v_mfma_f32_16x16x32_bf16 v[120:123], v[178:181], v[202:205], v[120:123]
	v_mfma_f32_16x16x32_bf16 v[116:119], v[186:189], v[202:205], v[116:119]
	v_mfma_f32_16x16x32_bf16 v[116:119], v[190:193], v[206:209], v[116:119]
	v_mfma_f32_16x16x32_bf16 v[112:115], v[198:201], v[206:209], v[112:115]
	v_mfma_f32_16x16x32_bf16 v[112:115], v[194:197], v[202:205], v[112:115]
	v_mfma_f32_16x16x32_bf16 v[96:99], v[194:197], v[210:213], v[96:99]
	v_mfma_f32_16x16x32_bf16 v[96:99], v[198:201], v[214:217], v[96:99]
	v_mfma_f32_16x16x32_bf16 v[100:103], v[190:193], v[214:217], v[100:103]
	v_mfma_f32_16x16x32_bf16 v[100:103], v[186:189], v[210:213], v[100:103]
	v_mfma_f32_16x16x32_bf16 v[104:107], v[178:181], v[210:213], v[104:107]
	v_mfma_f32_16x16x32_bf16 v[104:107], v[182:185], v[214:217], v[104:107]
	v_mfma_f32_16x16x32_bf16 v[108:111], v[174:177], v[214:217], v[108:111]
	v_mfma_f32_16x16x32_bf16 v[108:111], v[170:173], v[210:213], v[108:111]
	v_mfma_f32_16x16x32_bf16 v[92:95], v[170:173], v[222:225], v[92:95]
	v_mfma_f32_16x16x32_bf16 v[92:95], v[174:177], v[226:229], v[92:95]
	v_mfma_f32_16x16x32_bf16 v[88:91], v[182:185], v[226:229], v[88:91]
	v_mfma_f32_16x16x32_bf16 v[88:91], v[178:181], v[222:225], v[88:91]
	v_mfma_f32_16x16x32_bf16 v[84:87], v[186:189], v[222:225], v[84:87]
	v_mfma_f32_16x16x32_bf16 v[84:87], v[190:193], v[226:229], v[84:87]
	v_mfma_f32_16x16x32_bf16 v[80:83], v[198:201], v[226:229], v[80:83]
	v_mfma_f32_16x16x32_bf16 v[80:83], v[194:197], v[222:225], v[80:83]
	v_mfma_f32_16x16x32_bf16 v[64:67], v[194:197], v[230:233], v[64:67]
	v_mfma_f32_16x16x32_bf16 v[64:67], v[198:201], v[234:237], v[64:67]
	v_mfma_f32_16x16x32_bf16 v[68:71], v[190:193], v[234:237], v[68:71]
	v_mfma_f32_16x16x32_bf16 v[68:71], v[186:189], v[230:233], v[68:71]
	v_mfma_f32_16x16x32_bf16 v[72:75], v[178:181], v[230:233], v[72:75]
	v_mfma_f32_16x16x32_bf16 v[72:75], v[182:185], v[234:237], v[72:75]
	v_mfma_f32_16x16x32_bf16 v[76:79], v[174:177], v[234:237], v[76:79]
	v_mfma_f32_16x16x32_bf16 v[76:79], v[170:173], v[230:233], v[76:79]
	s_setprio 0
	s_barrier
	s_add_i32 s4, s9, s39
	v_lshl_add_u64 v[218:219], v[218:219], 0, s[24:25]
	s_mov_b32 m0, s4
	ds_read_b128 v[202:205], v166 offset:49152
	ds_read_b128 v[206:209], v166 offset:50176
	ds_read_b128 v[210:213], v166 offset:51200
	ds_read_b128 v[214:217], v166 offset:52224
	ds_read_b128 v[222:225], v166 offset:53248
	ds_read_b128 v[226:229], v166 offset:54272
	ds_read_b128 v[230:233], v166 offset:55296
	ds_read_b128 v[234:237], v166 offset:56320
	global_load_lds_dwordx4 v[218:219], off
	v_lshl_add_u64 v[218:219], v[238:239], 0, s[24:25]
	s_add_i32 m0, s4, 0x2000
	s_add_i32 s4, s10, s39
	global_load_lds_dwordx4 v[218:219], off
	v_lshl_add_u64 v[218:219], v[240:241], 0, s[24:25]
	s_mov_b32 m0, s4
	s_nop 0
	global_load_lds_dwordx4 v[218:219], off
	v_lshl_add_u64 v[218:219], v[242:243], 0, s[24:25]
	s_add_i32 m0, s4, 0x2000
	s_nop 0
	global_load_lds_dwordx4 v[218:219], off
	v_lshl_add_u64 v[218:219], v[244:245], 0, s[24:25]
	s_mov_b32 m0, s49
	s_nop 0
	global_load_lds_dwordx4 v[218:219], off
	v_lshl_add_u64 v[218:219], v[246:247], 0, s[24:25]
	s_mov_b32 m0, s50
	s_nop 0
	global_load_lds_dwordx4 v[218:219], off
	s_waitcnt vmcnt(8)
	s_waitcnt lgkmcnt(0)
	s_barrier
	s_setprio 1
	v_mfma_f32_16x16x32_bf16 v[60:63], v[170:173], v[202:205], v[60:63]
	v_mfma_f32_16x16x32_bf16 v[60:63], v[174:177], v[206:209], v[60:63]
	v_mfma_f32_16x16x32_bf16 v[56:59], v[182:185], v[206:209], v[56:59]
	v_mfma_f32_16x16x32_bf16 v[56:59], v[178:181], v[202:205], v[56:59]
	v_mfma_f32_16x16x32_bf16 v[52:55], v[186:189], v[202:205], v[52:55]
	v_mfma_f32_16x16x32_bf16 v[52:55], v[190:193], v[206:209], v[52:55]
	v_mfma_f32_16x16x32_bf16 v[48:51], v[198:201], v[206:209], v[48:51]
	v_mfma_f32_16x16x32_bf16 v[48:51], v[194:197], v[202:205], v[48:51]
	v_mfma_f32_16x16x32_bf16 v[32:35], v[194:197], v[210:213], v[32:35]
	v_mfma_f32_16x16x32_bf16 v[32:35], v[198:201], v[214:217], v[32:35]
	v_mfma_f32_16x16x32_bf16 v[36:39], v[190:193], v[214:217], v[36:39]
	v_mfma_f32_16x16x32_bf16 v[36:39], v[186:189], v[210:213], v[36:39]
	v_mfma_f32_16x16x32_bf16 v[40:43], v[178:181], v[210:213], v[40:43]
	v_mfma_f32_16x16x32_bf16 v[40:43], v[182:185], v[214:217], v[40:43]
	v_mfma_f32_16x16x32_bf16 v[44:47], v[174:177], v[214:217], v[44:47]
	v_mfma_f32_16x16x32_bf16 v[44:47], v[170:173], v[210:213], v[44:47]
	v_mfma_f32_16x16x32_bf16 v[28:31], v[170:173], v[222:225], v[28:31]
	v_mfma_f32_16x16x32_bf16 v[28:31], v[174:177], v[226:229], v[28:31]
	v_mfma_f32_16x16x32_bf16 v[24:27], v[182:185], v[226:229], v[24:27]
	v_mfma_f32_16x16x32_bf16 v[24:27], v[178:181], v[222:225], v[24:27]
	v_mfma_f32_16x16x32_bf16 v[20:23], v[186:189], v[222:225], v[20:23]
	v_mfma_f32_16x16x32_bf16 v[20:23], v[190:193], v[226:229], v[20:23]
	v_mfma_f32_16x16x32_bf16 v[16:19], v[198:201], v[226:229], v[16:19]
	v_mfma_f32_16x16x32_bf16 v[16:19], v[194:197], v[222:225], v[16:19]
	v_mfma_f32_16x16x32_bf16 v[0:3], v[194:197], v[230:233], v[0:3]
	v_mfma_f32_16x16x32_bf16 v[0:3], v[198:201], v[234:237], v[0:3]
	v_mfma_f32_16x16x32_bf16 v[4:7], v[190:193], v[234:237], v[4:7]
	v_mfma_f32_16x16x32_bf16 v[4:7], v[186:189], v[230:233], v[4:7]
	v_mfma_f32_16x16x32_bf16 v[8:11], v[178:181], v[230:233], v[8:11]
	v_mfma_f32_16x16x32_bf16 v[8:11], v[182:185], v[234:237], v[8:11]
	v_mfma_f32_16x16x32_bf16 v[12:15], v[174:177], v[234:237], v[12:15]
	v_mfma_f32_16x16x32_bf16 v[12:15], v[170:173], v[230:233], v[12:15]
	s_setprio 0
	s_barrier
	s_add_u32 s2, s2, 0x100
	s_addc_u32 s3, s3, 0
	s_add_u32 s6, s6, 0x100
	s_addc_u32 s7, s7, 0
	s_cmp_ge_i32 s8, s51
	s_mov_b32 s4, s8
	s_cbranch_scc0 .LBB0_970

.LBB0_1056:
	ds_read_b128 v[140:143], v222
	ds_read_b128 v[144:147], v222 offset:1024
	ds_read_b128 v[148:151], v222 offset:2048
	ds_read_b128 v[152:155], v222 offset:3072
	ds_read_b128 v[156:159], v223
	ds_read_b128 v[160:163], v223 offset:1024
	ds_read_b128 v[164:167], v223 offset:2048
	ds_read_b128 v[168:171], v223 offset:3072
	s_add_i32 s62, s26, 2
	s_add_u32 s27, s24, 0x4000
	s_addc_u32 s28, s25, 0
	s_cmp_eq_u32 s46, s26
	s_cselect_b32 s30, s0, s27
	s_cselect_b32 s31, s1, s28
	s_cselect_b32 s28, s22, s60
	s_cselect_b32 s29, s23, s61
	s_add_u32 s26, s30, 0x8000
	s_addc_u32 s27, s31, 0
	v_lshl_add_u64 v[204:205], s[24:25], 0, v[132:133]
	s_add_i32 m0, s38, 0xc000
	ds_read_b128 v[172:175], v224
	ds_read_b128 v[176:179], v224 offset:1024
	ds_read_b128 v[180:183], v224 offset:2048
	ds_read_b128 v[184:187], v224 offset:3072
	ds_read_b128 v[188:191], v224 offset:4096
	ds_read_b128 v[192:195], v224 offset:5120
	ds_read_b128 v[196:199], v224 offset:6144
	ds_read_b128 v[200:203], v224 offset:7168
	global_load_lds_dwordx4 v[204:205], off
	v_lshl_add_u64 v[204:205], s[24:25], 0, v[134:135]
	s_add_i32 m0, s38, 0xe000
	s_nop 0
	global_load_lds_dwordx4 v[204:205], off
	s_waitcnt vmcnt(8)
	s_waitcnt lgkmcnt(0)
	s_barrier
	s_setprio 1
	v_mfma_f32_16x16x32_bf16 v[124:127], v[140:143], v[172:175], v[124:127]
	v_mfma_f32_16x16x32_bf16 v[124:127], v[144:147], v[176:179], v[124:127]
	v_mfma_f32_16x16x32_bf16 v[120:123], v[152:155], v[176:179], v[120:123]
	v_mfma_f32_16x16x32_bf16 v[120:123], v[148:151], v[172:175], v[120:123]
	v_mfma_f32_16x16x32_bf16 v[108:111], v[156:159], v[172:175], v[108:111]
	v_mfma_f32_16x16x32_bf16 v[108:111], v[160:163], v[176:179], v[108:111]
	v_mfma_f32_16x16x32_bf16 v[100:103], v[168:171], v[176:179], v[100:103]
	v_mfma_f32_16x16x32_bf16 v[100:103], v[164:167], v[172:175], v[100:103]
	v_mfma_f32_16x16x32_bf16 v[84:87], v[164:167], v[180:183], v[84:87]
	v_mfma_f32_16x16x32_bf16 v[84:87], v[168:171], v[184:187], v[84:87]
	v_mfma_f32_16x16x32_bf16 v[92:95], v[160:163], v[184:187], v[92:95]
	v_mfma_f32_16x16x32_bf16 v[92:95], v[156:159], v[180:183], v[92:95]
	v_mfma_f32_16x16x32_bf16 v[112:115], v[148:151], v[180:183], v[112:115]
	v_mfma_f32_16x16x32_bf16 v[112:115], v[152:155], v[184:187], v[112:115]
	v_mfma_f32_16x16x32_bf16 v[116:119], v[144:147], v[184:187], v[116:119]
	v_mfma_f32_16x16x32_bf16 v[116:119], v[140:143], v[180:183], v[116:119]
	v_mfma_f32_16x16x32_bf16 v[104:107], v[140:143], v[188:191], v[104:107]
	v_mfma_f32_16x16x32_bf16 v[104:107], v[144:147], v[192:195], v[104:107]
	v_mfma_f32_16x16x32_bf16 v[96:99], v[152:155], v[192:195], v[96:99]
	v_mfma_f32_16x16x32_bf16 v[96:99], v[148:151], v[188:191], v[96:99]
	v_mfma_f32_16x16x32_bf16 v[76:79], v[156:159], v[188:191], v[76:79]
	v_mfma_f32_16x16x32_bf16 v[76:79], v[160:163], v[192:195], v[76:79]
	v_mfma_f32_16x16x32_bf16 v[72:75], v[168:171], v[192:195], v[72:75]
	v_mfma_f32_16x16x32_bf16 v[72:75], v[164:167], v[188:191], v[72:75]
	v_mfma_f32_16x16x32_bf16 v[64:67], v[164:167], v[196:199], v[64:67]
	v_mfma_f32_16x16x32_bf16 v[64:67], v[168:171], v[200:203], v[64:67]
	v_mfma_f32_16x16x32_bf16 v[68:71], v[160:163], v[200:203], v[68:71]
	v_mfma_f32_16x16x32_bf16 v[68:71], v[156:159], v[196:199], v[68:71]
	v_mfma_f32_16x16x32_bf16 v[80:83], v[148:151], v[196:199], v[80:83]
	v_mfma_f32_16x16x32_bf16 v[80:83], v[152:155], v[200:203], v[80:83]
	v_mfma_f32_16x16x32_bf16 v[88:91], v[144:147], v[200:203], v[88:91]
	v_mfma_f32_16x16x32_bf16 v[88:91], v[140:143], v[196:199], v[88:91]
	s_setprio 0
	s_barrier
	s_add_i32 s63, s50, s37
	v_lshl_add_u64 v[204:205], s[28:29], 0, v[128:129]
	s_mov_b32 m0, s63
	ds_read_b128 v[172:175], v224 offset:16384
	ds_read_b128 v[176:179], v224 offset:17408
	ds_read_b128 v[180:183], v224 offset:18432
	ds_read_b128 v[184:187], v224 offset:19456
	ds_read_b128 v[188:191], v224 offset:20480
	ds_read_b128 v[192:195], v224 offset:21504
	ds_read_b128 v[196:199], v224 offset:22528
	ds_read_b128 v[200:203], v224 offset:23552
	global_load_lds_dwordx4 v[204:205], off
	s_add_i32 m0, s63, 0x2000
	s_add_u32 s64, s28, 0x4000
	v_lshl_add_u64 v[204:205], s[28:29], 0, v[130:131]
	s_addc_u32 s65, s29, 0
	s_add_i32 s63, s51, s37
	global_load_lds_dwordx4 v[204:205], off
	v_lshl_add_u64 v[204:205], s[64:65], 0, v[128:129]
	s_mov_b32 m0, s63
	s_nop 0
	global_load_lds_dwordx4 v[204:205], off
	v_lshl_add_u64 v[204:205], s[64:65], 0, v[130:131]
	s_add_i32 m0, s63, 0x2000
	s_nop 0
	global_load_lds_dwordx4 v[204:205], off
	v_lshl_add_u64 v[204:205], s[30:31], 0, v[128:129]
	s_mov_b32 m0, s38
	s_nop 0
	global_load_lds_dwordx4 v[204:205], off
	v_lshl_add_u64 v[204:205], s[30:31], 0, v[130:131]
	s_mov_b32 m0, s39
	s_nop 0
	global_load_lds_dwordx4 v[204:205], off
	s_waitcnt vmcnt(8)
	s_waitcnt lgkmcnt(0)
	s_barrier
	s_setprio 1
	v_mfma_f32_16x16x32_bf16 v[60:63], v[140:143], v[172:175], v[60:63]
	v_mfma_f32_16x16x32_bf16 v[60:63], v[144:147], v[176:179], v[60:63]
	v_mfma_f32_16x16x32_bf16 v[56:59], v[152:155], v[176:179], v[56:59]
	v_mfma_f32_16x16x32_bf16 v[56:59], v[148:151], v[172:175], v[56:59]
	v_mfma_f32_16x16x32_bf16 v[44:47], v[156:159], v[172:175], v[44:47]
	v_mfma_f32_16x16x32_bf16 v[44:47], v[160:163], v[176:179], v[44:47]
	v_mfma_f32_16x16x32_bf16 v[36:39], v[168:171], v[176:179], v[36:39]
	v_mfma_f32_16x16x32_bf16 v[36:39], v[164:167], v[172:175], v[36:39]
	v_mfma_f32_16x16x32_bf16 v[20:23], v[164:167], v[180:183], v[20:23]
	v_mfma_f32_16x16x32_bf16 v[20:23], v[168:171], v[184:187], v[20:23]
	v_mfma_f32_16x16x32_bf16 v[28:31], v[160:163], v[184:187], v[28:31]
	v_mfma_f32_16x16x32_bf16 v[28:31], v[156:159], v[180:183], v[28:31]
	v_mfma_f32_16x16x32_bf16 v[48:51], v[148:151], v[180:183], v[48:51]
	v_mfma_f32_16x16x32_bf16 v[48:51], v[152:155], v[184:187], v[48:51]
	v_mfma_f32_16x16x32_bf16 v[52:55], v[144:147], v[184:187], v[52:55]
	v_mfma_f32_16x16x32_bf16 v[52:55], v[140:143], v[180:183], v[52:55]
	v_mfma_f32_16x16x32_bf16 v[40:43], v[140:143], v[188:191], v[40:43]
	v_mfma_f32_16x16x32_bf16 v[40:43], v[144:147], v[192:195], v[40:43]
	v_mfma_f32_16x16x32_bf16 v[32:35], v[152:155], v[192:195], v[32:35]
	v_mfma_f32_16x16x32_bf16 v[32:35], v[148:151], v[188:191], v[32:35]
	v_mfma_f32_16x16x32_bf16 v[12:15], v[156:159], v[188:191], v[12:15]
	v_mfma_f32_16x16x32_bf16 v[12:15], v[160:163], v[192:195], v[12:15]
	v_mfma_f32_16x16x32_bf16 v[8:11], v[168:171], v[192:195], v[8:11]
	v_mfma_f32_16x16x32_bf16 v[8:11], v[164:167], v[188:191], v[8:11]
	v_mfma_f32_16x16x32_bf16 v[0:3], v[164:167], v[196:199], v[0:3]
	v_mfma_f32_16x16x32_bf16 v[0:3], v[168:171], v[200:203], v[0:3]
	v_mfma_f32_16x16x32_bf16 v[4:7], v[160:163], v[200:203], v[4:7]
	v_mfma_f32_16x16x32_bf16 v[4:7], v[156:159], v[196:199], v[4:7]
	v_mfma_f32_16x16x32_bf16 v[16:19], v[148:151], v[196:199], v[16:19]
	v_mfma_f32_16x16x32_bf16 v[16:19], v[152:155], v[200:203], v[16:19]
	v_mfma_f32_16x16x32_bf16 v[24:27], v[144:147], v[200:203], v[24:27]
	v_mfma_f32_16x16x32_bf16 v[24:27], v[140:143], v[196:199], v[24:27]
	s_setprio 0
	s_barrier
	s_add_i32 s63, 0, 0x18000
	s_add_i32 s64, 0, 0x1c000
	v_add_u32_e32 v152, s63, v219
	v_add_u32_e32 v168, s64, v219
	ds_read_b128 v[140:143], v152
	ds_read_b128 v[144:147], v152 offset:1024
	ds_read_b128 v[148:151], v152 offset:2048
	ds_read_b128 v[152:155], v152 offset:3072
	ds_read_b128 v[156:159], v168
	ds_read_b128 v[160:163], v168 offset:1024
	ds_read_b128 v[164:167], v168 offset:2048
	ds_read_b128 v[168:171], v168 offset:3072
	s_add_u32 s30, s30, 0x4000
	s_addc_u32 s31, s31, 0
	s_mov_b32 m0, s40
	v_lshl_add_u64 v[204:205], s[30:31], 0, v[128:129]
	ds_read_b128 v[172:175], v224 offset:32768
	ds_read_b128 v[176:179], v224 offset:33792
	ds_read_b128 v[180:183], v224 offset:34816
	ds_read_b128 v[184:187], v224 offset:35840
	ds_read_b128 v[188:191], v224 offset:36864
	ds_read_b128 v[192:195], v224 offset:37888
	ds_read_b128 v[196:199], v224 offset:38912
	ds_read_b128 v[200:203], v224 offset:39936
	global_load_lds_dwordx4 v[204:205], off
	v_lshl_add_u64 v[204:205], s[30:31], 0, v[130:131]
	s_mov_b32 m0, s41
	s_nop 0
	global_load_lds_dwordx4 v[204:205], off
	s_waitcnt vmcnt(8)
	s_waitcnt lgkmcnt(0)
	s_barrier
	s_setprio 1
	v_mfma_f32_16x16x32_bf16 v[124:127], v[140:143], v[172:175], v[124:127]
	v_mfma_f32_16x16x32_bf16 v[124:127], v[144:147], v[176:179], v[124:127]
	v_mfma_f32_16x16x32_bf16 v[120:123], v[152:155], v[176:179], v[120:123]
	v_mfma_f32_16x16x32_bf16 v[120:123], v[148:151], v[172:175], v[120:123]
	v_mfma_f32_16x16x32_bf16 v[108:111], v[156:159], v[172:175], v[108:111]
	v_mfma_f32_16x16x32_bf16 v[108:111], v[160:163], v[176:179], v[108:111]
	v_mfma_f32_16x16x32_bf16 v[100:103], v[168:171], v[176:179], v[100:103]
	v_mfma_f32_16x16x32_bf16 v[100:103], v[164:167], v[172:175], v[100:103]
	v_mfma_f32_16x16x32_bf16 v[84:87], v[164:167], v[180:183], v[84:87]
	v_mfma_f32_16x16x32_bf16 v[84:87], v[168:171], v[184:187], v[84:87]
	v_mfma_f32_16x16x32_bf16 v[92:95], v[160:163], v[184:187], v[92:95]
	v_mfma_f32_16x16x32_bf16 v[92:95], v[156:159], v[180:183], v[92:95]
	v_mfma_f32_16x16x32_bf16 v[112:115], v[148:151], v[180:183], v[112:115]
	v_mfma_f32_16x16x32_bf16 v[112:115], v[152:155], v[184:187], v[112:115]
	v_mfma_f32_16x16x32_bf16 v[116:119], v[144:147], v[184:187], v[116:119]
	v_mfma_f32_16x16x32_bf16 v[116:119], v[140:143], v[180:183], v[116:119]
	v_mfma_f32_16x16x32_bf16 v[104:107], v[140:143], v[188:191], v[104:107]
	v_mfma_f32_16x16x32_bf16 v[104:107], v[144:147], v[192:195], v[104:107]
	v_mfma_f32_16x16x32_bf16 v[96:99], v[152:155], v[192:195], v[96:99]
	v_mfma_f32_16x16x32_bf16 v[96:99], v[148:151], v[188:191], v[96:99]
	v_mfma_f32_16x16x32_bf16 v[76:79], v[156:159], v[188:191], v[76:79]
	v_mfma_f32_16x16x32_bf16 v[76:79], v[160:163], v[192:195], v[76:79]
	v_mfma_f32_16x16x32_bf16 v[72:75], v[168:171], v[192:195], v[72:75]
	v_mfma_f32_16x16x32_bf16 v[72:75], v[164:167], v[188:191], v[72:75]
	v_mfma_f32_16x16x32_bf16 v[64:67], v[164:167], v[196:199], v[64:67]
	v_mfma_f32_16x16x32_bf16 v[64:67], v[168:171], v[200:203], v[64:67]
	v_mfma_f32_16x16x32_bf16 v[68:71], v[160:163], v[200:203], v[68:71]
	v_mfma_f32_16x16x32_bf16 v[68:71], v[156:159], v[196:199], v[68:71]
	v_mfma_f32_16x16x32_bf16 v[80:83], v[148:151], v[196:199], v[80:83]
	v_mfma_f32_16x16x32_bf16 v[80:83], v[152:155], v[200:203], v[80:83]
	v_mfma_f32_16x16x32_bf16 v[88:91], v[144:147], v[200:203], v[88:91]
	v_mfma_f32_16x16x32_bf16 v[88:91], v[140:143], v[196:199], v[88:91]
	s_setprio 0
	s_barrier
	s_add_u32 s30, s28, 0x8000
	s_addc_u32 s31, s29, 0
	s_add_i32 s63, s63, s37
	v_lshl_add_u64 v[204:205], s[30:31], 0, v[128:129]
	s_mov_b32 m0, s63
	ds_read_b128 v[172:175], v224 offset:49152
	ds_read_b128 v[176:179], v224 offset:50176
	ds_read_b128 v[180:183], v224 offset:51200
	ds_read_b128 v[184:187], v224 offset:52224
	ds_read_b128 v[188:191], v224 offset:53248
	ds_read_b128 v[192:195], v224 offset:54272
	ds_read_b128 v[196:199], v224 offset:55296
	ds_read_b128 v[200:203], v224 offset:56320
	global_load_lds_dwordx4 v[204:205], off
	s_add_i32 m0, s63, 0x2000
	s_add_u32 s28, s28, 0xc000
	v_lshl_add_u64 v[204:205], s[30:31], 0, v[130:131]
	s_addc_u32 s29, s29, 0
	s_add_i32 s30, s64, s37
	global_load_lds_dwordx4 v[204:205], off
	v_lshl_add_u64 v[204:205], s[28:29], 0, v[128:129]
	s_mov_b32 m0, s30
	s_nop 0
	global_load_lds_dwordx4 v[204:205], off
	v_lshl_add_u64 v[204:205], s[28:29], 0, v[130:131]
	s_add_i32 m0, s30, 0x2000
	s_nop 0
	global_load_lds_dwordx4 v[204:205], off
	v_lshl_add_u64 v[204:205], s[26:27], 0, v[128:129]
	s_mov_b32 m0, s44
	s_nop 0
	global_load_lds_dwordx4 v[204:205], off
	v_lshl_add_u64 v[204:205], s[26:27], 0, v[130:131]
	s_mov_b32 m0, s45
	s_nop 0
	global_load_lds_dwordx4 v[204:205], off
	s_waitcnt vmcnt(8)
	s_waitcnt lgkmcnt(0)
	s_barrier
	s_setprio 1
	v_mfma_f32_16x16x32_bf16 v[60:63], v[140:143], v[172:175], v[60:63]
	v_mfma_f32_16x16x32_bf16 v[60:63], v[144:147], v[176:179], v[60:63]
	v_mfma_f32_16x16x32_bf16 v[56:59], v[152:155], v[176:179], v[56:59]
	v_mfma_f32_16x16x32_bf16 v[56:59], v[148:151], v[172:175], v[56:59]
	v_mfma_f32_16x16x32_bf16 v[44:47], v[156:159], v[172:175], v[44:47]
	v_mfma_f32_16x16x32_bf16 v[44:47], v[160:163], v[176:179], v[44:47]
	v_mfma_f32_16x16x32_bf16 v[36:39], v[168:171], v[176:179], v[36:39]
	v_mfma_f32_16x16x32_bf16 v[36:39], v[164:167], v[172:175], v[36:39]
	v_mfma_f32_16x16x32_bf16 v[20:23], v[164:167], v[180:183], v[20:23]
	v_mfma_f32_16x16x32_bf16 v[20:23], v[168:171], v[184:187], v[20:23]
	v_mfma_f32_16x16x32_bf16 v[28:31], v[160:163], v[184:187], v[28:31]
	v_mfma_f32_16x16x32_bf16 v[28:31], v[156:159], v[180:183], v[28:31]
	v_mfma_f32_16x16x32_bf16 v[48:51], v[148:151], v[180:183], v[48:51]
	v_mfma_f32_16x16x32_bf16 v[48:51], v[152:155], v[184:187], v[48:51]
	v_mfma_f32_16x16x32_bf16 v[52:55], v[144:147], v[184:187], v[52:55]
	v_mfma_f32_16x16x32_bf16 v[52:55], v[140:143], v[180:183], v[52:55]
	v_mfma_f32_16x16x32_bf16 v[40:43], v[140:143], v[188:191], v[40:43]
	v_mfma_f32_16x16x32_bf16 v[40:43], v[144:147], v[192:195], v[40:43]
	v_mfma_f32_16x16x32_bf16 v[32:35], v[152:155], v[192:195], v[32:35]
	v_mfma_f32_16x16x32_bf16 v[32:35], v[148:151], v[188:191], v[32:35]
	v_mfma_f32_16x16x32_bf16 v[12:15], v[156:159], v[188:191], v[12:15]
	v_mfma_f32_16x16x32_bf16 v[12:15], v[160:163], v[192:195], v[12:15]
	v_mfma_f32_16x16x32_bf16 v[8:11], v[168:171], v[192:195], v[8:11]
	v_mfma_f32_16x16x32_bf16 v[8:11], v[164:167], v[188:191], v[8:11]
	v_mfma_f32_16x16x32_bf16 v[0:3], v[164:167], v[196:199], v[0:3]
	v_mfma_f32_16x16x32_bf16 v[0:3], v[168:171], v[200:203], v[0:3]
	v_mfma_f32_16x16x32_bf16 v[4:7], v[160:163], v[200:203], v[4:7]
	v_mfma_f32_16x16x32_bf16 v[4:7], v[156:159], v[196:199], v[4:7]
	v_mfma_f32_16x16x32_bf16 v[16:19], v[148:151], v[196:199], v[16:19]
	v_mfma_f32_16x16x32_bf16 v[16:19], v[152:155], v[200:203], v[16:19]
	v_mfma_f32_16x16x32_bf16 v[24:27], v[144:147], v[200:203], v[24:27]
	v_mfma_f32_16x16x32_bf16 v[24:27], v[140:143], v[196:199], v[24:27]
	s_setprio 0
	s_barrier
	s_add_u32 s24, s24, 0x10000
	s_addc_u32 s25, s25, 0
	s_add_u32 s60, s60, 0x10000
	s_addc_u32 s61, s61, 0
	s_cmp_ge_i32 s62, s43
	s_mov_b32 s26, s62
	s_cbranch_scc0 .LBB0_1056
	v_pk_mul_f32 v[198:199], v[126:127], 0.5 op_sel_hi:[1,0]
	v_pk_mul_f32 v[200:201], v[124:125], 0.5 op_sel_hi:[1,0]
	v_pk_mul_f32 v[202:203], v[122:123], 0.5 op_sel_hi:[1,0]
	v_pk_mul_f32 v[204:205], v[120:121], 0.5 op_sel_hi:[1,0]
	v_pk_mul_f32 v[208:209], v[110:111], 0.5 op_sel_hi:[1,0]
	v_pk_mul_f32 v[206:207], v[108:109], 0.5 op_sel_hi:[1,0]
	v_pk_mul_f32 v[196:197], v[102:103], 0.5 op_sel_hi:[1,0]
	v_pk_mul_f32 v[194:195], v[100:101], 0.5 op_sel_hi:[1,0]
	v_pk_mul_f32 v[192:193], v[118:119], 0.5 op_sel_hi:[1,0]
	v_pk_mul_f32 v[190:191], v[116:117], 0.5 op_sel_hi:[1,0]
	v_pk_mul_f32 v[188:189], v[114:115], 0.5 op_sel_hi:[1,0]
	v_pk_mul_f32 v[186:187], v[112:113], 0.5 op_sel_hi:[1,0]
	v_pk_mul_f32 v[184:185], v[94:95], 0.5 op_sel_hi:[1,0]
	v_pk_mul_f32 v[182:183], v[92:93], 0.5 op_sel_hi:[1,0]
	v_pk_mul_f32 v[180:181], v[86:87], 0.5 op_sel_hi:[1,0]
	v_pk_mul_f32 v[178:179], v[84:85], 0.5 op_sel_hi:[1,0]
	v_pk_mul_f32 v[176:177], v[106:107], 0.5 op_sel_hi:[1,0]
	v_pk_mul_f32 v[174:175], v[104:105], 0.5 op_sel_hi:[1,0]
	v_pk_mul_f32 v[172:173], v[98:99], 0.5 op_sel_hi:[1,0]
	v_pk_mul_f32 v[170:171], v[96:97], 0.5 op_sel_hi:[1,0]
	v_pk_mul_f32 v[168:169], v[78:79], 0.5 op_sel_hi:[1,0]
	v_pk_mul_f32 v[166:167], v[76:77], 0.5 op_sel_hi:[1,0]
	v_pk_mul_f32 v[164:165], v[74:75], 0.5 op_sel_hi:[1,0]
	v_pk_mul_f32 v[162:163], v[72:73], 0.5 op_sel_hi:[1,0]
	v_pk_mul_f32 v[160:161], v[90:91], 0.5 op_sel_hi:[1,0]
	v_pk_mul_f32 v[158:159], v[88:89], 0.5 op_sel_hi:[1,0]
	v_pk_mul_f32 v[156:157], v[82:83], 0.5 op_sel_hi:[1,0]
	v_pk_mul_f32 v[154:155], v[80:81], 0.5 op_sel_hi:[1,0]
	v_pk_mul_f32 v[152:153], v[70:71], 0.5 op_sel_hi:[1,0]
	v_pk_mul_f32 v[150:151], v[68:69], 0.5 op_sel_hi:[1,0]
	v_pk_mul_f32 v[148:149], v[66:67], 0.5 op_sel_hi:[1,0]
	v_pk_mul_f32 v[146:147], v[64:65], 0.5 op_sel_hi:[1,0]
	v_pk_mul_f32 v[142:143], v[62:63], 0.5 op_sel_hi:[1,0]
	v_pk_mul_f32 v[140:141], v[60:61], 0.5 op_sel_hi:[1,0]
	v_pk_mul_f32 v[126:127], v[58:59], 0.5 op_sel_hi:[1,0]
	v_pk_mul_f32 v[124:125], v[56:57], 0.5 op_sel_hi:[1,0]
	v_pk_mul_f32 v[122:123], v[46:47], 0.5 op_sel_hi:[1,0]
	v_pk_mul_f32 v[120:121], v[44:45], 0.5 op_sel_hi:[1,0]
	v_pk_mul_f32 v[118:119], v[38:39], 0.5 op_sel_hi:[1,0]
	v_pk_mul_f32 v[116:117], v[36:37], 0.5 op_sel_hi:[1,0]
	v_pk_mul_f32 v[114:115], v[54:55], 0.5 op_sel_hi:[1,0]
	v_pk_mul_f32 v[112:113], v[52:53], 0.5 op_sel_hi:[1,0]
	v_pk_mul_f32 v[110:111], v[50:51], 0.5 op_sel_hi:[1,0]
	v_pk_mul_f32 v[108:109], v[48:49], 0.5 op_sel_hi:[1,0]
	v_pk_mul_f32 v[106:107], v[30:31], 0.5 op_sel_hi:[1,0]
	v_pk_mul_f32 v[104:105], v[28:29], 0.5 op_sel_hi:[1,0]
	v_pk_mul_f32 v[102:103], v[22:23], 0.5 op_sel_hi:[1,0]
	v_pk_mul_f32 v[100:101], v[20:21], 0.5 op_sel_hi:[1,0]
	v_pk_mul_f32 v[98:99], v[42:43], 0.5 op_sel_hi:[1,0]
	v_pk_mul_f32 v[96:97], v[40:41], 0.5 op_sel_hi:[1,0]
	v_pk_mul_f32 v[94:95], v[34:35], 0.5 op_sel_hi:[1,0]
	v_pk_mul_f32 v[92:93], v[32:33], 0.5 op_sel_hi:[1,0]
	v_pk_mul_f32 v[90:91], v[14:15], 0.5 op_sel_hi:[1,0]
	v_pk_mul_f32 v[88:89], v[12:13], 0.5 op_sel_hi:[1,0]
	v_pk_mul_f32 v[86:87], v[10:11], 0.5 op_sel_hi:[1,0]
	v_pk_mul_f32 v[84:85], v[8:9], 0.5 op_sel_hi:[1,0]
	v_pk_mul_f32 v[82:83], v[26:27], 0.5 op_sel_hi:[1,0]
	v_pk_mul_f32 v[80:81], v[24:25], 0.5 op_sel_hi:[1,0]
	v_pk_mul_f32 v[78:79], v[18:19], 0.5 op_sel_hi:[1,0]
	v_pk_mul_f32 v[76:77], v[16:17], 0.5 op_sel_hi:[1,0]
	v_pk_mul_f32 v[74:75], v[6:7], 0.5 op_sel_hi:[1,0]
	v_pk_mul_f32 v[72:73], v[4:5], 0.5 op_sel_hi:[1,0]
	v_pk_mul_f32 v[70:71], v[2:3], 0.5 op_sel_hi:[1,0]
	v_pk_mul_f32 v[68:69], v[0:1], 0.5 op_sel_hi:[1,0]

.LBB0_1159:
	ds_read_b128 v[128:131], v205
	ds_read_b128 v[132:135], v205 offset:1024
	ds_read_b128 v[136:139], v205 offset:2048
	ds_read_b128 v[140:143], v205 offset:3072
	ds_read_b128 v[144:147], v206
	ds_read_b128 v[160:163], v206 offset:1024
	ds_read_b128 v[164:167], v206 offset:2048
	ds_read_b128 v[168:171], v206 offset:3072
	s_add_i32 s41, s6, 2
	s_add_u32 s68, s0, 0x80
	s_addc_u32 s7, s1, 0
	s_cmp_eq_u32 s57, s6
	s_cselect_b32 s6, s34, s68
	s_cselect_b32 s7, s35, s7
	s_cselect_b32 s69, s37, s39
	s_cselect_b32 s68, s36, s38
	v_lshl_add_u64 v[200:201], s[0:1], 0, v[152:153]
	s_add_i32 m0, s47, 0xc000
	ds_read_b128 v[172:175], v207
	ds_read_b128 v[176:179], v207 offset:1024
	ds_read_b128 v[180:183], v207 offset:2048
	ds_read_b128 v[184:187], v207 offset:3072
	ds_read_b128 v[188:191], v207 offset:4096
	ds_read_b128 v[192:195], v207 offset:5120
	ds_read_b128 v[196:199], v207 offset:6144
	ds_read_b128 v[212:215], v207 offset:7168
	global_load_lds_dwordx4 v[200:201], off
	v_lshl_add_u64 v[200:201], s[0:1], 0, v[154:155]
	s_add_i32 m0, s47, 0xe000
	s_nop 0
	global_load_lds_dwordx4 v[200:201], off
	s_waitcnt vmcnt(8)
	s_waitcnt lgkmcnt(0)
	s_barrier
	s_setprio 1
	v_mfma_f32_16x16x32_bf16 v[124:127], v[128:131], v[172:175], v[124:127]
	v_mfma_f32_16x16x32_bf16 v[124:127], v[132:135], v[176:179], v[124:127]
	v_mfma_f32_16x16x32_bf16 v[120:123], v[140:143], v[176:179], v[120:123]
	v_mfma_f32_16x16x32_bf16 v[120:123], v[136:139], v[172:175], v[120:123]
	v_mfma_f32_16x16x32_bf16 v[116:119], v[144:147], v[172:175], v[116:119]
	v_mfma_f32_16x16x32_bf16 v[116:119], v[160:163], v[176:179], v[116:119]
	v_mfma_f32_16x16x32_bf16 v[112:115], v[168:171], v[176:179], v[112:115]
	v_mfma_f32_16x16x32_bf16 v[112:115], v[164:167], v[172:175], v[112:115]
	v_mfma_f32_16x16x32_bf16 v[96:99], v[164:167], v[180:183], v[96:99]
	v_mfma_f32_16x16x32_bf16 v[96:99], v[168:171], v[184:187], v[96:99]
	v_mfma_f32_16x16x32_bf16 v[100:103], v[160:163], v[184:187], v[100:103]
	v_mfma_f32_16x16x32_bf16 v[100:103], v[144:147], v[180:183], v[100:103]
	v_mfma_f32_16x16x32_bf16 v[104:107], v[136:139], v[180:183], v[104:107]
	v_mfma_f32_16x16x32_bf16 v[104:107], v[140:143], v[184:187], v[104:107]
	v_mfma_f32_16x16x32_bf16 v[108:111], v[132:135], v[184:187], v[108:111]
	v_mfma_f32_16x16x32_bf16 v[108:111], v[128:131], v[180:183], v[108:111]
	v_mfma_f32_16x16x32_bf16 v[92:95], v[128:131], v[188:191], v[92:95]
	v_mfma_f32_16x16x32_bf16 v[92:95], v[132:135], v[192:195], v[92:95]
	v_mfma_f32_16x16x32_bf16 v[88:91], v[140:143], v[192:195], v[88:91]
	v_mfma_f32_16x16x32_bf16 v[88:91], v[136:139], v[188:191], v[88:91]
	v_mfma_f32_16x16x32_bf16 v[84:87], v[144:147], v[188:191], v[84:87]
	v_mfma_f32_16x16x32_bf16 v[84:87], v[160:163], v[192:195], v[84:87]
	v_mfma_f32_16x16x32_bf16 v[80:83], v[168:171], v[192:195], v[80:83]
	v_mfma_f32_16x16x32_bf16 v[80:83], v[164:167], v[188:191], v[80:83]
	v_mfma_f32_16x16x32_bf16 v[64:67], v[164:167], v[196:199], v[64:67]
	v_mfma_f32_16x16x32_bf16 v[64:67], v[168:171], v[212:215], v[64:67]
	v_mfma_f32_16x16x32_bf16 v[68:71], v[160:163], v[212:215], v[68:71]
	v_mfma_f32_16x16x32_bf16 v[68:71], v[144:147], v[196:199], v[68:71]
	v_mfma_f32_16x16x32_bf16 v[72:75], v[136:139], v[196:199], v[72:75]
	v_mfma_f32_16x16x32_bf16 v[72:75], v[140:143], v[212:215], v[72:75]
	v_mfma_f32_16x16x32_bf16 v[76:79], v[132:135], v[212:215], v[76:79]
	v_mfma_f32_16x16x32_bf16 v[76:79], v[128:131], v[196:199], v[76:79]
	s_setprio 0
	s_barrier
	s_add_i32 s70, s60, s46
	v_lshl_add_u64 v[200:201], s[68:69], 0, v[148:149]
	s_mov_b32 m0, s70
	ds_read_b128 v[172:175], v207 offset:16384
	ds_read_b128 v[176:179], v207 offset:17408
	ds_read_b128 v[180:183], v207 offset:18432
	ds_read_b128 v[184:187], v207 offset:19456
	ds_read_b128 v[188:191], v207 offset:20480
	ds_read_b128 v[192:195], v207 offset:21504
	ds_read_b128 v[196:199], v207 offset:22528
	ds_read_b128 v[212:215], v207 offset:23552
	global_load_lds_dwordx4 v[200:201], off
	s_add_i32 m0, s70, 0x2000
	v_lshl_add_u64 v[216:217], s[68:69], 0, v[150:151]
	s_add_u32 s68, s68, s10
	s_addc_u32 s69, s69, s11
	s_add_i32 s70, s61, s46
	global_load_lds_dwordx4 v[216:217], off
	v_lshl_add_u64 v[218:219], s[68:69], 0, v[148:149]
	s_mov_b32 m0, s70
	v_lshl_add_u64 v[220:221], s[68:69], 0, v[150:151]
	global_load_lds_dwordx4 v[218:219], off
	s_add_i32 m0, s70, 0x2000
	v_lshl_add_u64 v[222:223], s[6:7], 0, v[148:149]
	global_load_lds_dwordx4 v[220:221], off
	s_mov_b32 m0, s47
	v_lshl_add_u64 v[224:225], s[6:7], 0, v[150:151]
	global_load_lds_dwordx4 v[222:223], off
	s_mov_b32 m0, s48
	s_nop 0
	global_load_lds_dwordx4 v[224:225], off
	s_waitcnt vmcnt(8)
	s_waitcnt lgkmcnt(0)
	s_barrier
	s_setprio 1
	v_mfma_f32_16x16x32_bf16 v[60:63], v[128:131], v[172:175], v[60:63]
	v_mfma_f32_16x16x32_bf16 v[60:63], v[132:135], v[176:179], v[60:63]
	v_mfma_f32_16x16x32_bf16 v[56:59], v[140:143], v[176:179], v[56:59]
	v_mfma_f32_16x16x32_bf16 v[56:59], v[136:139], v[172:175], v[56:59]
	v_mfma_f32_16x16x32_bf16 v[52:55], v[144:147], v[172:175], v[52:55]
	v_mfma_f32_16x16x32_bf16 v[52:55], v[160:163], v[176:179], v[52:55]
	v_mfma_f32_16x16x32_bf16 v[48:51], v[168:171], v[176:179], v[48:51]
	v_mfma_f32_16x16x32_bf16 v[48:51], v[164:167], v[172:175], v[48:51]
	v_mfma_f32_16x16x32_bf16 v[32:35], v[164:167], v[180:183], v[32:35]
	v_mfma_f32_16x16x32_bf16 v[32:35], v[168:171], v[184:187], v[32:35]
	v_mfma_f32_16x16x32_bf16 v[36:39], v[160:163], v[184:187], v[36:39]
	v_mfma_f32_16x16x32_bf16 v[36:39], v[144:147], v[180:183], v[36:39]
	v_mfma_f32_16x16x32_bf16 v[40:43], v[136:139], v[180:183], v[40:43]
	v_mfma_f32_16x16x32_bf16 v[40:43], v[140:143], v[184:187], v[40:43]
	v_mfma_f32_16x16x32_bf16 v[44:47], v[132:135], v[184:187], v[44:47]
	v_mfma_f32_16x16x32_bf16 v[44:47], v[128:131], v[180:183], v[44:47]
	v_mfma_f32_16x16x32_bf16 v[28:31], v[128:131], v[188:191], v[28:31]
	v_mfma_f32_16x16x32_bf16 v[28:31], v[132:135], v[192:195], v[28:31]
	v_mfma_f32_16x16x32_bf16 v[24:27], v[140:143], v[192:195], v[24:27]
	v_mfma_f32_16x16x32_bf16 v[24:27], v[136:139], v[188:191], v[24:27]
	v_mfma_f32_16x16x32_bf16 v[20:23], v[144:147], v[188:191], v[20:23]
	v_mfma_f32_16x16x32_bf16 v[20:23], v[160:163], v[192:195], v[20:23]
	v_mfma_f32_16x16x32_bf16 v[16:19], v[168:171], v[192:195], v[16:19]
	v_mfma_f32_16x16x32_bf16 v[16:19], v[164:167], v[188:191], v[16:19]
	v_mfma_f32_16x16x32_bf16 v[0:3], v[164:167], v[196:199], v[0:3]
	v_mfma_f32_16x16x32_bf16 v[0:3], v[168:171], v[212:215], v[0:3]
	v_mfma_f32_16x16x32_bf16 v[4:7], v[160:163], v[212:215], v[4:7]
	v_mfma_f32_16x16x32_bf16 v[4:7], v[144:147], v[196:199], v[4:7]
	v_mfma_f32_16x16x32_bf16 v[8:11], v[136:139], v[196:199], v[8:11]
	v_mfma_f32_16x16x32_bf16 v[8:11], v[140:143], v[212:215], v[8:11]
	v_mfma_f32_16x16x32_bf16 v[12:15], v[132:135], v[212:215], v[12:15]
	v_mfma_f32_16x16x32_bf16 v[12:15], v[128:131], v[196:199], v[12:15]
	s_setprio 0
	s_barrier
	s_add_i32 s68, 0, 0x18000
	s_add_i32 s69, 0, 0x1c000
	v_add_u32_e32 v140, s68, v203
	v_add_u32_e32 v168, s69, v203
	ds_read_b128 v[128:131], v140
	ds_read_b128 v[132:135], v140 offset:1024
	ds_read_b128 v[136:139], v140 offset:2048
	ds_read_b128 v[140:143], v140 offset:3072
	ds_read_b128 v[144:147], v168
	ds_read_b128 v[160:163], v168 offset:1024
	ds_read_b128 v[164:167], v168 offset:2048
	ds_read_b128 v[168:171], v168 offset:3072
	s_add_u32 s6, s6, s10
	s_addc_u32 s7, s7, s11
	s_mov_b32 m0, s49
	v_lshl_add_u64 v[226:227], s[6:7], 0, v[148:149]
	ds_read_b128 v[172:175], v207 offset:32768
	ds_read_b128 v[176:179], v207 offset:33792
	ds_read_b128 v[180:183], v207 offset:34816
	ds_read_b128 v[184:187], v207 offset:35840
	ds_read_b128 v[188:191], v207 offset:36864
	ds_read_b128 v[192:195], v207 offset:37888
	ds_read_b128 v[196:199], v207 offset:38912
	ds_read_b128 v[212:215], v207 offset:39936
	global_load_lds_dwordx4 v[226:227], off
	v_lshl_add_u64 v[226:227], s[6:7], 0, v[150:151]
	s_mov_b32 m0, s50
	s_nop 0
	global_load_lds_dwordx4 v[226:227], off
	s_waitcnt vmcnt(8)
	s_waitcnt lgkmcnt(0)
	s_barrier
	s_setprio 1
	v_mfma_f32_16x16x32_bf16 v[124:127], v[128:131], v[172:175], v[124:127]
	v_mfma_f32_16x16x32_bf16 v[124:127], v[132:135], v[176:179], v[124:127]
	v_mfma_f32_16x16x32_bf16 v[120:123], v[140:143], v[176:179], v[120:123]
	v_mfma_f32_16x16x32_bf16 v[120:123], v[136:139], v[172:175], v[120:123]
	v_mfma_f32_16x16x32_bf16 v[116:119], v[144:147], v[172:175], v[116:119]
	v_mfma_f32_16x16x32_bf16 v[116:119], v[160:163], v[176:179], v[116:119]
	v_mfma_f32_16x16x32_bf16 v[112:115], v[168:171], v[176:179], v[112:115]
	v_mfma_f32_16x16x32_bf16 v[112:115], v[164:167], v[172:175], v[112:115]
	v_mfma_f32_16x16x32_bf16 v[96:99], v[164:167], v[180:183], v[96:99]
	v_mfma_f32_16x16x32_bf16 v[96:99], v[168:171], v[184:187], v[96:99]
	v_mfma_f32_16x16x32_bf16 v[100:103], v[160:163], v[184:187], v[100:103]
	v_mfma_f32_16x16x32_bf16 v[100:103], v[144:147], v[180:183], v[100:103]
	v_mfma_f32_16x16x32_bf16 v[104:107], v[136:139], v[180:183], v[104:107]
	v_mfma_f32_16x16x32_bf16 v[104:107], v[140:143], v[184:187], v[104:107]
	v_mfma_f32_16x16x32_bf16 v[108:111], v[132:135], v[184:187], v[108:111]
	v_mfma_f32_16x16x32_bf16 v[108:111], v[128:131], v[180:183], v[108:111]
	v_mfma_f32_16x16x32_bf16 v[92:95], v[128:131], v[188:191], v[92:95]
	v_mfma_f32_16x16x32_bf16 v[92:95], v[132:135], v[192:195], v[92:95]
	v_mfma_f32_16x16x32_bf16 v[88:91], v[140:143], v[192:195], v[88:91]
	v_mfma_f32_16x16x32_bf16 v[88:91], v[136:139], v[188:191], v[88:91]
	v_mfma_f32_16x16x32_bf16 v[84:87], v[144:147], v[188:191], v[84:87]
	v_mfma_f32_16x16x32_bf16 v[84:87], v[160:163], v[192:195], v[84:87]
	v_mfma_f32_16x16x32_bf16 v[80:83], v[168:171], v[192:195], v[80:83]
	v_mfma_f32_16x16x32_bf16 v[80:83], v[164:167], v[188:191], v[80:83]
	v_mfma_f32_16x16x32_bf16 v[64:67], v[164:167], v[196:199], v[64:67]
	v_mfma_f32_16x16x32_bf16 v[64:67], v[168:171], v[212:215], v[64:67]
	v_mfma_f32_16x16x32_bf16 v[68:71], v[160:163], v[212:215], v[68:71]
	v_mfma_f32_16x16x32_bf16 v[68:71], v[144:147], v[196:199], v[68:71]
	v_mfma_f32_16x16x32_bf16 v[72:75], v[136:139], v[196:199], v[72:75]
	v_mfma_f32_16x16x32_bf16 v[72:75], v[140:143], v[212:215], v[72:75]
	v_mfma_f32_16x16x32_bf16 v[76:79], v[132:135], v[212:215], v[76:79]
	v_mfma_f32_16x16x32_bf16 v[76:79], v[128:131], v[196:199], v[76:79]
	s_setprio 0
	s_barrier
	s_add_i32 s6, s68, s46
	v_lshl_add_u64 v[200:201], v[200:201], 0, s[20:21]
	s_mov_b32 m0, s6
	ds_read_b128 v[172:175], v207 offset:49152
	ds_read_b128 v[176:179], v207 offset:50176
	ds_read_b128 v[180:183], v207 offset:51200
	ds_read_b128 v[184:187], v207 offset:52224
	ds_read_b128 v[188:191], v207 offset:53248
	ds_read_b128 v[192:195], v207 offset:54272
	ds_read_b128 v[196:199], v207 offset:55296
	ds_read_b128 v[212:215], v207 offset:56320
	global_load_lds_dwordx4 v[200:201], off
	v_lshl_add_u64 v[200:201], v[216:217], 0, s[20:21]
	s_add_i32 m0, s6, 0x2000
	s_add_i32 s6, s69, s46
	global_load_lds_dwordx4 v[200:201], off
	v_lshl_add_u64 v[200:201], v[218:219], 0, s[20:21]
	s_mov_b32 m0, s6
	s_nop 0
	global_load_lds_dwordx4 v[200:201], off
	v_lshl_add_u64 v[200:201], v[220:221], 0, s[20:21]
	s_add_i32 m0, s6, 0x2000
	s_nop 0
	global_load_lds_dwordx4 v[200:201], off
	v_lshl_add_u64 v[200:201], v[222:223], 0, s[20:21]
	s_mov_b32 m0, s54
	s_nop 0
	global_load_lds_dwordx4 v[200:201], off
	v_lshl_add_u64 v[200:201], v[224:225], 0, s[20:21]
	s_mov_b32 m0, s55
	s_nop 0
	global_load_lds_dwordx4 v[200:201], off
	s_waitcnt vmcnt(8)
	s_waitcnt lgkmcnt(0)
	s_barrier
	s_setprio 1
	v_mfma_f32_16x16x32_bf16 v[60:63], v[128:131], v[172:175], v[60:63]
	v_mfma_f32_16x16x32_bf16 v[60:63], v[132:135], v[176:179], v[60:63]
	v_mfma_f32_16x16x32_bf16 v[56:59], v[140:143], v[176:179], v[56:59]
	v_mfma_f32_16x16x32_bf16 v[56:59], v[136:139], v[172:175], v[56:59]
	v_mfma_f32_16x16x32_bf16 v[52:55], v[144:147], v[172:175], v[52:55]
	v_mfma_f32_16x16x32_bf16 v[52:55], v[160:163], v[176:179], v[52:55]
	v_mfma_f32_16x16x32_bf16 v[48:51], v[168:171], v[176:179], v[48:51]
	v_mfma_f32_16x16x32_bf16 v[48:51], v[164:167], v[172:175], v[48:51]
	v_mfma_f32_16x16x32_bf16 v[32:35], v[164:167], v[180:183], v[32:35]
	v_mfma_f32_16x16x32_bf16 v[32:35], v[168:171], v[184:187], v[32:35]
	v_mfma_f32_16x16x32_bf16 v[36:39], v[160:163], v[184:187], v[36:39]
	v_mfma_f32_16x16x32_bf16 v[36:39], v[144:147], v[180:183], v[36:39]
	v_mfma_f32_16x16x32_bf16 v[40:43], v[136:139], v[180:183], v[40:43]
	v_mfma_f32_16x16x32_bf16 v[40:43], v[140:143], v[184:187], v[40:43]
	v_mfma_f32_16x16x32_bf16 v[44:47], v[132:135], v[184:187], v[44:47]
	v_mfma_f32_16x16x32_bf16 v[44:47], v[128:131], v[180:183], v[44:47]
	v_mfma_f32_16x16x32_bf16 v[28:31], v[128:131], v[188:191], v[28:31]
	v_mfma_f32_16x16x32_bf16 v[28:31], v[132:135], v[192:195], v[28:31]
	v_mfma_f32_16x16x32_bf16 v[24:27], v[140:143], v[192:195], v[24:27]
	v_mfma_f32_16x16x32_bf16 v[24:27], v[136:139], v[188:191], v[24:27]
	v_mfma_f32_16x16x32_bf16 v[20:23], v[144:147], v[188:191], v[20:23]
	v_mfma_f32_16x16x32_bf16 v[20:23], v[160:163], v[192:195], v[20:23]
	v_mfma_f32_16x16x32_bf16 v[16:19], v[168:171], v[192:195], v[16:19]
	v_mfma_f32_16x16x32_bf16 v[16:19], v[164:167], v[188:191], v[16:19]
	v_mfma_f32_16x16x32_bf16 v[0:3], v[164:167], v[196:199], v[0:3]
	v_mfma_f32_16x16x32_bf16 v[0:3], v[168:171], v[212:215], v[0:3]
	v_mfma_f32_16x16x32_bf16 v[4:7], v[160:163], v[212:215], v[4:7]
	v_mfma_f32_16x16x32_bf16 v[4:7], v[144:147], v[196:199], v[4:7]
	v_mfma_f32_16x16x32_bf16 v[8:11], v[136:139], v[196:199], v[8:11]
	v_mfma_f32_16x16x32_bf16 v[8:11], v[140:143], v[212:215], v[8:11]
	v_mfma_f32_16x16x32_bf16 v[12:15], v[132:135], v[212:215], v[12:15]
	v_mfma_f32_16x16x32_bf16 v[12:15], v[128:131], v[196:199], v[12:15]
	s_setprio 0
	s_barrier
	s_add_u32 s0, s0, 0x100
	s_addc_u32 s1, s1, 0
	s_add_u32 s38, s38, 0x100
	s_addc_u32 s39, s39, 0
	s_cmp_ge_i32 s41, s56
	s_mov_b32 s6, s41
	s_cbranch_scc0 .LBB0_1159
